# k11 minus every s_setprio in the GEMM K-loops
# speedup vs baseline: 1.0026x; 1.0026x over previous
; #define PG8_STAGE(bufoff, gbase, voff) do { _Pragma("unroll") for (int _i = 0; _i < 2; ++_i) \
;         __builtin_amdgcn_global_load_lds((const unsigned*)((const char*)(gbase) + (voff)[_i]), (PG8_LAS unsigned*)(lds + (bufoff) + ldsw + _i * 8192), 16, 0, 0); } while (0)
; #define PG8_LDA(dst, b, h) do { _Pragma("unroll") for (int m = 0; m < 4; ++m) _Pragma("unroll") for (int k = 0; k < 2; ++k) dst[m][k] = *(const PG8_LAS bf16x8*)(lds + PG8_SA(b, h) + aoff + m * 2048 + k * 1024); } while (0)
; #define PG8_LDB(dst, b, h) do { _Pragma("unroll") for (int n = 0; n < 2; ++n) _Pragma("unroll") for (int k = 0; k < 2; ++k) dst[n][k] = *(const PG8_LAS bf16x8*)(lds + PG8_SB(b, h) + boff + n * 2048 + k * 1024); } while (0)
; #define PG8_MMA(ai, bj, At, Bt) do { __builtin_amdgcn_s_setprio(1); _Pragma("unroll") for (int m = 0; m < 4; ++m) _Pragma("unroll") for (int n = 0; n < 2; ++n) _Pragma("unroll") for (int k = 0; k < 2; ++k) \
;         acc[ai][bj][m][n] = __builtin_amdgcn_mfma_f32_16x16x32_bf16(Bt[n][k], At[m][k], acc[ai][bj][m][n], 0, 0, 0); __builtin_amdgcn_s_setprio(0); } while (0)
; #define PG8_WAIT_V(n) asm volatile("s_waitcnt vmcnt(" #n ")" ::: "memory")
; #define PG8_BAR __builtin_amdgcn_s_barrier()
; template <class Epi, class Sched, bool ALIGN_EPI = false, bool SP2 = false>
; __device__ __forceinline__ void gemm_phase(PG8_LAS unsigned char* lds, const Gemm g, const Sched S, const Epi E) {
;     ...
;         for (int t = 0; t < nt; t += 2) {
;             const bool last = (t == nt - 2);
;             const char* a1 = cA + (size_t)(t + 1) * kstep;
;             const char* a2 = last ? nA : cA + (size_t)(t + 2) * kstep; const char* b2 = last ? nB : cB + (size_t)(t + 2) * kstep;
;             const char* a3 = a2 + kstep; const char* b3 = b2 + kstep;
;             if (last && has_next) S.a_ready(nxt);
;             if constexpr (SP2) {
;             PG8_LDB(B0, 0, 0); PG8_LDB(B1, 0, 1); PG8_SCHED; PG8_LDA(At, 0, 0); PG8_STAGE(PG8_SA(1, 1), a1 + hstep, voffA);
;             PG8_WAIT_V(8); PG8_WAIT_L(0); PG8_BAR; PG8_MMA(0, 0, At, B0); PG8_MMA(0, 1, At, B1); PG8_BAR; PG8_SCHED;
;             PG8_LDA(At, 0, 1); PG8_STAGE(PG8_SB(0, 0), b2, voffB); PG8_STAGE(PG8_SB(0, 1), b2 + hstep, voffB); PG8_STAGE(PG8_SA(0, 0), a2, voffA);
;             PG8_WAIT_V(8); PG8_WAIT_L(0); PG8_BAR; PG8_MMA(1, 0, At, B0); PG8_MMA(1, 1, At, B1); PG8_BAR; PG8_SCHED;
.LBB0_193:
	s_add_u32 s25, s56, 0xfff80080
	s_addc_u32 s26, s57, -1
	s_add_i32 s27, 0, 0x10000
	s_cmp_eq_u32 s24, 28
	s_cselect_b32 s65, s45, s26
	s_cselect_b32 s64, vcc_lo, s25
	v_add_u32_e32 v140, s27, v143
	s_cselect_b32 s59, s43, s15
	s_cselect_b32 s58, vcc_hi, s14
	s_add_i32 s25, 0, 0x14000
	ds_read_b128 v[146:149], v140
	ds_read_b128 v[150:153], v140 offset:1024
	ds_read_b128 v[154:157], v140 offset:2048
	ds_read_b128 v[158:161], v140 offset:3072
	v_add_u32_e32 v140, s25, v143
	ds_read_b128 v[168:171], v140
	ds_read_b128 v[172:175], v140 offset:1024
	ds_read_b128 v[176:179], v140 offset:2048
	ds_read_b128 v[180:183], v140 offset:3072
	v_lshl_add_u64 v[140:141], s[56:57], 0, v[136:137]
	s_add_i32 m0, s75, 0xc000
	ds_read_b128 v[184:187], v145
	ds_read_b128 v[188:191], v145 offset:1024
	ds_read_b128 v[192:195], v145 offset:2048
	ds_read_b128 v[196:199], v145 offset:3072
	ds_read_b128 v[200:203], v145 offset:4096
	ds_read_b128 v[224:227], v145 offset:5120
	ds_read_b128 v[228:231], v145 offset:6144
	ds_read_b128 v[232:235], v145 offset:7168
	global_load_lds_dwordx4 v[140:141], off
	v_lshl_add_u64 v[140:141], s[56:57], 0, v[138:139]
	s_add_i32 m0, s75, 0xe000
	s_nop 0
	global_load_lds_dwordx4 v[140:141], off
	s_waitcnt vmcnt(8)
	s_waitcnt lgkmcnt(0)
	s_barrier
	v_mfma_f32_16x16x32_bf16 v[126:129], v[146:149], v[184:187], v[126:129]
	v_mfma_f32_16x16x32_bf16 v[126:129], v[150:153], v[188:191], v[126:129]
	v_mfma_f32_16x16x32_bf16 v[118:121], v[154:157], v[184:187], v[118:121]
	v_mfma_f32_16x16x32_bf16 v[118:121], v[158:161], v[188:191], v[118:121]
	v_mfma_f32_16x16x32_bf16 v[110:113], v[146:149], v[192:195], v[110:113]
	v_mfma_f32_16x16x32_bf16 v[110:113], v[150:153], v[196:199], v[110:113]
	v_mfma_f32_16x16x32_bf16 v[102:105], v[154:157], v[192:195], v[102:105]
	v_mfma_f32_16x16x32_bf16 v[102:105], v[158:161], v[196:199], v[102:105]
	v_mfma_f32_16x16x32_bf16 v[94:97], v[146:149], v[200:203], v[94:97]
	v_mfma_f32_16x16x32_bf16 v[94:97], v[150:153], v[224:227], v[94:97]
	v_mfma_f32_16x16x32_bf16 v[86:89], v[154:157], v[200:203], v[86:89]
	v_mfma_f32_16x16x32_bf16 v[86:89], v[158:161], v[224:227], v[86:89]
	v_mfma_f32_16x16x32_bf16 v[78:81], v[146:149], v[228:231], v[78:81]
	v_mfma_f32_16x16x32_bf16 v[78:81], v[150:153], v[232:235], v[78:81]
	v_mfma_f32_16x16x32_bf16 v[70:73], v[154:157], v[228:231], v[70:73]
	v_mfma_f32_16x16x32_bf16 v[70:73], v[158:161], v[232:235], v[70:73]
	v_mfma_f32_16x16x32_bf16 v[122:125], v[168:171], v[184:187], v[122:125]
	v_mfma_f32_16x16x32_bf16 v[122:125], v[172:175], v[188:191], v[122:125]
	v_mfma_f32_16x16x32_bf16 v[114:117], v[176:179], v[184:187], v[114:117]
	v_mfma_f32_16x16x32_bf16 v[114:117], v[180:183], v[188:191], v[114:117]
	v_mfma_f32_16x16x32_bf16 v[106:109], v[168:171], v[192:195], v[106:109]
	v_mfma_f32_16x16x32_bf16 v[106:109], v[172:175], v[196:199], v[106:109]
	v_mfma_f32_16x16x32_bf16 v[98:101], v[176:179], v[192:195], v[98:101]
	v_mfma_f32_16x16x32_bf16 v[98:101], v[180:183], v[196:199], v[98:101]
	v_mfma_f32_16x16x32_bf16 v[90:93], v[168:171], v[200:203], v[90:93]
	v_mfma_f32_16x16x32_bf16 v[90:93], v[172:175], v[224:227], v[90:93]
	v_mfma_f32_16x16x32_bf16 v[82:85], v[176:179], v[200:203], v[82:85]
	v_mfma_f32_16x16x32_bf16 v[82:85], v[180:183], v[224:227], v[82:85]
	v_mfma_f32_16x16x32_bf16 v[74:77], v[168:171], v[228:231], v[74:77]
	v_mfma_f32_16x16x32_bf16 v[74:77], v[172:175], v[232:235], v[74:77]
	v_mfma_f32_16x16x32_bf16 v[66:69], v[176:179], v[228:231], v[66:69]
	v_mfma_f32_16x16x32_bf16 v[66:69], v[180:183], v[232:235], v[66:69]
	s_barrier
	s_add_i32 s26, s27, s74
	v_lshl_add_u64 v[140:141], s[58:59], 0, v[0:1]
	s_mov_b32 m0, s26
	ds_read_b128 v[184:187], v145 offset:16384
	ds_read_b128 v[188:191], v145 offset:17408
	ds_read_b128 v[192:195], v145 offset:18432
	ds_read_b128 v[196:199], v145 offset:19456
	ds_read_b128 v[200:203], v145 offset:20480
	ds_read_b128 v[224:227], v145 offset:21504
	ds_read_b128 v[228:231], v145 offset:22528
	ds_read_b128 v[232:235], v145 offset:23552
	global_load_lds_dwordx4 v[140:141], off
	s_add_i32 m0, s26, 0x2000
	s_add_u32 s26, s58, 0x80000
	v_lshl_add_u64 v[236:237], s[58:59], 0, v[130:131]
	s_addc_u32 s27, s59, 0
	s_add_i32 s25, s25, s74
	global_load_lds_dwordx4 v[236:237], off
	v_lshl_add_u64 v[238:239], s[26:27], 0, v[0:1]
	s_mov_b32 m0, s25
	v_lshl_add_u64 v[240:241], s[64:65], 0, v[132:133]
	global_load_lds_dwordx4 v[238:239], off
	v_lshl_add_u64 v[238:239], s[26:27], 0, v[130:131]
	s_add_i32 m0, s25, 0x2000
	s_nop 0
	global_load_lds_dwordx4 v[238:239], off
	v_lshl_add_u64 v[238:239], s[64:65], 0, v[134:135]
	s_mov_b32 m0, s75
	s_nop 0
	global_load_lds_dwordx4 v[238:239], off
	s_mov_b32 m0, s21
	s_nop 0
	global_load_lds_dwordx4 v[240:241], off
	s_waitcnt vmcnt(8)
	s_waitcnt lgkmcnt(0)
	s_barrier
; #define PG8_STAGE(bufoff, gbase, voff) do { _Pragma("unroll") for (int _i = 0; _i < 2; ++_i) \
;         __builtin_amdgcn_global_load_lds((const unsigned*)((const char*)(gbase) + (voff)[_i]), (PG8_LAS unsigned*)(lds + (bufoff) + ldsw + _i * 8192), 16, 0, 0); } while (0)
; #define PG8_LDA(dst, b, h) do { _Pragma("unroll") for (int m = 0; m < 4; ++m) _Pragma("unroll") for (int k = 0; k < 2; ++k) dst[m][k] = *(const PG8_LAS bf16x8*)(lds + PG8_SA(b, h) + aoff + m * 2048 + k * 1024); } while (0)
; #define PG8_LDB(dst, b, h) do { _Pragma("unroll") for (int n = 0; n < 2; ++n) _Pragma("unroll") for (int k = 0; k < 2; ++k) dst[n][k] = *(const PG8_LAS bf16x8*)(lds + PG8_SB(b, h) + boff + n * 2048 + k * 1024); } while (0)
; #define PG8_MMA(ai, bj, At, Bt) do { __builtin_amdgcn_s_setprio(1); _Pragma("unroll") for (int m = 0; m < 4; ++m) _Pragma("unroll") for (int n = 0; n < 2; ++n) _Pragma("unroll") for (int k = 0; k < 2; ++k) \
;         acc[ai][bj][m][n] = __builtin_amdgcn_mfma_f32_16x16x32_bf16(Bt[n][k], At[m][k], acc[ai][bj][m][n], 0, 0, 0); __builtin_amdgcn_s_setprio(0); } while (0)
; #define PG8_WAIT_V(n) asm volatile("s_waitcnt vmcnt(" #n ")" ::: "memory")
; #define PG8_WAIT_L(n) asm volatile("s_waitcnt lgkmcnt(" #n ")" ::: "memory")
; #define PG8_BAR __builtin_amdgcn_s_barrier()
; #define PG8_SCHED __builtin_amdgcn_sched_barrier(0)
; template <class Epi, class Sched, bool ALIGN_EPI = false, bool SP2 = false>
; __device__ __forceinline__ void gemm_phase(PG8_LAS unsigned char* lds, const Gemm g, const Sched S, const Epi E) {
;     ...
;             PG8_WAIT_V(8); PG8_WAIT_L(0); PG8_BAR; PG8_MMA(1, 0, At, B0); PG8_MMA(1, 1, At, B1); PG8_BAR; PG8_SCHED;
;             PG8_LDB(B0, 1, 0); PG8_LDB(B1, 1, 1); PG8_SCHED; PG8_LDA(At, 1, 0); PG8_STAGE(PG8_SA(0, 1), a2 + hstep, voffA);
;             PG8_WAIT_V(8); PG8_WAIT_L(0); PG8_BAR; PG8_MMA(0, 0, At, B0); PG8_MMA(0, 1, At, B1); PG8_BAR; PG8_SCHED;
	v_mfma_f32_16x16x32_bf16 v[62:65], v[146:149], v[184:187], v[62:65]
	v_mfma_f32_16x16x32_bf16 v[62:65], v[150:153], v[188:191], v[62:65]
	v_mfma_f32_16x16x32_bf16 v[54:57], v[154:157], v[184:187], v[54:57]
	v_mfma_f32_16x16x32_bf16 v[54:57], v[158:161], v[188:191], v[54:57]
	v_mfma_f32_16x16x32_bf16 v[46:49], v[146:149], v[192:195], v[46:49]
	v_mfma_f32_16x16x32_bf16 v[46:49], v[150:153], v[196:199], v[46:49]
	v_mfma_f32_16x16x32_bf16 v[38:41], v[154:157], v[192:195], v[38:41]
	v_mfma_f32_16x16x32_bf16 v[38:41], v[158:161], v[196:199], v[38:41]
	v_mfma_f32_16x16x32_bf16 v[30:33], v[146:149], v[200:203], v[30:33]
	v_mfma_f32_16x16x32_bf16 v[30:33], v[150:153], v[224:227], v[30:33]
	v_mfma_f32_16x16x32_bf16 v[22:25], v[154:157], v[200:203], v[22:25]
	v_mfma_f32_16x16x32_bf16 v[22:25], v[158:161], v[224:227], v[22:25]
	v_mfma_f32_16x16x32_bf16 v[14:17], v[146:149], v[228:231], v[14:17]
	v_mfma_f32_16x16x32_bf16 v[14:17], v[150:153], v[232:235], v[14:17]
	v_mfma_f32_16x16x32_bf16 v[6:9], v[154:157], v[228:231], v[6:9]
	v_mfma_f32_16x16x32_bf16 v[6:9], v[158:161], v[232:235], v[6:9]
	v_mfma_f32_16x16x32_bf16 v[58:61], v[168:171], v[184:187], v[58:61]
	v_mfma_f32_16x16x32_bf16 v[58:61], v[172:175], v[188:191], v[58:61]
	v_mfma_f32_16x16x32_bf16 v[50:53], v[176:179], v[184:187], v[50:53]
	v_mfma_f32_16x16x32_bf16 v[50:53], v[180:183], v[188:191], v[50:53]
	v_mfma_f32_16x16x32_bf16 v[42:45], v[168:171], v[192:195], v[42:45]
	v_mfma_f32_16x16x32_bf16 v[42:45], v[172:175], v[196:199], v[42:45]
	v_mfma_f32_16x16x32_bf16 v[34:37], v[176:179], v[192:195], v[34:37]
	v_mfma_f32_16x16x32_bf16 v[34:37], v[180:183], v[196:199], v[34:37]
	v_mfma_f32_16x16x32_bf16 v[26:29], v[168:171], v[200:203], v[26:29]
	v_mfma_f32_16x16x32_bf16 v[26:29], v[172:175], v[224:227], v[26:29]
	v_mfma_f32_16x16x32_bf16 v[18:21], v[176:179], v[200:203], v[18:21]
	v_mfma_f32_16x16x32_bf16 v[18:21], v[180:183], v[224:227], v[18:21]
	v_mfma_f32_16x16x32_bf16 v[10:13], v[168:171], v[228:231], v[10:13]
	v_mfma_f32_16x16x32_bf16 v[10:13], v[172:175], v[232:235], v[10:13]
	v_mfma_f32_16x16x32_bf16 v[2:5], v[176:179], v[228:231], v[2:5]
	v_mfma_f32_16x16x32_bf16 v[2:5], v[180:183], v[232:235], v[2:5]
	s_barrier
	s_add_i32 s25, 0, 0x18000
	s_add_i32 s30, 0, 0x1c000
	v_add_u32_e32 v158, s25, v143
	v_add_u32_e32 v167, s30, v143
	ds_read_b128 v[146:149], v158
	ds_read_b128 v[150:153], v158 offset:1024
	ds_read_b128 v[154:157], v158 offset:2048
	ds_read_b128 v[158:161], v158 offset:3072
	ds_read_b128 v[168:171], v167
	ds_read_b128 v[172:175], v167 offset:1024
	ds_read_b128 v[176:179], v167 offset:2048
	ds_read_b128 v[180:183], v167 offset:3072
	s_add_u32 s26, s64, 0x80000
	s_addc_u32 s27, s65, 0
	s_mov_b32 m0, s47
	v_lshl_add_u64 v[242:243], s[26:27], 0, v[134:135]
	ds_read_b128 v[184:187], v145 offset:32768
	ds_read_b128 v[188:191], v145 offset:33792
	ds_read_b128 v[192:195], v145 offset:34816
	ds_read_b128 v[196:199], v145 offset:35840
	ds_read_b128 v[200:203], v145 offset:36864
	ds_read_b128 v[224:227], v145 offset:37888
	ds_read_b128 v[228:231], v145 offset:38912
	ds_read_b128 v[232:235], v145 offset:39936
	global_load_lds_dwordx4 v[242:243], off
	v_lshl_add_u64 v[242:243], s[26:27], 0, v[132:133]
	s_mov_b32 m0, s77
	s_nop 0
	global_load_lds_dwordx4 v[242:243], off
	s_waitcnt vmcnt(8)
	s_waitcnt lgkmcnt(0)
	s_barrier
	v_mfma_f32_16x16x32_bf16 v[126:129], v[146:149], v[184:187], v[126:129]
	v_mfma_f32_16x16x32_bf16 v[126:129], v[150:153], v[188:191], v[126:129]
	v_mfma_f32_16x16x32_bf16 v[118:121], v[154:157], v[184:187], v[118:121]
	v_mfma_f32_16x16x32_bf16 v[118:121], v[158:161], v[188:191], v[118:121]
	v_mfma_f32_16x16x32_bf16 v[110:113], v[146:149], v[192:195], v[110:113]
	v_mfma_f32_16x16x32_bf16 v[110:113], v[150:153], v[196:199], v[110:113]
	v_mfma_f32_16x16x32_bf16 v[102:105], v[154:157], v[192:195], v[102:105]
	v_mfma_f32_16x16x32_bf16 v[102:105], v[158:161], v[196:199], v[102:105]
	v_mfma_f32_16x16x32_bf16 v[94:97], v[146:149], v[200:203], v[94:97]
	v_mfma_f32_16x16x32_bf16 v[94:97], v[150:153], v[224:227], v[94:97]
	v_mfma_f32_16x16x32_bf16 v[86:89], v[154:157], v[200:203], v[86:89]
	v_mfma_f32_16x16x32_bf16 v[86:89], v[158:161], v[224:227], v[86:89]
	v_mfma_f32_16x16x32_bf16 v[78:81], v[146:149], v[228:231], v[78:81]
	v_mfma_f32_16x16x32_bf16 v[78:81], v[150:153], v[232:235], v[78:81]
	v_mfma_f32_16x16x32_bf16 v[70:73], v[154:157], v[228:231], v[70:73]
	v_mfma_f32_16x16x32_bf16 v[70:73], v[158:161], v[232:235], v[70:73]
	v_mfma_f32_16x16x32_bf16 v[122:125], v[168:171], v[184:187], v[122:125]
	v_mfma_f32_16x16x32_bf16 v[122:125], v[172:175], v[188:191], v[122:125]
	v_mfma_f32_16x16x32_bf16 v[114:117], v[176:179], v[184:187], v[114:117]
	v_mfma_f32_16x16x32_bf16 v[114:117], v[180:183], v[188:191], v[114:117]
	v_mfma_f32_16x16x32_bf16 v[106:109], v[168:171], v[192:195], v[106:109]
	v_mfma_f32_16x16x32_bf16 v[106:109], v[172:175], v[196:199], v[106:109]
	v_mfma_f32_16x16x32_bf16 v[98:101], v[176:179], v[192:195], v[98:101]
	v_mfma_f32_16x16x32_bf16 v[98:101], v[180:183], v[196:199], v[98:101]
	v_mfma_f32_16x16x32_bf16 v[90:93], v[168:171], v[200:203], v[90:93]
	v_mfma_f32_16x16x32_bf16 v[90:93], v[172:175], v[224:227], v[90:93]
	v_mfma_f32_16x16x32_bf16 v[82:85], v[176:179], v[200:203], v[82:85]
	v_mfma_f32_16x16x32_bf16 v[82:85], v[180:183], v[224:227], v[82:85]
	v_mfma_f32_16x16x32_bf16 v[74:77], v[168:171], v[228:231], v[74:77]
	v_mfma_f32_16x16x32_bf16 v[74:77], v[172:175], v[232:235], v[74:77]
	v_mfma_f32_16x16x32_bf16 v[66:69], v[176:179], v[228:231], v[66:69]
	v_mfma_f32_16x16x32_bf16 v[66:69], v[180:183], v[232:235], v[66:69]
	s_barrier
; #define PG8_STAGE(bufoff, gbase, voff) do { _Pragma("unroll") for (int _i = 0; _i < 2; ++_i) \
;         __builtin_amdgcn_global_load_lds((const unsigned*)((const char*)(gbase) + (voff)[_i]), (PG8_LAS unsigned*)(lds + (bufoff) + ldsw + _i * 8192), 16, 0, 0); } while (0)
; #define PG8_LDA(dst, b, h) do { _Pragma("unroll") for (int m = 0; m < 4; ++m) _Pragma("unroll") for (int k = 0; k < 2; ++k) dst[m][k] = *(const PG8_LAS bf16x8*)(lds + PG8_SA(b, h) + aoff + m * 2048 + k * 1024); } while (0)
; #define PG8_MMA(ai, bj, At, Bt) do { __builtin_amdgcn_s_setprio(1); _Pragma("unroll") for (int m = 0; m < 4; ++m) _Pragma("unroll") for (int n = 0; n < 2; ++n) _Pragma("unroll") for (int k = 0; k < 2; ++k) \
;         acc[ai][bj][m][n] = __builtin_amdgcn_mfma_f32_16x16x32_bf16(Bt[n][k], At[m][k], acc[ai][bj][m][n], 0, 0, 0); __builtin_amdgcn_s_setprio(0); } while (0)
; #define PG8_WAIT_V(n) asm volatile("s_waitcnt vmcnt(" #n ")" ::: "memory")
; #define PG8_WAIT_L(n) asm volatile("s_waitcnt lgkmcnt(" #n ")" ::: "memory")
; #define PG8_BAR __builtin_amdgcn_s_barrier()
; #define PG8_SCHED __builtin_amdgcn_sched_barrier(0)
; template <class Epi, class Sched, bool ALIGN_EPI = false, bool SP2 = false>
; __device__ __forceinline__ void gemm_phase(PG8_LAS unsigned char* lds, const Gemm g, const Sched S, const Epi E) {
;     ...
;             PG8_LDA(At, 1, 1); PG8_STAGE(PG8_SB(1, 0), b3, voffB); PG8_STAGE(PG8_SB(1, 1), b3 + hstep, voffB); PG8_STAGE(PG8_SA(1, 0), a3, voffA);
;             PG8_WAIT_V(8); PG8_WAIT_L(0); PG8_BAR; PG8_MMA(1, 0, At, B0); PG8_MMA(1, 1, At, B1); PG8_BAR; PG8_SCHED;
;     ...
;         if constexpr (ALIGN_EPI) { if (wr == 0) PG8_BAR; }
	s_add_i32 s25, s25, s74
	v_lshl_add_u64 v[140:141], v[140:141], 0, s[28:29]
	s_mov_b32 m0, s25
	ds_read_b128 v[184:187], v145 offset:49152
	ds_read_b128 v[188:191], v145 offset:50176
	ds_read_b128 v[192:195], v145 offset:51200
	ds_read_b128 v[196:199], v145 offset:52224
	ds_read_b128 v[200:203], v145 offset:53248
	ds_read_b128 v[224:227], v145 offset:54272
	ds_read_b128 v[228:231], v145 offset:55296
	ds_read_b128 v[232:235], v145 offset:56320
	global_load_lds_dwordx4 v[140:141], off
	s_add_i32 m0, s25, 0x2000
	s_add_u32 s26, s58, 0x80080
	v_lshl_add_u64 v[140:141], v[236:237], 0, s[28:29]
	s_addc_u32 s27, s59, 0
	s_add_i32 s25, s30, s74
	global_load_lds_dwordx4 v[140:141], off
	v_lshl_add_u64 v[140:141], s[26:27], 0, v[0:1]
	s_mov_b32 m0, s25
	s_nop 0
	global_load_lds_dwordx4 v[140:141], off
	v_lshl_add_u64 v[140:141], s[26:27], 0, v[130:131]
	s_add_i32 m0, s25, 0x2000
	s_nop 0
	global_load_lds_dwordx4 v[140:141], off
	v_lshl_add_u64 v[140:141], v[238:239], 0, s[28:29]
	s_mov_b32 m0, s62
	s_nop 0
	global_load_lds_dwordx4 v[140:141], off
	v_lshl_add_u64 v[140:141], v[240:241], 0, s[28:29]
	s_mov_b32 m0, s63
	s_nop 0
	global_load_lds_dwordx4 v[140:141], off
	s_waitcnt vmcnt(8)
	s_waitcnt lgkmcnt(0)
	s_barrier
	v_mfma_f32_16x16x32_bf16 v[62:65], v[146:149], v[184:187], v[62:65]
	v_mfma_f32_16x16x32_bf16 v[62:65], v[150:153], v[188:191], v[62:65]
	v_mfma_f32_16x16x32_bf16 v[54:57], v[154:157], v[184:187], v[54:57]
	v_mfma_f32_16x16x32_bf16 v[54:57], v[158:161], v[188:191], v[54:57]
	v_mfma_f32_16x16x32_bf16 v[46:49], v[146:149], v[192:195], v[46:49]
	v_mfma_f32_16x16x32_bf16 v[46:49], v[150:153], v[196:199], v[46:49]
	v_mfma_f32_16x16x32_bf16 v[38:41], v[154:157], v[192:195], v[38:41]
	v_mfma_f32_16x16x32_bf16 v[38:41], v[158:161], v[196:199], v[38:41]
	v_mfma_f32_16x16x32_bf16 v[30:33], v[146:149], v[200:203], v[30:33]
	v_mfma_f32_16x16x32_bf16 v[30:33], v[150:153], v[224:227], v[30:33]
	v_mfma_f32_16x16x32_bf16 v[22:25], v[154:157], v[200:203], v[22:25]
	v_mfma_f32_16x16x32_bf16 v[22:25], v[158:161], v[224:227], v[22:25]
	v_mfma_f32_16x16x32_bf16 v[14:17], v[146:149], v[228:231], v[14:17]
	v_mfma_f32_16x16x32_bf16 v[14:17], v[150:153], v[232:235], v[14:17]
	v_mfma_f32_16x16x32_bf16 v[6:9], v[154:157], v[228:231], v[6:9]
	v_mfma_f32_16x16x32_bf16 v[6:9], v[158:161], v[232:235], v[6:9]
	v_mfma_f32_16x16x32_bf16 v[58:61], v[168:171], v[184:187], v[58:61]
	v_mfma_f32_16x16x32_bf16 v[58:61], v[172:175], v[188:191], v[58:61]
	v_mfma_f32_16x16x32_bf16 v[50:53], v[176:179], v[184:187], v[50:53]
	v_mfma_f32_16x16x32_bf16 v[50:53], v[180:183], v[188:191], v[50:53]
	v_mfma_f32_16x16x32_bf16 v[42:45], v[168:171], v[192:195], v[42:45]
	v_mfma_f32_16x16x32_bf16 v[42:45], v[172:175], v[196:199], v[42:45]
	v_mfma_f32_16x16x32_bf16 v[34:37], v[176:179], v[192:195], v[34:37]
	v_mfma_f32_16x16x32_bf16 v[34:37], v[180:183], v[196:199], v[34:37]
	v_mfma_f32_16x16x32_bf16 v[26:29], v[168:171], v[200:203], v[26:29]
	v_mfma_f32_16x16x32_bf16 v[26:29], v[172:175], v[224:227], v[26:29]
	v_mfma_f32_16x16x32_bf16 v[18:21], v[176:179], v[200:203], v[18:21]
	v_mfma_f32_16x16x32_bf16 v[18:21], v[180:183], v[224:227], v[18:21]
	v_mfma_f32_16x16x32_bf16 v[10:13], v[168:171], v[228:231], v[10:13]
	v_mfma_f32_16x16x32_bf16 v[10:13], v[172:175], v[232:235], v[10:13]
	v_mfma_f32_16x16x32_bf16 v[2:5], v[176:179], v[228:231], v[2:5]
	v_mfma_f32_16x16x32_bf16 v[2:5], v[180:183], v[232:235], v[2:5]
	s_barrier
	s_add_i32 s24, s24, 2
	s_add_u32 s56, s56, 0x100
	s_addc_u32 s57, s57, 0
	s_add_u32 s14, s14, 0x100
	s_addc_u32 s15, s15, 0
	s_cmp_gt_u32 s24, 29
	s_cbranch_scc0 .LBB0_193
	s_and_b64 vcc, exec, s[40:41]
	s_cbranch_vccz .LBB0_196
	s_barrier

; #define PG8_STAGE(bufoff, gbase, voff) do { _Pragma("unroll") for (int _i = 0; _i < 2; ++_i) \
;         __builtin_amdgcn_global_load_lds((const unsigned*)((const char*)(gbase) + (voff)[_i]), (PG8_LAS unsigned*)(lds + (bufoff) + ldsw + _i * 8192), 16, 0, 0); } while (0)
; #define PG8_LDA(dst, b, h) do { _Pragma("unroll") for (int m = 0; m < 4; ++m) _Pragma("unroll") for (int k = 0; k < 2; ++k) dst[m][k] = *(const PG8_LAS bf16x8*)(lds + PG8_SA(b, h) + aoff + m * 2048 + k * 1024); } while (0)
; #define PG8_LDB(dst, b, h) do { _Pragma("unroll") for (int n = 0; n < 2; ++n) _Pragma("unroll") for (int k = 0; k < 2; ++k) dst[n][k] = *(const PG8_LAS bf16x8*)(lds + PG8_SB(b, h) + boff + n * 2048 + k * 1024); } while (0)
; #define PG8_MMA(ai, bj, At, Bt) do { __builtin_amdgcn_s_setprio(1); _Pragma("unroll") for (int m = 0; m < 4; ++m) _Pragma("unroll") for (int n = 0; n < 2; ++n) _Pragma("unroll") for (int k = 0; k < 2; ++k) \
;         acc[ai][bj][m][n] = __builtin_amdgcn_mfma_f32_16x16x32_bf16(Bt[n][k], At[m][k], acc[ai][bj][m][n], 0, 0, 0); __builtin_amdgcn_s_setprio(0); } while (0)
; #define PG8_WAIT_V(n) asm volatile("s_waitcnt vmcnt(" #n ")" ::: "memory")
; #define PG8_BAR __builtin_amdgcn_s_barrier()
; template <class Epi, class Sched, bool ALIGN_EPI = false, bool SP2 = false>
; __device__ __forceinline__ void gemm_phase(PG8_LAS unsigned char* lds, const Gemm g, const Sched S, const Epi E) {
;     ...
;         for (int t = 0; t < nt; t += 2) {
;             const bool last = (t == nt - 2);
;             const char* a1 = cA + (size_t)(t + 1) * kstep;
;             const char* a2 = last ? nA : cA + (size_t)(t + 2) * kstep; const char* b2 = last ? nB : cB + (size_t)(t + 2) * kstep;
;             const char* a3 = a2 + kstep; const char* b3 = b2 + kstep;
;             if (last && has_next) S.a_ready(nxt);
;             if constexpr (SP2) {
;             PG8_LDB(B0, 0, 0); PG8_LDB(B1, 0, 1); PG8_SCHED; PG8_LDA(At, 0, 0); PG8_STAGE(PG8_SA(1, 1), a1 + hstep, voffA);
;             PG8_WAIT_V(8); PG8_WAIT_L(0); PG8_BAR; PG8_MMA(0, 0, At, B0); PG8_MMA(0, 1, At, B1); PG8_BAR; PG8_SCHED;
;             PG8_LDA(At, 0, 1); PG8_STAGE(PG8_SB(0, 0), b2, voffB); PG8_STAGE(PG8_SB(0, 1), b2 + hstep, voffB); PG8_STAGE(PG8_SA(0, 0), a2, voffA);
;             PG8_WAIT_V(8); PG8_WAIT_L(0); PG8_BAR; PG8_MMA(1, 0, At, B0); PG8_MMA(1, 1, At, B1); PG8_BAR; PG8_SCHED;
.LBB0_272:
	s_add_u32 s52, s50, 0x100
	s_addc_u32 s53, s51, 0
	s_add_i32 s24, 0, 0x10000
	s_cmpk_eq_i32 s15, 0x54
	s_cselect_b32 s59, s1, s53
	s_cselect_b32 s58, s0, s52
	v_add_u32_e32 v140, s24, v143
	s_cselect_b32 s57, s45, s14
	s_cselect_b32 s56, s44, s5
	s_add_i32 s26, 0, 0x14000
	ds_read_b128 v[136:139], v140
	ds_read_b128 v[146:149], v140 offset:1024
	ds_read_b128 v[150:153], v140 offset:2048
	ds_read_b128 v[154:157], v140 offset:3072
	v_add_u32_e32 v140, s26, v143
	ds_read_b128 v[158:161], v140
	ds_read_b128 v[168:171], v140 offset:1024
	ds_read_b128 v[172:175], v140 offset:2048
	ds_read_b128 v[176:179], v140 offset:3072
	v_lshl_add_u64 v[140:141], s[50:51], 0, v[132:133]
	s_add_i32 m0, s47, 0xc000
	ds_read_b128 v[180:183], v145
	ds_read_b128 v[184:187], v145 offset:1024
	ds_read_b128 v[188:191], v145 offset:2048
	ds_read_b128 v[192:195], v145 offset:3072
	ds_read_b128 v[196:199], v145 offset:4096
	ds_read_b128 v[200:203], v145 offset:5120
	ds_read_b128 v[224:227], v145 offset:6144
	ds_read_b128 v[228:231], v145 offset:7168
	global_load_lds_dwordx4 v[140:141], off
	v_lshl_add_u64 v[140:141], s[50:51], 0, v[134:135]
	s_add_i32 m0, s47, 0xe000
	s_nop 0
	global_load_lds_dwordx4 v[140:141], off
	s_waitcnt vmcnt(8)
	s_waitcnt lgkmcnt(0)
	s_barrier
	v_mfma_f32_16x16x32_bf16 v[126:129], v[136:139], v[180:183], v[126:129]
	v_mfma_f32_16x16x32_bf16 v[126:129], v[146:149], v[184:187], v[126:129]
	v_mfma_f32_16x16x32_bf16 v[122:125], v[150:153], v[180:183], v[122:125]
	v_mfma_f32_16x16x32_bf16 v[122:125], v[154:157], v[184:187], v[122:125]
	v_mfma_f32_16x16x32_bf16 v[110:113], v[136:139], v[188:191], v[110:113]
	v_mfma_f32_16x16x32_bf16 v[110:113], v[146:149], v[192:195], v[110:113]
	v_mfma_f32_16x16x32_bf16 v[106:109], v[150:153], v[188:191], v[106:109]
	v_mfma_f32_16x16x32_bf16 v[106:109], v[154:157], v[192:195], v[106:109]
	v_mfma_f32_16x16x32_bf16 v[94:97], v[136:139], v[196:199], v[94:97]
	v_mfma_f32_16x16x32_bf16 v[94:97], v[146:149], v[200:203], v[94:97]
	v_mfma_f32_16x16x32_bf16 v[90:93], v[150:153], v[196:199], v[90:93]
	v_mfma_f32_16x16x32_bf16 v[90:93], v[154:157], v[200:203], v[90:93]
	v_mfma_f32_16x16x32_bf16 v[78:81], v[136:139], v[224:227], v[78:81]
	v_mfma_f32_16x16x32_bf16 v[78:81], v[146:149], v[228:231], v[78:81]
	v_mfma_f32_16x16x32_bf16 v[74:77], v[150:153], v[224:227], v[74:77]
	v_mfma_f32_16x16x32_bf16 v[74:77], v[154:157], v[228:231], v[74:77]
	v_mfma_f32_16x16x32_bf16 v[118:121], v[158:161], v[180:183], v[118:121]
	v_mfma_f32_16x16x32_bf16 v[118:121], v[168:171], v[184:187], v[118:121]
	v_mfma_f32_16x16x32_bf16 v[114:117], v[172:175], v[180:183], v[114:117]
	v_mfma_f32_16x16x32_bf16 v[114:117], v[176:179], v[184:187], v[114:117]
	v_mfma_f32_16x16x32_bf16 v[102:105], v[158:161], v[188:191], v[102:105]
	v_mfma_f32_16x16x32_bf16 v[102:105], v[168:171], v[192:195], v[102:105]
	v_mfma_f32_16x16x32_bf16 v[98:101], v[172:175], v[188:191], v[98:101]
	v_mfma_f32_16x16x32_bf16 v[98:101], v[176:179], v[192:195], v[98:101]
	v_mfma_f32_16x16x32_bf16 v[86:89], v[158:161], v[196:199], v[86:89]
	v_mfma_f32_16x16x32_bf16 v[86:89], v[168:171], v[200:203], v[86:89]
	v_mfma_f32_16x16x32_bf16 v[82:85], v[172:175], v[196:199], v[82:85]
	v_mfma_f32_16x16x32_bf16 v[82:85], v[176:179], v[200:203], v[82:85]
	v_mfma_f32_16x16x32_bf16 v[70:73], v[158:161], v[224:227], v[70:73]
	v_mfma_f32_16x16x32_bf16 v[70:73], v[168:171], v[228:231], v[70:73]
	v_mfma_f32_16x16x32_bf16 v[66:69], v[172:175], v[224:227], v[66:69]
	v_mfma_f32_16x16x32_bf16 v[66:69], v[176:179], v[228:231], v[66:69]
	s_barrier
	s_add_i32 s24, s24, s22
	v_lshl_add_u64 v[140:141], s[56:57], 0, v[0:1]
	s_mov_b32 m0, s24
	ds_read_b128 v[180:183], v145 offset:16384
	ds_read_b128 v[184:187], v145 offset:17408
	ds_read_b128 v[188:191], v145 offset:18432
	ds_read_b128 v[192:195], v145 offset:19456
	ds_read_b128 v[196:199], v145 offset:20480
	ds_read_b128 v[200:203], v145 offset:21504
	ds_read_b128 v[224:227], v145 offset:22528
	ds_read_b128 v[228:231], v145 offset:23552
	global_load_lds_dwordx4 v[140:141], off
	s_add_i32 m0, s24, 0x2000
	s_add_u32 s24, s56, 0x160000
	v_lshl_add_u64 v[232:233], s[56:57], 0, v[130:131]
	s_addc_u32 s25, s57, 0
	s_add_i32 s26, s26, s22
	global_load_lds_dwordx4 v[232:233], off
	v_lshl_add_u64 v[234:235], s[24:25], 0, v[0:1]
	s_mov_b32 m0, s26
	v_lshl_add_u64 v[236:237], s[58:59], 0, v[130:131]
	global_load_lds_dwordx4 v[234:235], off
	v_lshl_add_u64 v[234:235], s[24:25], 0, v[130:131]
	s_add_i32 m0, s26, 0x2000
	s_nop 0
	global_load_lds_dwordx4 v[234:235], off
	v_lshl_add_u64 v[234:235], s[58:59], 0, v[0:1]
	s_mov_b32 m0, s47
	s_nop 0
	global_load_lds_dwordx4 v[234:235], off
	s_mov_b32 m0, s62
	s_nop 0
	global_load_lds_dwordx4 v[236:237], off
	s_waitcnt vmcnt(8)
	s_waitcnt lgkmcnt(0)
	s_barrier
; #define PG8_STAGE(bufoff, gbase, voff) do { _Pragma("unroll") for (int _i = 0; _i < 2; ++_i) \
;         __builtin_amdgcn_global_load_lds((const unsigned*)((const char*)(gbase) + (voff)[_i]), (PG8_LAS unsigned*)(lds + (bufoff) + ldsw + _i * 8192), 16, 0, 0); } while (0)
; #define PG8_LDA(dst, b, h) do { _Pragma("unroll") for (int m = 0; m < 4; ++m) _Pragma("unroll") for (int k = 0; k < 2; ++k) dst[m][k] = *(const PG8_LAS bf16x8*)(lds + PG8_SA(b, h) + aoff + m * 2048 + k * 1024); } while (0)
; #define PG8_LDB(dst, b, h) do { _Pragma("unroll") for (int n = 0; n < 2; ++n) _Pragma("unroll") for (int k = 0; k < 2; ++k) dst[n][k] = *(const PG8_LAS bf16x8*)(lds + PG8_SB(b, h) + boff + n * 2048 + k * 1024); } while (0)
; #define PG8_MMA(ai, bj, At, Bt) do { __builtin_amdgcn_s_setprio(1); _Pragma("unroll") for (int m = 0; m < 4; ++m) _Pragma("unroll") for (int n = 0; n < 2; ++n) _Pragma("unroll") for (int k = 0; k < 2; ++k) \
;         acc[ai][bj][m][n] = __builtin_amdgcn_mfma_f32_16x16x32_bf16(Bt[n][k], At[m][k], acc[ai][bj][m][n], 0, 0, 0); __builtin_amdgcn_s_setprio(0); } while (0)
; #define PG8_WAIT_V(n) asm volatile("s_waitcnt vmcnt(" #n ")" ::: "memory")
; #define PG8_WAIT_L(n) asm volatile("s_waitcnt lgkmcnt(" #n ")" ::: "memory")
; #define PG8_BAR __builtin_amdgcn_s_barrier()
; #define PG8_SCHED __builtin_amdgcn_sched_barrier(0)
; template <class Epi, class Sched, bool ALIGN_EPI = false, bool SP2 = false>
; __device__ __forceinline__ void gemm_phase(PG8_LAS unsigned char* lds, const Gemm g, const Sched S, const Epi E) {
;     ...
;             PG8_WAIT_V(8); PG8_WAIT_L(0); PG8_BAR; PG8_MMA(1, 0, At, B0); PG8_MMA(1, 1, At, B1); PG8_BAR; PG8_SCHED;
;             PG8_LDB(B0, 1, 0); PG8_LDB(B1, 1, 1); PG8_SCHED; PG8_LDA(At, 1, 0); PG8_STAGE(PG8_SA(0, 1), a2 + hstep, voffA);
;             PG8_WAIT_V(8); PG8_WAIT_L(0); PG8_BAR; PG8_MMA(0, 0, At, B0); PG8_MMA(0, 1, At, B1); PG8_BAR; PG8_SCHED;
	v_mfma_f32_16x16x32_bf16 v[62:65], v[136:139], v[180:183], v[62:65]
	v_mfma_f32_16x16x32_bf16 v[62:65], v[146:149], v[184:187], v[62:65]
	v_mfma_f32_16x16x32_bf16 v[58:61], v[150:153], v[180:183], v[58:61]
	v_mfma_f32_16x16x32_bf16 v[58:61], v[154:157], v[184:187], v[58:61]
	v_mfma_f32_16x16x32_bf16 v[46:49], v[136:139], v[188:191], v[46:49]
	v_mfma_f32_16x16x32_bf16 v[46:49], v[146:149], v[192:195], v[46:49]
	v_mfma_f32_16x16x32_bf16 v[42:45], v[150:153], v[188:191], v[42:45]
	v_mfma_f32_16x16x32_bf16 v[42:45], v[154:157], v[192:195], v[42:45]
	v_mfma_f32_16x16x32_bf16 v[30:33], v[136:139], v[196:199], v[30:33]
	v_mfma_f32_16x16x32_bf16 v[30:33], v[146:149], v[200:203], v[30:33]
	v_mfma_f32_16x16x32_bf16 v[26:29], v[150:153], v[196:199], v[26:29]
	v_mfma_f32_16x16x32_bf16 v[26:29], v[154:157], v[200:203], v[26:29]
	v_mfma_f32_16x16x32_bf16 v[14:17], v[136:139], v[224:227], v[14:17]
	v_mfma_f32_16x16x32_bf16 v[14:17], v[146:149], v[228:231], v[14:17]
	v_mfma_f32_16x16x32_bf16 v[10:13], v[150:153], v[224:227], v[10:13]
	v_mfma_f32_16x16x32_bf16 v[10:13], v[154:157], v[228:231], v[10:13]
	v_mfma_f32_16x16x32_bf16 v[54:57], v[158:161], v[180:183], v[54:57]
	v_mfma_f32_16x16x32_bf16 v[54:57], v[168:171], v[184:187], v[54:57]
	v_mfma_f32_16x16x32_bf16 v[50:53], v[172:175], v[180:183], v[50:53]
	v_mfma_f32_16x16x32_bf16 v[50:53], v[176:179], v[184:187], v[50:53]
	v_mfma_f32_16x16x32_bf16 v[38:41], v[158:161], v[188:191], v[38:41]
	v_mfma_f32_16x16x32_bf16 v[38:41], v[168:171], v[192:195], v[38:41]
	v_mfma_f32_16x16x32_bf16 v[34:37], v[172:175], v[188:191], v[34:37]
	v_mfma_f32_16x16x32_bf16 v[34:37], v[176:179], v[192:195], v[34:37]
	v_mfma_f32_16x16x32_bf16 v[22:25], v[158:161], v[196:199], v[22:25]
	v_mfma_f32_16x16x32_bf16 v[22:25], v[168:171], v[200:203], v[22:25]
	v_mfma_f32_16x16x32_bf16 v[18:21], v[172:175], v[196:199], v[18:21]
	v_mfma_f32_16x16x32_bf16 v[18:21], v[176:179], v[200:203], v[18:21]
	v_mfma_f32_16x16x32_bf16 v[6:9], v[158:161], v[224:227], v[6:9]
	v_mfma_f32_16x16x32_bf16 v[6:9], v[168:171], v[228:231], v[6:9]
	v_mfma_f32_16x16x32_bf16 v[2:5], v[172:175], v[224:227], v[2:5]
	v_mfma_f32_16x16x32_bf16 v[2:5], v[176:179], v[228:231], v[2:5]
	s_barrier
	s_add_i32 s26, 0, 0x18000
	s_add_i32 s27, 0, 0x1c000
	v_add_u32_e32 v154, s26, v143
	v_add_u32_e32 v167, s27, v143
	ds_read_b128 v[136:139], v154
	ds_read_b128 v[146:149], v154 offset:1024
	ds_read_b128 v[150:153], v154 offset:2048
	ds_read_b128 v[154:157], v154 offset:3072
	ds_read_b128 v[158:161], v167
	ds_read_b128 v[168:171], v167 offset:1024
	ds_read_b128 v[172:175], v167 offset:2048
	ds_read_b128 v[176:179], v167 offset:3072
	s_add_u32 s24, s58, 0x160000
	s_addc_u32 s25, s59, 0
	s_mov_b32 m0, s63
	v_lshl_add_u64 v[238:239], s[24:25], 0, v[0:1]
	ds_read_b128 v[180:183], v145 offset:32768
	ds_read_b128 v[184:187], v145 offset:33792
	ds_read_b128 v[188:191], v145 offset:34816
	ds_read_b128 v[192:195], v145 offset:35840
	ds_read_b128 v[196:199], v145 offset:36864
	ds_read_b128 v[200:203], v145 offset:37888
	ds_read_b128 v[224:227], v145 offset:38912
	ds_read_b128 v[228:231], v145 offset:39936
	global_load_lds_dwordx4 v[238:239], off
	v_lshl_add_u64 v[238:239], s[24:25], 0, v[130:131]
	s_mov_b32 m0, s64
	s_nop 0
	global_load_lds_dwordx4 v[238:239], off
	s_waitcnt vmcnt(8)
	s_waitcnt lgkmcnt(0)
	s_barrier
	v_mfma_f32_16x16x32_bf16 v[126:129], v[136:139], v[180:183], v[126:129]
	v_mfma_f32_16x16x32_bf16 v[126:129], v[146:149], v[184:187], v[126:129]
	v_mfma_f32_16x16x32_bf16 v[122:125], v[150:153], v[180:183], v[122:125]
	v_mfma_f32_16x16x32_bf16 v[122:125], v[154:157], v[184:187], v[122:125]
	v_mfma_f32_16x16x32_bf16 v[110:113], v[136:139], v[188:191], v[110:113]
	v_mfma_f32_16x16x32_bf16 v[110:113], v[146:149], v[192:195], v[110:113]
	v_mfma_f32_16x16x32_bf16 v[106:109], v[150:153], v[188:191], v[106:109]
	v_mfma_f32_16x16x32_bf16 v[106:109], v[154:157], v[192:195], v[106:109]
	v_mfma_f32_16x16x32_bf16 v[94:97], v[136:139], v[196:199], v[94:97]
	v_mfma_f32_16x16x32_bf16 v[94:97], v[146:149], v[200:203], v[94:97]
	v_mfma_f32_16x16x32_bf16 v[90:93], v[150:153], v[196:199], v[90:93]
	v_mfma_f32_16x16x32_bf16 v[90:93], v[154:157], v[200:203], v[90:93]
	v_mfma_f32_16x16x32_bf16 v[78:81], v[136:139], v[224:227], v[78:81]
	v_mfma_f32_16x16x32_bf16 v[78:81], v[146:149], v[228:231], v[78:81]
	v_mfma_f32_16x16x32_bf16 v[74:77], v[150:153], v[224:227], v[74:77]
	v_mfma_f32_16x16x32_bf16 v[74:77], v[154:157], v[228:231], v[74:77]
	v_mfma_f32_16x16x32_bf16 v[118:121], v[158:161], v[180:183], v[118:121]
	v_mfma_f32_16x16x32_bf16 v[118:121], v[168:171], v[184:187], v[118:121]
	v_mfma_f32_16x16x32_bf16 v[114:117], v[172:175], v[180:183], v[114:117]
	v_mfma_f32_16x16x32_bf16 v[114:117], v[176:179], v[184:187], v[114:117]
	v_mfma_f32_16x16x32_bf16 v[102:105], v[158:161], v[188:191], v[102:105]
	v_mfma_f32_16x16x32_bf16 v[102:105], v[168:171], v[192:195], v[102:105]
	v_mfma_f32_16x16x32_bf16 v[98:101], v[172:175], v[188:191], v[98:101]
	v_mfma_f32_16x16x32_bf16 v[98:101], v[176:179], v[192:195], v[98:101]
	v_mfma_f32_16x16x32_bf16 v[86:89], v[158:161], v[196:199], v[86:89]
	v_mfma_f32_16x16x32_bf16 v[86:89], v[168:171], v[200:203], v[86:89]
	v_mfma_f32_16x16x32_bf16 v[82:85], v[172:175], v[196:199], v[82:85]
	v_mfma_f32_16x16x32_bf16 v[82:85], v[176:179], v[200:203], v[82:85]
	v_mfma_f32_16x16x32_bf16 v[70:73], v[158:161], v[224:227], v[70:73]
	v_mfma_f32_16x16x32_bf16 v[70:73], v[168:171], v[228:231], v[70:73]
	v_mfma_f32_16x16x32_bf16 v[66:69], v[172:175], v[224:227], v[66:69]
	v_mfma_f32_16x16x32_bf16 v[66:69], v[176:179], v[228:231], v[66:69]
	s_barrier
; #define PG8_STAGE(bufoff, gbase, voff) do { _Pragma("unroll") for (int _i = 0; _i < 2; ++_i) \
;         __builtin_amdgcn_global_load_lds((const unsigned*)((const char*)(gbase) + (voff)[_i]), (PG8_LAS unsigned*)(lds + (bufoff) + ldsw + _i * 8192), 16, 0, 0); } while (0)
; #define PG8_LDA(dst, b, h) do { _Pragma("unroll") for (int m = 0; m < 4; ++m) _Pragma("unroll") for (int k = 0; k < 2; ++k) dst[m][k] = *(const PG8_LAS bf16x8*)(lds + PG8_SA(b, h) + aoff + m * 2048 + k * 1024); } while (0)
; #define PG8_MMA(ai, bj, At, Bt) do { __builtin_amdgcn_s_setprio(1); _Pragma("unroll") for (int m = 0; m < 4; ++m) _Pragma("unroll") for (int n = 0; n < 2; ++n) _Pragma("unroll") for (int k = 0; k < 2; ++k) \
;         acc[ai][bj][m][n] = __builtin_amdgcn_mfma_f32_16x16x32_bf16(Bt[n][k], At[m][k], acc[ai][bj][m][n], 0, 0, 0); __builtin_amdgcn_s_setprio(0); } while (0)
; #define PG8_WAIT_V(n) asm volatile("s_waitcnt vmcnt(" #n ")" ::: "memory")
; #define PG8_WAIT_L(n) asm volatile("s_waitcnt lgkmcnt(" #n ")" ::: "memory")
; #define PG8_BAR __builtin_amdgcn_s_barrier()
; #define PG8_SCHED __builtin_amdgcn_sched_barrier(0)
; template <class Epi, class Sched, bool ALIGN_EPI = false, bool SP2 = false>
; __device__ __forceinline__ void gemm_phase(PG8_LAS unsigned char* lds, const Gemm g, const Sched S, const Epi E) {
;     ...
;             PG8_LDA(At, 1, 1); PG8_STAGE(PG8_SB(1, 0), b3, voffB); PG8_STAGE(PG8_SB(1, 1), b3 + hstep, voffB); PG8_STAGE(PG8_SA(1, 0), a3, voffA);
;             PG8_WAIT_V(8); PG8_WAIT_L(0); PG8_BAR; PG8_MMA(1, 0, At, B0); PG8_MMA(1, 1, At, B1); PG8_BAR; PG8_SCHED;
;     ...
;         if constexpr (ALIGN_EPI) { if (wr == 0) PG8_BAR; }
	s_add_i32 s24, s26, s22
	v_lshl_add_u64 v[140:141], v[140:141], 0, s[28:29]
	s_mov_b32 m0, s24
	ds_read_b128 v[180:183], v145 offset:49152
	ds_read_b128 v[184:187], v145 offset:50176
	ds_read_b128 v[188:191], v145 offset:51200
	ds_read_b128 v[192:195], v145 offset:52224
	ds_read_b128 v[196:199], v145 offset:53248
	ds_read_b128 v[200:203], v145 offset:54272
	ds_read_b128 v[224:227], v145 offset:55296
	ds_read_b128 v[228:231], v145 offset:56320
	global_load_lds_dwordx4 v[140:141], off
	s_add_i32 m0, s24, 0x2000
	s_add_u32 s24, s56, 0x160080
	v_lshl_add_u64 v[140:141], v[232:233], 0, s[28:29]
	s_addc_u32 s25, s57, 0
	s_add_i32 s26, s27, s22
	global_load_lds_dwordx4 v[140:141], off
	v_lshl_add_u64 v[140:141], s[24:25], 0, v[0:1]
	s_mov_b32 m0, s26
	s_nop 0
	global_load_lds_dwordx4 v[140:141], off
	v_lshl_add_u64 v[140:141], s[24:25], 0, v[130:131]
	s_add_i32 m0, s26, 0x2000
	s_nop 0
	global_load_lds_dwordx4 v[140:141], off
	v_lshl_add_u64 v[140:141], v[234:235], 0, s[28:29]
	s_mov_b32 m0, s65
	s_nop 0
	global_load_lds_dwordx4 v[140:141], off
	v_lshl_add_u64 v[140:141], v[236:237], 0, s[28:29]
	s_mov_b32 m0, s66
	s_nop 0
	global_load_lds_dwordx4 v[140:141], off
	s_waitcnt vmcnt(8)
	s_waitcnt lgkmcnt(0)
	s_barrier
	v_mfma_f32_16x16x32_bf16 v[62:65], v[136:139], v[180:183], v[62:65]
	v_mfma_f32_16x16x32_bf16 v[62:65], v[146:149], v[184:187], v[62:65]
	v_mfma_f32_16x16x32_bf16 v[58:61], v[150:153], v[180:183], v[58:61]
	v_mfma_f32_16x16x32_bf16 v[58:61], v[154:157], v[184:187], v[58:61]
	v_mfma_f32_16x16x32_bf16 v[46:49], v[136:139], v[188:191], v[46:49]
	v_mfma_f32_16x16x32_bf16 v[46:49], v[146:149], v[192:195], v[46:49]
	v_mfma_f32_16x16x32_bf16 v[42:45], v[150:153], v[188:191], v[42:45]
	v_mfma_f32_16x16x32_bf16 v[42:45], v[154:157], v[192:195], v[42:45]
	v_mfma_f32_16x16x32_bf16 v[30:33], v[136:139], v[196:199], v[30:33]
	v_mfma_f32_16x16x32_bf16 v[30:33], v[146:149], v[200:203], v[30:33]
	v_mfma_f32_16x16x32_bf16 v[26:29], v[150:153], v[196:199], v[26:29]
	v_mfma_f32_16x16x32_bf16 v[26:29], v[154:157], v[200:203], v[26:29]
	v_mfma_f32_16x16x32_bf16 v[14:17], v[136:139], v[224:227], v[14:17]
	v_mfma_f32_16x16x32_bf16 v[14:17], v[146:149], v[228:231], v[14:17]
	v_mfma_f32_16x16x32_bf16 v[10:13], v[150:153], v[224:227], v[10:13]
	v_mfma_f32_16x16x32_bf16 v[10:13], v[154:157], v[228:231], v[10:13]
	v_mfma_f32_16x16x32_bf16 v[54:57], v[158:161], v[180:183], v[54:57]
	v_mfma_f32_16x16x32_bf16 v[54:57], v[168:171], v[184:187], v[54:57]
	v_mfma_f32_16x16x32_bf16 v[50:53], v[172:175], v[180:183], v[50:53]
	v_mfma_f32_16x16x32_bf16 v[50:53], v[176:179], v[184:187], v[50:53]
	v_mfma_f32_16x16x32_bf16 v[38:41], v[158:161], v[188:191], v[38:41]
	v_mfma_f32_16x16x32_bf16 v[38:41], v[168:171], v[192:195], v[38:41]
	v_mfma_f32_16x16x32_bf16 v[34:37], v[172:175], v[188:191], v[34:37]
	v_mfma_f32_16x16x32_bf16 v[34:37], v[176:179], v[192:195], v[34:37]
	v_mfma_f32_16x16x32_bf16 v[22:25], v[158:161], v[196:199], v[22:25]
	v_mfma_f32_16x16x32_bf16 v[22:25], v[168:171], v[200:203], v[22:25]
	v_mfma_f32_16x16x32_bf16 v[18:21], v[172:175], v[196:199], v[18:21]
	v_mfma_f32_16x16x32_bf16 v[18:21], v[176:179], v[200:203], v[18:21]
	v_mfma_f32_16x16x32_bf16 v[6:9], v[158:161], v[224:227], v[6:9]
	v_mfma_f32_16x16x32_bf16 v[6:9], v[168:171], v[228:231], v[6:9]
	v_mfma_f32_16x16x32_bf16 v[2:5], v[172:175], v[224:227], v[2:5]
	v_mfma_f32_16x16x32_bf16 v[2:5], v[176:179], v[228:231], v[2:5]
	s_barrier
	s_add_i32 s15, s15, 2
	s_add_u32 s5, s5, 0x100
	s_addc_u32 s14, s14, 0
	s_cmpk_gt_u32 s15, 0x55
	s_mov_b64 s[50:51], s[52:53]
	s_cbranch_scc0 .LBB0_272
	s_and_b64 vcc, exec, s[42:43]
	s_cbranch_vccz .LBB0_275
	s_barrier

; #define PG8_STAGE(bufoff, gbase, voff) do { _Pragma("unroll") for (int _i = 0; _i < 2; ++_i) \
;         __builtin_amdgcn_global_load_lds((const unsigned*)((const char*)(gbase) + (voff)[_i]), (PG8_LAS unsigned*)(lds + (bufoff) + ldsw + _i * 8192), 16, 0, 0); } while (0)
; #define PG8_LDA(dst, b, h) do { _Pragma("unroll") for (int m = 0; m < 4; ++m) _Pragma("unroll") for (int k = 0; k < 2; ++k) dst[m][k] = *(const PG8_LAS bf16x8*)(lds + PG8_SA(b, h) + aoff + m * 2048 + k * 1024); } while (0)
; #define PG8_LDB(dst, b, h) do { _Pragma("unroll") for (int n = 0; n < 2; ++n) _Pragma("unroll") for (int k = 0; k < 2; ++k) dst[n][k] = *(const PG8_LAS bf16x8*)(lds + PG8_SB(b, h) + boff + n * 2048 + k * 1024); } while (0)
; #define PG8_MMA(ai, bj, At, Bt) do { __builtin_amdgcn_s_setprio(1); _Pragma("unroll") for (int m = 0; m < 4; ++m) _Pragma("unroll") for (int n = 0; n < 2; ++n) _Pragma("unroll") for (int k = 0; k < 2; ++k) \
;         acc[ai][bj][m][n] = __builtin_amdgcn_mfma_f32_16x16x32_bf16(Bt[n][k], At[m][k], acc[ai][bj][m][n], 0, 0, 0); __builtin_amdgcn_s_setprio(0); } while (0)
; #define PG8_WAIT_V(n) asm volatile("s_waitcnt vmcnt(" #n ")" ::: "memory")
; #define PG8_BAR __builtin_amdgcn_s_barrier()
; template <class Epi, class Sched, bool ALIGN_EPI = false, bool SP2 = false>
; __device__ __forceinline__ void gemm_phase(PG8_LAS unsigned char* lds, const Gemm g, const Sched S, const Epi E) {
;     ...
;         for (int t = 0; t < nt; t += 2) {
;             const bool last = (t == nt - 2);
;             const char* a1 = cA + (size_t)(t + 1) * kstep;
;             const char* a2 = last ? nA : cA + (size_t)(t + 2) * kstep; const char* b2 = last ? nB : cB + (size_t)(t + 2) * kstep;
;             const char* a3 = a2 + kstep; const char* b3 = b2 + kstep;
;             if (last && has_next) S.a_ready(nxt);
;             if constexpr (SP2) {
;             PG8_LDB(B0, 0, 0); PG8_LDB(B1, 0, 1); PG8_SCHED; PG8_LDA(At, 0, 0); PG8_STAGE(PG8_SA(1, 1), a1 + hstep, voffA);
;             PG8_WAIT_V(8); PG8_WAIT_L(0); PG8_BAR; PG8_MMA(0, 0, At, B0); PG8_MMA(0, 1, At, B1); PG8_BAR; PG8_SCHED;
;             PG8_LDA(At, 0, 1); PG8_STAGE(PG8_SB(0, 0), b2, voffB); PG8_STAGE(PG8_SB(0, 1), b2 + hstep, voffB); PG8_STAGE(PG8_SA(0, 0), a2, voffA);
;             PG8_WAIT_V(8); PG8_WAIT_L(0); PG8_BAR; PG8_MMA(1, 0, At, B0); PG8_MMA(1, 1, At, B1); PG8_BAR; PG8_SCHED;
.LBB0_404:
	s_add_u32 s25, s0, 0xfff80080
	s_addc_u32 s26, s1, -1
	s_add_i32 s27, 0, 0x10000
	s_cmp_eq_u32 s24, 28
	s_cselect_b32 s67, s53, s26
	s_cselect_b32 s66, vcc_lo, s25
	v_add_u32_e32 v152, s27, v155
	s_cselect_b32 s65, s45, s15
	s_cselect_b32 s64, vcc_hi, s14
	s_add_i32 s25, 0, 0x14000
	ds_read_b128 v[130:133], v152
	ds_read_b128 v[134:137], v152 offset:1024
	ds_read_b128 v[148:151], v152 offset:2048
	ds_read_b128 v[174:177], v152 offset:3072
	v_add_u32_e32 v152, s25, v155
	ds_read_b128 v[178:181], v152
	ds_read_b128 v[182:185], v152 offset:1024
	ds_read_b128 v[186:189], v152 offset:2048
	ds_read_b128 v[190:193], v152 offset:3072
	v_lshl_add_u64 v[152:153], s[0:1], 0, v[144:145]
	s_add_i32 m0, s21, 0xc000
	ds_read_b128 v[194:197], v171
	ds_read_b128 v[198:201], v171 offset:1024
	ds_read_b128 v[224:227], v171 offset:2048
	ds_read_b128 v[228:231], v171 offset:3072
	ds_read_b128 v[232:235], v171 offset:4096
	ds_read_b128 v[236:239], v171 offset:5120
	ds_read_b128 v[240:243], v171 offset:6144
	ds_read_b128 v[244:247], v171 offset:7168
	global_load_lds_dwordx4 v[152:153], off
	v_lshl_add_u64 v[152:153], s[0:1], 0, v[146:147]
	s_add_i32 m0, s21, 0xe000
	s_nop 0
	global_load_lds_dwordx4 v[152:153], off
	s_waitcnt vmcnt(8)
	s_waitcnt lgkmcnt(0)
	s_barrier
	v_mfma_f32_16x16x32_bf16 v[126:129], v[130:133], v[194:197], v[126:129]
	v_mfma_f32_16x16x32_bf16 v[126:129], v[134:137], v[198:201], v[126:129]
	v_mfma_f32_16x16x32_bf16 v[122:125], v[148:151], v[194:197], v[122:125]
	v_mfma_f32_16x16x32_bf16 v[122:125], v[174:177], v[198:201], v[122:125]
	v_mfma_f32_16x16x32_bf16 v[118:121], v[130:133], v[224:227], v[118:121]
	v_mfma_f32_16x16x32_bf16 v[118:121], v[134:137], v[228:231], v[118:121]
	v_mfma_f32_16x16x32_bf16 v[110:113], v[148:151], v[224:227], v[110:113]
	v_mfma_f32_16x16x32_bf16 v[110:113], v[174:177], v[228:231], v[110:113]
	v_mfma_f32_16x16x32_bf16 v[102:105], v[130:133], v[232:235], v[102:105]
	v_mfma_f32_16x16x32_bf16 v[102:105], v[134:137], v[236:239], v[102:105]
	v_mfma_f32_16x16x32_bf16 v[94:97], v[148:151], v[232:235], v[94:97]
	v_mfma_f32_16x16x32_bf16 v[94:97], v[174:177], v[236:239], v[94:97]
	v_mfma_f32_16x16x32_bf16 v[86:89], v[130:133], v[240:243], v[86:89]
	v_mfma_f32_16x16x32_bf16 v[86:89], v[134:137], v[244:247], v[86:89]
	v_mfma_f32_16x16x32_bf16 v[78:81], v[148:151], v[240:243], v[78:81]
	v_mfma_f32_16x16x32_bf16 v[78:81], v[174:177], v[244:247], v[78:81]
	v_mfma_f32_16x16x32_bf16 v[114:117], v[178:181], v[194:197], v[114:117]
	v_mfma_f32_16x16x32_bf16 v[114:117], v[182:185], v[198:201], v[114:117]
	v_mfma_f32_16x16x32_bf16 v[106:109], v[186:189], v[194:197], v[106:109]
	v_mfma_f32_16x16x32_bf16 v[106:109], v[190:193], v[198:201], v[106:109]
	v_mfma_f32_16x16x32_bf16 v[98:101], v[178:181], v[224:227], v[98:101]
	v_mfma_f32_16x16x32_bf16 v[98:101], v[182:185], v[228:231], v[98:101]
	v_mfma_f32_16x16x32_bf16 v[90:93], v[186:189], v[224:227], v[90:93]
	v_mfma_f32_16x16x32_bf16 v[90:93], v[190:193], v[228:231], v[90:93]
	v_mfma_f32_16x16x32_bf16 v[82:85], v[178:181], v[232:235], v[82:85]
	v_mfma_f32_16x16x32_bf16 v[82:85], v[182:185], v[236:239], v[82:85]
	v_mfma_f32_16x16x32_bf16 v[74:77], v[186:189], v[232:235], v[74:77]
	v_mfma_f32_16x16x32_bf16 v[74:77], v[190:193], v[236:239], v[74:77]
	v_mfma_f32_16x16x32_bf16 v[70:73], v[178:181], v[240:243], v[70:73]
	v_mfma_f32_16x16x32_bf16 v[70:73], v[182:185], v[244:247], v[70:73]
	v_mfma_f32_16x16x32_bf16 v[66:69], v[186:189], v[240:243], v[66:69]
	v_mfma_f32_16x16x32_bf16 v[66:69], v[190:193], v[244:247], v[66:69]
	s_barrier
	s_add_i32 s26, s27, s16
	v_lshl_add_u64 v[152:153], s[64:65], 0, v[0:1]
	s_mov_b32 m0, s26
	ds_read_b128 v[194:197], v171 offset:16384
	ds_read_b128 v[198:201], v171 offset:17408
	ds_read_b128 v[224:227], v171 offset:18432
	ds_read_b128 v[228:231], v171 offset:19456
	ds_read_b128 v[232:235], v171 offset:20480
	ds_read_b128 v[236:239], v171 offset:21504
	ds_read_b128 v[240:243], v171 offset:22528
	ds_read_b128 v[244:247], v171 offset:23552
	global_load_lds_dwordx4 v[152:153], off
	s_add_i32 m0, s26, 0x2000
	s_add_u32 s26, s64, 0x80000
	v_lshl_add_u64 v[202:203], s[64:65], 0, v[138:139]
	s_addc_u32 s27, s65, 0
	s_add_i32 s25, s25, s16
	global_load_lds_dwordx4 v[202:203], off
	v_lshl_add_u64 v[248:249], s[26:27], 0, v[0:1]
	s_mov_b32 m0, s25
	v_lshl_add_u64 v[250:251], s[66:67], 0, v[140:141]
	global_load_lds_dwordx4 v[248:249], off
	v_lshl_add_u64 v[248:249], s[26:27], 0, v[138:139]
	s_add_i32 m0, s25, 0x2000
	s_nop 0
	global_load_lds_dwordx4 v[248:249], off
	v_lshl_add_u64 v[248:249], s[66:67], 0, v[142:143]
	s_mov_b32 m0, s21
	s_nop 0
	global_load_lds_dwordx4 v[248:249], off
	s_mov_b32 m0, s22
	s_nop 0
	global_load_lds_dwordx4 v[250:251], off
	s_waitcnt vmcnt(8)
	s_waitcnt lgkmcnt(0)
	s_barrier
; #define PG8_STAGE(bufoff, gbase, voff) do { _Pragma("unroll") for (int _i = 0; _i < 2; ++_i) \
;         __builtin_amdgcn_global_load_lds((const unsigned*)((const char*)(gbase) + (voff)[_i]), (PG8_LAS unsigned*)(lds + (bufoff) + ldsw + _i * 8192), 16, 0, 0); } while (0)
; #define PG8_LDA(dst, b, h) do { _Pragma("unroll") for (int m = 0; m < 4; ++m) _Pragma("unroll") for (int k = 0; k < 2; ++k) dst[m][k] = *(const PG8_LAS bf16x8*)(lds + PG8_SA(b, h) + aoff + m * 2048 + k * 1024); } while (0)
; #define PG8_LDB(dst, b, h) do { _Pragma("unroll") for (int n = 0; n < 2; ++n) _Pragma("unroll") for (int k = 0; k < 2; ++k) dst[n][k] = *(const PG8_LAS bf16x8*)(lds + PG8_SB(b, h) + boff + n * 2048 + k * 1024); } while (0)
; #define PG8_MMA(ai, bj, At, Bt) do { __builtin_amdgcn_s_setprio(1); _Pragma("unroll") for (int m = 0; m < 4; ++m) _Pragma("unroll") for (int n = 0; n < 2; ++n) _Pragma("unroll") for (int k = 0; k < 2; ++k) \
;         acc[ai][bj][m][n] = __builtin_amdgcn_mfma_f32_16x16x32_bf16(Bt[n][k], At[m][k], acc[ai][bj][m][n], 0, 0, 0); __builtin_amdgcn_s_setprio(0); } while (0)
; #define PG8_WAIT_V(n) asm volatile("s_waitcnt vmcnt(" #n ")" ::: "memory")
; #define PG8_WAIT_L(n) asm volatile("s_waitcnt lgkmcnt(" #n ")" ::: "memory")
; #define PG8_BAR __builtin_amdgcn_s_barrier()
; #define PG8_SCHED __builtin_amdgcn_sched_barrier(0)
; template <class Epi, class Sched, bool ALIGN_EPI = false, bool SP2 = false>
; __device__ __forceinline__ void gemm_phase(PG8_LAS unsigned char* lds, const Gemm g, const Sched S, const Epi E) {
;     ...
;             PG8_WAIT_V(8); PG8_WAIT_L(0); PG8_BAR; PG8_MMA(1, 0, At, B0); PG8_MMA(1, 1, At, B1); PG8_BAR; PG8_SCHED;
;             PG8_LDB(B0, 1, 0); PG8_LDB(B1, 1, 1); PG8_SCHED; PG8_LDA(At, 1, 0); PG8_STAGE(PG8_SA(0, 1), a2 + hstep, voffA);
;             PG8_WAIT_V(8); PG8_WAIT_L(0); PG8_BAR; PG8_MMA(0, 0, At, B0); PG8_MMA(0, 1, At, B1); PG8_BAR; PG8_SCHED;
	v_mfma_f32_16x16x32_bf16 v[62:65], v[130:133], v[194:197], v[62:65]
	v_mfma_f32_16x16x32_bf16 v[62:65], v[134:137], v[198:201], v[62:65]
	v_mfma_f32_16x16x32_bf16 v[58:61], v[148:151], v[194:197], v[58:61]
	v_mfma_f32_16x16x32_bf16 v[58:61], v[174:177], v[198:201], v[58:61]
	v_mfma_f32_16x16x32_bf16 v[54:57], v[130:133], v[224:227], v[54:57]
	v_mfma_f32_16x16x32_bf16 v[54:57], v[134:137], v[228:231], v[54:57]
	v_mfma_f32_16x16x32_bf16 v[46:49], v[148:151], v[224:227], v[46:49]
	v_mfma_f32_16x16x32_bf16 v[46:49], v[174:177], v[228:231], v[46:49]
	v_mfma_f32_16x16x32_bf16 v[38:41], v[130:133], v[232:235], v[38:41]
	v_mfma_f32_16x16x32_bf16 v[38:41], v[134:137], v[236:239], v[38:41]
	v_mfma_f32_16x16x32_bf16 v[30:33], v[148:151], v[232:235], v[30:33]
	v_mfma_f32_16x16x32_bf16 v[30:33], v[174:177], v[236:239], v[30:33]
	v_mfma_f32_16x16x32_bf16 v[22:25], v[130:133], v[240:243], v[22:25]
	v_mfma_f32_16x16x32_bf16 v[22:25], v[134:137], v[244:247], v[22:25]
	v_mfma_f32_16x16x32_bf16 v[14:17], v[148:151], v[240:243], v[14:17]
	v_mfma_f32_16x16x32_bf16 v[14:17], v[174:177], v[244:247], v[14:17]
	v_mfma_f32_16x16x32_bf16 v[50:53], v[178:181], v[194:197], v[50:53]
	v_mfma_f32_16x16x32_bf16 v[50:53], v[182:185], v[198:201], v[50:53]
	v_mfma_f32_16x16x32_bf16 v[42:45], v[186:189], v[194:197], v[42:45]
	v_mfma_f32_16x16x32_bf16 v[42:45], v[190:193], v[198:201], v[42:45]
	v_mfma_f32_16x16x32_bf16 v[34:37], v[178:181], v[224:227], v[34:37]
	v_mfma_f32_16x16x32_bf16 v[34:37], v[182:185], v[228:231], v[34:37]
	v_mfma_f32_16x16x32_bf16 v[26:29], v[186:189], v[224:227], v[26:29]
	v_mfma_f32_16x16x32_bf16 v[26:29], v[190:193], v[228:231], v[26:29]
	v_mfma_f32_16x16x32_bf16 v[18:21], v[178:181], v[232:235], v[18:21]
	v_mfma_f32_16x16x32_bf16 v[18:21], v[182:185], v[236:239], v[18:21]
	v_mfma_f32_16x16x32_bf16 v[10:13], v[186:189], v[232:235], v[10:13]
	v_mfma_f32_16x16x32_bf16 v[10:13], v[190:193], v[236:239], v[10:13]
	v_mfma_f32_16x16x32_bf16 v[6:9], v[178:181], v[240:243], v[6:9]
	v_mfma_f32_16x16x32_bf16 v[6:9], v[182:185], v[244:247], v[6:9]
	v_mfma_f32_16x16x32_bf16 v[2:5], v[186:189], v[240:243], v[2:5]
	v_mfma_f32_16x16x32_bf16 v[2:5], v[190:193], v[244:247], v[2:5]
	s_barrier
	s_add_i32 s25, 0, 0x18000
	v_add_u32_e32 v173, s25, v155
	s_add_i32 s30, 0, 0x1c000
	ds_read_b128 v[130:133], v173
	ds_read_b128 v[134:137], v173 offset:1024
	ds_read_b128 v[148:151], v173 offset:2048
	ds_read_b128 v[174:177], v173 offset:3072
	v_add_u32_e32 v173, s30, v155
	ds_read_b128 v[178:181], v173
	ds_read_b128 v[182:185], v173 offset:1024
	ds_read_b128 v[186:189], v173 offset:2048
	ds_read_b128 v[190:193], v173 offset:3072
	s_add_u32 s26, s66, 0x80000
	s_addc_u32 s27, s67, 0
	s_mov_b32 m0, s47
	v_lshl_add_u64 v[214:215], s[26:27], 0, v[142:143]
	ds_read_b128 v[194:197], v171 offset:32768
	ds_read_b128 v[198:201], v171 offset:33792
	ds_read_b128 v[224:227], v171 offset:34816
	ds_read_b128 v[228:231], v171 offset:35840
	ds_read_b128 v[232:235], v171 offset:36864
	ds_read_b128 v[236:239], v171 offset:37888
	ds_read_b128 v[240:243], v171 offset:38912
	ds_read_b128 v[244:247], v171 offset:39936
	global_load_lds_dwordx4 v[214:215], off
	v_lshl_add_u64 v[214:215], s[26:27], 0, v[140:141]
	s_mov_b32 m0, s62
	s_nop 0
	global_load_lds_dwordx4 v[214:215], off
	s_waitcnt vmcnt(8)
	s_waitcnt lgkmcnt(0)
	s_barrier
	v_mfma_f32_16x16x32_bf16 v[126:129], v[130:133], v[194:197], v[126:129]
	v_mfma_f32_16x16x32_bf16 v[126:129], v[134:137], v[198:201], v[126:129]
	v_mfma_f32_16x16x32_bf16 v[122:125], v[148:151], v[194:197], v[122:125]
	v_mfma_f32_16x16x32_bf16 v[122:125], v[174:177], v[198:201], v[122:125]
	v_mfma_f32_16x16x32_bf16 v[118:121], v[130:133], v[224:227], v[118:121]
	v_mfma_f32_16x16x32_bf16 v[118:121], v[134:137], v[228:231], v[118:121]
	v_mfma_f32_16x16x32_bf16 v[110:113], v[148:151], v[224:227], v[110:113]
	v_mfma_f32_16x16x32_bf16 v[110:113], v[174:177], v[228:231], v[110:113]
	v_mfma_f32_16x16x32_bf16 v[102:105], v[130:133], v[232:235], v[102:105]
	v_mfma_f32_16x16x32_bf16 v[102:105], v[134:137], v[236:239], v[102:105]
	v_mfma_f32_16x16x32_bf16 v[94:97], v[148:151], v[232:235], v[94:97]
	v_mfma_f32_16x16x32_bf16 v[94:97], v[174:177], v[236:239], v[94:97]
	v_mfma_f32_16x16x32_bf16 v[86:89], v[130:133], v[240:243], v[86:89]
	v_mfma_f32_16x16x32_bf16 v[86:89], v[134:137], v[244:247], v[86:89]
	v_mfma_f32_16x16x32_bf16 v[78:81], v[148:151], v[240:243], v[78:81]
	v_mfma_f32_16x16x32_bf16 v[78:81], v[174:177], v[244:247], v[78:81]
	v_mfma_f32_16x16x32_bf16 v[114:117], v[178:181], v[194:197], v[114:117]
	v_mfma_f32_16x16x32_bf16 v[114:117], v[182:185], v[198:201], v[114:117]
	v_mfma_f32_16x16x32_bf16 v[106:109], v[186:189], v[194:197], v[106:109]
	v_mfma_f32_16x16x32_bf16 v[106:109], v[190:193], v[198:201], v[106:109]
	v_mfma_f32_16x16x32_bf16 v[98:101], v[178:181], v[224:227], v[98:101]
	v_mfma_f32_16x16x32_bf16 v[98:101], v[182:185], v[228:231], v[98:101]
	v_mfma_f32_16x16x32_bf16 v[90:93], v[186:189], v[224:227], v[90:93]
	v_mfma_f32_16x16x32_bf16 v[90:93], v[190:193], v[228:231], v[90:93]
	v_mfma_f32_16x16x32_bf16 v[82:85], v[178:181], v[232:235], v[82:85]
	v_mfma_f32_16x16x32_bf16 v[82:85], v[182:185], v[236:239], v[82:85]
	v_mfma_f32_16x16x32_bf16 v[74:77], v[186:189], v[232:235], v[74:77]
	v_mfma_f32_16x16x32_bf16 v[74:77], v[190:193], v[236:239], v[74:77]
	v_mfma_f32_16x16x32_bf16 v[70:73], v[178:181], v[240:243], v[70:73]
	v_mfma_f32_16x16x32_bf16 v[70:73], v[182:185], v[244:247], v[70:73]
	v_mfma_f32_16x16x32_bf16 v[66:69], v[186:189], v[240:243], v[66:69]
	v_mfma_f32_16x16x32_bf16 v[66:69], v[190:193], v[244:247], v[66:69]
	s_barrier
; #define PG8_STAGE(bufoff, gbase, voff) do { _Pragma("unroll") for (int _i = 0; _i < 2; ++_i) \
;         __builtin_amdgcn_global_load_lds((const unsigned*)((const char*)(gbase) + (voff)[_i]), (PG8_LAS unsigned*)(lds + (bufoff) + ldsw + _i * 8192), 16, 0, 0); } while (0)
; #define PG8_LDA(dst, b, h) do { _Pragma("unroll") for (int m = 0; m < 4; ++m) _Pragma("unroll") for (int k = 0; k < 2; ++k) dst[m][k] = *(const PG8_LAS bf16x8*)(lds + PG8_SA(b, h) + aoff + m * 2048 + k * 1024); } while (0)
; #define PG8_MMA(ai, bj, At, Bt) do { __builtin_amdgcn_s_setprio(1); _Pragma("unroll") for (int m = 0; m < 4; ++m) _Pragma("unroll") for (int n = 0; n < 2; ++n) _Pragma("unroll") for (int k = 0; k < 2; ++k) \
;         acc[ai][bj][m][n] = __builtin_amdgcn_mfma_f32_16x16x32_bf16(Bt[n][k], At[m][k], acc[ai][bj][m][n], 0, 0, 0); __builtin_amdgcn_s_setprio(0); } while (0)
; #define PG8_WAIT_V(n) asm volatile("s_waitcnt vmcnt(" #n ")" ::: "memory")
; #define PG8_WAIT_L(n) asm volatile("s_waitcnt lgkmcnt(" #n ")" ::: "memory")
; #define PG8_BAR __builtin_amdgcn_s_barrier()
; #define PG8_SCHED __builtin_amdgcn_sched_barrier(0)
; template <class Epi, class Sched, bool ALIGN_EPI = false, bool SP2 = false>
; __device__ __forceinline__ void gemm_phase(PG8_LAS unsigned char* lds, const Gemm g, const Sched S, const Epi E) {
;     ...
;             PG8_LDA(At, 1, 1); PG8_STAGE(PG8_SB(1, 0), b3, voffB); PG8_STAGE(PG8_SB(1, 1), b3 + hstep, voffB); PG8_STAGE(PG8_SA(1, 0), a3, voffA);
;             PG8_WAIT_V(8); PG8_WAIT_L(0); PG8_BAR; PG8_MMA(1, 0, At, B0); PG8_MMA(1, 1, At, B1); PG8_BAR; PG8_SCHED;
;     ...
;         if constexpr (ALIGN_EPI) { if (wr == 0) PG8_BAR; }
	s_add_i32 s25, s25, s16
	v_lshl_add_u64 v[152:153], v[152:153], 0, s[28:29]
	s_mov_b32 m0, s25
	ds_read_b128 v[194:197], v171 offset:49152
	ds_read_b128 v[198:201], v171 offset:50176
	ds_read_b128 v[224:227], v171 offset:51200
	ds_read_b128 v[228:231], v171 offset:52224
	ds_read_b128 v[232:235], v171 offset:53248
	ds_read_b128 v[236:239], v171 offset:54272
	ds_read_b128 v[240:243], v171 offset:55296
	ds_read_b128 v[244:247], v171 offset:56320
	global_load_lds_dwordx4 v[152:153], off
	s_add_i32 m0, s25, 0x2000
	s_add_u32 s26, s64, 0x80080
	v_lshl_add_u64 v[152:153], v[202:203], 0, s[28:29]
	s_addc_u32 s27, s65, 0
	s_add_i32 s25, s30, s16
	global_load_lds_dwordx4 v[152:153], off
	v_lshl_add_u64 v[152:153], s[26:27], 0, v[0:1]
	s_mov_b32 m0, s25
	s_nop 0
	global_load_lds_dwordx4 v[152:153], off
	v_lshl_add_u64 v[152:153], s[26:27], 0, v[138:139]
	s_add_i32 m0, s25, 0x2000
	s_nop 0
	global_load_lds_dwordx4 v[152:153], off
	v_lshl_add_u64 v[152:153], v[248:249], 0, s[28:29]
	s_mov_b32 m0, s63
	s_nop 0
	global_load_lds_dwordx4 v[152:153], off
	v_lshl_add_u64 v[152:153], v[250:251], 0, s[28:29]
	s_mov_b32 m0, s74
	s_nop 0
	global_load_lds_dwordx4 v[152:153], off
	s_waitcnt vmcnt(8)
	s_waitcnt lgkmcnt(0)
	s_barrier
	v_mfma_f32_16x16x32_bf16 v[62:65], v[130:133], v[194:197], v[62:65]
	v_mfma_f32_16x16x32_bf16 v[62:65], v[134:137], v[198:201], v[62:65]
	v_mfma_f32_16x16x32_bf16 v[58:61], v[148:151], v[194:197], v[58:61]
	v_mfma_f32_16x16x32_bf16 v[58:61], v[174:177], v[198:201], v[58:61]
	v_mfma_f32_16x16x32_bf16 v[54:57], v[130:133], v[224:227], v[54:57]
	v_mfma_f32_16x16x32_bf16 v[54:57], v[134:137], v[228:231], v[54:57]
	v_mfma_f32_16x16x32_bf16 v[46:49], v[148:151], v[224:227], v[46:49]
	v_mfma_f32_16x16x32_bf16 v[46:49], v[174:177], v[228:231], v[46:49]
	v_mfma_f32_16x16x32_bf16 v[38:41], v[130:133], v[232:235], v[38:41]
	v_mfma_f32_16x16x32_bf16 v[38:41], v[134:137], v[236:239], v[38:41]
	v_mfma_f32_16x16x32_bf16 v[30:33], v[148:151], v[232:235], v[30:33]
	v_mfma_f32_16x16x32_bf16 v[30:33], v[174:177], v[236:239], v[30:33]
	v_mfma_f32_16x16x32_bf16 v[22:25], v[130:133], v[240:243], v[22:25]
	v_mfma_f32_16x16x32_bf16 v[22:25], v[134:137], v[244:247], v[22:25]
	v_mfma_f32_16x16x32_bf16 v[14:17], v[148:151], v[240:243], v[14:17]
	v_mfma_f32_16x16x32_bf16 v[14:17], v[174:177], v[244:247], v[14:17]
	v_mfma_f32_16x16x32_bf16 v[50:53], v[178:181], v[194:197], v[50:53]
	v_mfma_f32_16x16x32_bf16 v[50:53], v[182:185], v[198:201], v[50:53]
	v_mfma_f32_16x16x32_bf16 v[42:45], v[186:189], v[194:197], v[42:45]
	v_mfma_f32_16x16x32_bf16 v[42:45], v[190:193], v[198:201], v[42:45]
	v_mfma_f32_16x16x32_bf16 v[34:37], v[178:181], v[224:227], v[34:37]
	v_mfma_f32_16x16x32_bf16 v[34:37], v[182:185], v[228:231], v[34:37]
	v_mfma_f32_16x16x32_bf16 v[26:29], v[186:189], v[224:227], v[26:29]
	v_mfma_f32_16x16x32_bf16 v[26:29], v[190:193], v[228:231], v[26:29]
	v_mfma_f32_16x16x32_bf16 v[18:21], v[178:181], v[232:235], v[18:21]
	v_mfma_f32_16x16x32_bf16 v[18:21], v[182:185], v[236:239], v[18:21]
	v_mfma_f32_16x16x32_bf16 v[10:13], v[186:189], v[232:235], v[10:13]
	v_mfma_f32_16x16x32_bf16 v[10:13], v[190:193], v[236:239], v[10:13]
	v_mfma_f32_16x16x32_bf16 v[6:9], v[178:181], v[240:243], v[6:9]
	v_mfma_f32_16x16x32_bf16 v[6:9], v[182:185], v[244:247], v[6:9]
	v_mfma_f32_16x16x32_bf16 v[2:5], v[186:189], v[240:243], v[2:5]
	v_mfma_f32_16x16x32_bf16 v[2:5], v[190:193], v[244:247], v[2:5]
	s_barrier
	s_add_i32 s24, s24, 2
	s_add_u32 s0, s0, 0x100
	s_addc_u32 s1, s1, 0
	s_add_u32 s14, s14, 0x100
	s_addc_u32 s15, s15, 0
	s_cmp_gt_u32 s24, 29
	s_cbranch_scc0 .LBB0_404
	s_and_b64 vcc, exec, s[8:9]
	s_cbranch_vccz .LBB0_407
	s_barrier

; #define PG8_STAGE(bufoff, gbase, voff) do { _Pragma("unroll") for (int _i = 0; _i < 2; ++_i) \
;         __builtin_amdgcn_global_load_lds((const unsigned*)((const char*)(gbase) + (voff)[_i]), (PG8_LAS unsigned*)(lds + (bufoff) + ldsw + _i * 8192), 16, 0, 0); } while (0)
; #define PG8_LDA(dst, b, h) do { _Pragma("unroll") for (int m = 0; m < 4; ++m) _Pragma("unroll") for (int k = 0; k < 2; ++k) dst[m][k] = *(const PG8_LAS bf16x8*)(lds + PG8_SA(b, h) + aoff + m * 2048 + k * 1024); } while (0)
; #define PG8_LDB(dst, b, h) do { _Pragma("unroll") for (int n = 0; n < 2; ++n) _Pragma("unroll") for (int k = 0; k < 2; ++k) dst[n][k] = *(const PG8_LAS bf16x8*)(lds + PG8_SB(b, h) + boff + n * 2048 + k * 1024); } while (0)
; #define PG8_MMA(ai, bj, At, Bt) do { __builtin_amdgcn_s_setprio(1); _Pragma("unroll") for (int m = 0; m < 4; ++m) _Pragma("unroll") for (int n = 0; n < 2; ++n) _Pragma("unroll") for (int k = 0; k < 2; ++k) \
;         acc[ai][bj][m][n] = __builtin_amdgcn_mfma_f32_16x16x32_bf16(Bt[n][k], At[m][k], acc[ai][bj][m][n], 0, 0, 0); __builtin_amdgcn_s_setprio(0); } while (0)
; #define PG8_WAIT_V(n) asm volatile("s_waitcnt vmcnt(" #n ")" ::: "memory")
; #define PG8_BAR __builtin_amdgcn_s_barrier()
; template <class Epi, class Sched, bool ALIGN_EPI = false, bool SP2 = false>
; __device__ __forceinline__ void gemm_phase(PG8_LAS unsigned char* lds, const Gemm g, const Sched S, const Epi E) {
;     ...
;         for (int t = 0; t < nt; t += 2) {
;             const bool last = (t == nt - 2);
;             const char* a1 = cA + (size_t)(t + 1) * kstep;
;             const char* a2 = last ? nA : cA + (size_t)(t + 2) * kstep; const char* b2 = last ? nB : cB + (size_t)(t + 2) * kstep;
;             const char* a3 = a2 + kstep; const char* b3 = b2 + kstep;
;             if (last && has_next) S.a_ready(nxt);
;             if constexpr (SP2) {
;             PG8_LDB(B0, 0, 0); PG8_LDB(B1, 0, 1); PG8_SCHED; PG8_LDA(At, 0, 0); PG8_STAGE(PG8_SA(1, 1), a1 + hstep, voffA);
;             PG8_WAIT_V(8); PG8_WAIT_L(0); PG8_BAR; PG8_MMA(0, 0, At, B0); PG8_MMA(0, 1, At, B1); PG8_BAR; PG8_SCHED;
;             PG8_LDA(At, 0, 1); PG8_STAGE(PG8_SB(0, 0), b2, voffB); PG8_STAGE(PG8_SB(0, 1), b2 + hstep, voffB); PG8_STAGE(PG8_SA(0, 0), a2, voffA);
;             PG8_WAIT_V(8); PG8_WAIT_L(0); PG8_BAR; PG8_MMA(1, 0, At, B0); PG8_MMA(1, 1, At, B1); PG8_BAR; PG8_SCHED;
.LBB0_654:
	s_add_u32 s64, s58, 0x100
	s_addc_u32 s65, s59, 0
	s_add_i32 s25, 0, 0x10000
	s_cmp_eq_u32 s24, 12
	s_cselect_b32 vcc_hi, s45, s65
	s_cselect_b32 vcc_lo, s77, s64
	v_add_u32_e32 v140, s25, v143
	s_cselect_b32 s67, s43, s15
	s_cselect_b32 s66, s36, s14
	s_add_i32 s30, 0, 0x14000
	ds_read_b128 v[136:139], v140
	ds_read_b128 v[146:149], v140 offset:1024
	ds_read_b128 v[150:153], v140 offset:2048
	ds_read_b128 v[154:157], v140 offset:3072
	v_add_u32_e32 v140, s30, v143
	ds_read_b128 v[158:161], v140
	ds_read_b128 v[168:171], v140 offset:1024
	ds_read_b128 v[172:175], v140 offset:2048
	ds_read_b128 v[176:179], v140 offset:3072
	v_lshl_add_u64 v[140:141], s[58:59], 0, v[132:133]
	s_add_i32 m0, s21, 0xc000
	ds_read_b128 v[180:183], v145
	ds_read_b128 v[184:187], v145 offset:1024
	ds_read_b128 v[188:191], v145 offset:2048
	ds_read_b128 v[192:195], v145 offset:3072
	ds_read_b128 v[196:199], v145 offset:4096
	ds_read_b128 v[200:203], v145 offset:5120
	ds_read_b128 v[224:227], v145 offset:6144
	ds_read_b128 v[228:231], v145 offset:7168
	global_load_lds_dwordx4 v[140:141], off
	v_lshl_add_u64 v[140:141], s[58:59], 0, v[134:135]
	s_add_i32 m0, s21, 0xe000
	s_nop 0
	global_load_lds_dwordx4 v[140:141], off
	s_waitcnt vmcnt(8)
	s_waitcnt lgkmcnt(0)
	s_barrier
	v_mfma_f32_16x16x32_bf16 v[126:129], v[136:139], v[180:183], v[126:129]
	v_mfma_f32_16x16x32_bf16 v[126:129], v[146:149], v[184:187], v[126:129]
	v_mfma_f32_16x16x32_bf16 v[122:125], v[150:153], v[180:183], v[122:125]
	v_mfma_f32_16x16x32_bf16 v[122:125], v[154:157], v[184:187], v[122:125]
	v_mfma_f32_16x16x32_bf16 v[110:113], v[136:139], v[188:191], v[110:113]
	v_mfma_f32_16x16x32_bf16 v[110:113], v[146:149], v[192:195], v[110:113]
	v_mfma_f32_16x16x32_bf16 v[106:109], v[150:153], v[188:191], v[106:109]
	v_mfma_f32_16x16x32_bf16 v[106:109], v[154:157], v[192:195], v[106:109]
	v_mfma_f32_16x16x32_bf16 v[94:97], v[136:139], v[196:199], v[94:97]
	v_mfma_f32_16x16x32_bf16 v[94:97], v[146:149], v[200:203], v[94:97]
	v_mfma_f32_16x16x32_bf16 v[90:93], v[150:153], v[196:199], v[90:93]
	v_mfma_f32_16x16x32_bf16 v[90:93], v[154:157], v[200:203], v[90:93]
	v_mfma_f32_16x16x32_bf16 v[78:81], v[136:139], v[224:227], v[78:81]
	v_mfma_f32_16x16x32_bf16 v[78:81], v[146:149], v[228:231], v[78:81]
	v_mfma_f32_16x16x32_bf16 v[74:77], v[150:153], v[224:227], v[74:77]
	v_mfma_f32_16x16x32_bf16 v[74:77], v[154:157], v[228:231], v[74:77]
	v_mfma_f32_16x16x32_bf16 v[118:121], v[158:161], v[180:183], v[118:121]
	v_mfma_f32_16x16x32_bf16 v[118:121], v[168:171], v[184:187], v[118:121]
	v_mfma_f32_16x16x32_bf16 v[114:117], v[172:175], v[180:183], v[114:117]
	v_mfma_f32_16x16x32_bf16 v[114:117], v[176:179], v[184:187], v[114:117]
	v_mfma_f32_16x16x32_bf16 v[102:105], v[158:161], v[188:191], v[102:105]
	v_mfma_f32_16x16x32_bf16 v[102:105], v[168:171], v[192:195], v[102:105]
	v_mfma_f32_16x16x32_bf16 v[98:101], v[172:175], v[188:191], v[98:101]
	v_mfma_f32_16x16x32_bf16 v[98:101], v[176:179], v[192:195], v[98:101]
	v_mfma_f32_16x16x32_bf16 v[86:89], v[158:161], v[196:199], v[86:89]
	v_mfma_f32_16x16x32_bf16 v[86:89], v[168:171], v[200:203], v[86:89]
	v_mfma_f32_16x16x32_bf16 v[82:85], v[172:175], v[196:199], v[82:85]
	v_mfma_f32_16x16x32_bf16 v[82:85], v[176:179], v[200:203], v[82:85]
	v_mfma_f32_16x16x32_bf16 v[70:73], v[158:161], v[224:227], v[70:73]
	v_mfma_f32_16x16x32_bf16 v[70:73], v[168:171], v[228:231], v[70:73]
	v_mfma_f32_16x16x32_bf16 v[66:69], v[172:175], v[224:227], v[66:69]
	v_mfma_f32_16x16x32_bf16 v[66:69], v[176:179], v[228:231], v[66:69]
	s_barrier
	s_add_i32 s25, s25, s16
	v_lshl_add_u64 v[140:141], s[66:67], 0, v[0:1]
	s_mov_b32 m0, s25
	ds_read_b128 v[180:183], v145 offset:16384
	ds_read_b128 v[184:187], v145 offset:17408
	ds_read_b128 v[188:191], v145 offset:18432
	ds_read_b128 v[192:195], v145 offset:19456
	ds_read_b128 v[196:199], v145 offset:20480
	ds_read_b128 v[200:203], v145 offset:21504
	ds_read_b128 v[224:227], v145 offset:22528
	ds_read_b128 v[228:231], v145 offset:23552
	global_load_lds_dwordx4 v[140:141], off
	s_add_i32 m0, s25, 0x2000
	s_add_u32 s26, s66, 0x40000
	v_lshl_add_u64 v[214:215], s[66:67], 0, v[130:131]
	s_addc_u32 s27, s67, 0
	s_add_i32 s25, s30, s16
	global_load_lds_dwordx4 v[214:215], off
	v_lshl_add_u64 v[232:233], s[26:27], 0, v[0:1]
	s_mov_b32 m0, s25
	v_lshl_add_u64 v[234:235], vcc, 0, v[130:131]
	global_load_lds_dwordx4 v[232:233], off
	v_lshl_add_u64 v[232:233], s[26:27], 0, v[130:131]
	s_add_i32 m0, s25, 0x2000
	s_nop 0
	global_load_lds_dwordx4 v[232:233], off
	v_lshl_add_u64 v[232:233], vcc, 0, v[0:1]
	s_mov_b32 m0, s21
	s_nop 0
	global_load_lds_dwordx4 v[232:233], off
	s_mov_b32 m0, s22
	s_nop 0
	global_load_lds_dwordx4 v[234:235], off
	s_waitcnt vmcnt(8)
	s_waitcnt lgkmcnt(0)
	s_barrier
; #define PG8_STAGE(bufoff, gbase, voff) do { _Pragma("unroll") for (int _i = 0; _i < 2; ++_i) \
;         __builtin_amdgcn_global_load_lds((const unsigned*)((const char*)(gbase) + (voff)[_i]), (PG8_LAS unsigned*)(lds + (bufoff) + ldsw + _i * 8192), 16, 0, 0); } while (0)
; #define PG8_LDA(dst, b, h) do { _Pragma("unroll") for (int m = 0; m < 4; ++m) _Pragma("unroll") for (int k = 0; k < 2; ++k) dst[m][k] = *(const PG8_LAS bf16x8*)(lds + PG8_SA(b, h) + aoff + m * 2048 + k * 1024); } while (0)
; #define PG8_LDB(dst, b, h) do { _Pragma("unroll") for (int n = 0; n < 2; ++n) _Pragma("unroll") for (int k = 0; k < 2; ++k) dst[n][k] = *(const PG8_LAS bf16x8*)(lds + PG8_SB(b, h) + boff + n * 2048 + k * 1024); } while (0)
; #define PG8_MMA(ai, bj, At, Bt) do { __builtin_amdgcn_s_setprio(1); _Pragma("unroll") for (int m = 0; m < 4; ++m) _Pragma("unroll") for (int n = 0; n < 2; ++n) _Pragma("unroll") for (int k = 0; k < 2; ++k) \
;         acc[ai][bj][m][n] = __builtin_amdgcn_mfma_f32_16x16x32_bf16(Bt[n][k], At[m][k], acc[ai][bj][m][n], 0, 0, 0); __builtin_amdgcn_s_setprio(0); } while (0)
; #define PG8_WAIT_V(n) asm volatile("s_waitcnt vmcnt(" #n ")" ::: "memory")
; #define PG8_WAIT_L(n) asm volatile("s_waitcnt lgkmcnt(" #n ")" ::: "memory")
; #define PG8_BAR __builtin_amdgcn_s_barrier()
; #define PG8_SCHED __builtin_amdgcn_sched_barrier(0)
; template <class Epi, class Sched, bool ALIGN_EPI = false, bool SP2 = false>
; __device__ __forceinline__ void gemm_phase(PG8_LAS unsigned char* lds, const Gemm g, const Sched S, const Epi E) {
;     ...
;             PG8_WAIT_V(8); PG8_WAIT_L(0); PG8_BAR; PG8_MMA(1, 0, At, B0); PG8_MMA(1, 1, At, B1); PG8_BAR; PG8_SCHED;
;             PG8_LDB(B0, 1, 0); PG8_LDB(B1, 1, 1); PG8_SCHED; PG8_LDA(At, 1, 0); PG8_STAGE(PG8_SA(0, 1), a2 + hstep, voffA);
;             PG8_WAIT_V(8); PG8_WAIT_L(0); PG8_BAR; PG8_MMA(0, 0, At, B0); PG8_MMA(0, 1, At, B1); PG8_BAR; PG8_SCHED;
	v_mfma_f32_16x16x32_bf16 v[62:65], v[136:139], v[180:183], v[62:65]
	v_mfma_f32_16x16x32_bf16 v[62:65], v[146:149], v[184:187], v[62:65]
	v_mfma_f32_16x16x32_bf16 v[58:61], v[150:153], v[180:183], v[58:61]
	v_mfma_f32_16x16x32_bf16 v[58:61], v[154:157], v[184:187], v[58:61]
	v_mfma_f32_16x16x32_bf16 v[46:49], v[136:139], v[188:191], v[46:49]
	v_mfma_f32_16x16x32_bf16 v[46:49], v[146:149], v[192:195], v[46:49]
	v_mfma_f32_16x16x32_bf16 v[42:45], v[150:153], v[188:191], v[42:45]
	v_mfma_f32_16x16x32_bf16 v[42:45], v[154:157], v[192:195], v[42:45]
	v_mfma_f32_16x16x32_bf16 v[30:33], v[136:139], v[196:199], v[30:33]
	v_mfma_f32_16x16x32_bf16 v[30:33], v[146:149], v[200:203], v[30:33]
	v_mfma_f32_16x16x32_bf16 v[26:29], v[150:153], v[196:199], v[26:29]
	v_mfma_f32_16x16x32_bf16 v[26:29], v[154:157], v[200:203], v[26:29]
	v_mfma_f32_16x16x32_bf16 v[14:17], v[136:139], v[224:227], v[14:17]
	v_mfma_f32_16x16x32_bf16 v[14:17], v[146:149], v[228:231], v[14:17]
	v_mfma_f32_16x16x32_bf16 v[10:13], v[150:153], v[224:227], v[10:13]
	v_mfma_f32_16x16x32_bf16 v[10:13], v[154:157], v[228:231], v[10:13]
	v_mfma_f32_16x16x32_bf16 v[54:57], v[158:161], v[180:183], v[54:57]
	v_mfma_f32_16x16x32_bf16 v[54:57], v[168:171], v[184:187], v[54:57]
	v_mfma_f32_16x16x32_bf16 v[50:53], v[172:175], v[180:183], v[50:53]
	v_mfma_f32_16x16x32_bf16 v[50:53], v[176:179], v[184:187], v[50:53]
	v_mfma_f32_16x16x32_bf16 v[38:41], v[158:161], v[188:191], v[38:41]
	v_mfma_f32_16x16x32_bf16 v[38:41], v[168:171], v[192:195], v[38:41]
	v_mfma_f32_16x16x32_bf16 v[34:37], v[172:175], v[188:191], v[34:37]
	v_mfma_f32_16x16x32_bf16 v[34:37], v[176:179], v[192:195], v[34:37]
	v_mfma_f32_16x16x32_bf16 v[22:25], v[158:161], v[196:199], v[22:25]
	v_mfma_f32_16x16x32_bf16 v[22:25], v[168:171], v[200:203], v[22:25]
	v_mfma_f32_16x16x32_bf16 v[18:21], v[172:175], v[196:199], v[18:21]
	v_mfma_f32_16x16x32_bf16 v[18:21], v[176:179], v[200:203], v[18:21]
	v_mfma_f32_16x16x32_bf16 v[6:9], v[158:161], v[224:227], v[6:9]
	v_mfma_f32_16x16x32_bf16 v[6:9], v[168:171], v[228:231], v[6:9]
	v_mfma_f32_16x16x32_bf16 v[2:5], v[172:175], v[224:227], v[2:5]
	v_mfma_f32_16x16x32_bf16 v[2:5], v[176:179], v[228:231], v[2:5]
	s_barrier
	s_add_i32 s25, 0, 0x18000
	s_add_i32 s30, 0, 0x1c000
	v_add_u32_e32 v154, s25, v143
	v_add_u32_e32 v167, s30, v143
	ds_read_b128 v[136:139], v154
	ds_read_b128 v[146:149], v154 offset:1024
	ds_read_b128 v[150:153], v154 offset:2048
	ds_read_b128 v[154:157], v154 offset:3072
	ds_read_b128 v[158:161], v167
	ds_read_b128 v[168:171], v167 offset:1024
	ds_read_b128 v[172:175], v167 offset:2048
	ds_read_b128 v[176:179], v167 offset:3072
	s_add_u32 s26, vcc_lo, 0x40000
	s_addc_u32 s27, vcc_hi, 0
	s_mov_b32 m0, s47
	v_lshl_add_u64 v[236:237], s[26:27], 0, v[0:1]
	ds_read_b128 v[180:183], v145 offset:32768
	ds_read_b128 v[184:187], v145 offset:33792
	ds_read_b128 v[188:191], v145 offset:34816
	ds_read_b128 v[192:195], v145 offset:35840
	ds_read_b128 v[196:199], v145 offset:36864
	ds_read_b128 v[200:203], v145 offset:37888
	ds_read_b128 v[224:227], v145 offset:38912
	ds_read_b128 v[228:231], v145 offset:39936
	global_load_lds_dwordx4 v[236:237], off
	v_lshl_add_u64 v[236:237], s[26:27], 0, v[130:131]
	s_mov_b32 m0, s62
	s_nop 0
	global_load_lds_dwordx4 v[236:237], off
	s_waitcnt vmcnt(8)
	s_waitcnt lgkmcnt(0)
	s_barrier
	v_mfma_f32_16x16x32_bf16 v[126:129], v[136:139], v[180:183], v[126:129]
	v_mfma_f32_16x16x32_bf16 v[126:129], v[146:149], v[184:187], v[126:129]
	v_mfma_f32_16x16x32_bf16 v[122:125], v[150:153], v[180:183], v[122:125]
	v_mfma_f32_16x16x32_bf16 v[122:125], v[154:157], v[184:187], v[122:125]
	v_mfma_f32_16x16x32_bf16 v[110:113], v[136:139], v[188:191], v[110:113]
	v_mfma_f32_16x16x32_bf16 v[110:113], v[146:149], v[192:195], v[110:113]
	v_mfma_f32_16x16x32_bf16 v[106:109], v[150:153], v[188:191], v[106:109]
	v_mfma_f32_16x16x32_bf16 v[106:109], v[154:157], v[192:195], v[106:109]
	v_mfma_f32_16x16x32_bf16 v[94:97], v[136:139], v[196:199], v[94:97]
	v_mfma_f32_16x16x32_bf16 v[94:97], v[146:149], v[200:203], v[94:97]
	v_mfma_f32_16x16x32_bf16 v[90:93], v[150:153], v[196:199], v[90:93]
	v_mfma_f32_16x16x32_bf16 v[90:93], v[154:157], v[200:203], v[90:93]
	v_mfma_f32_16x16x32_bf16 v[78:81], v[136:139], v[224:227], v[78:81]
	v_mfma_f32_16x16x32_bf16 v[78:81], v[146:149], v[228:231], v[78:81]
	v_mfma_f32_16x16x32_bf16 v[74:77], v[150:153], v[224:227], v[74:77]
	v_mfma_f32_16x16x32_bf16 v[74:77], v[154:157], v[228:231], v[74:77]
	v_mfma_f32_16x16x32_bf16 v[118:121], v[158:161], v[180:183], v[118:121]
	v_mfma_f32_16x16x32_bf16 v[118:121], v[168:171], v[184:187], v[118:121]
	v_mfma_f32_16x16x32_bf16 v[114:117], v[172:175], v[180:183], v[114:117]
	v_mfma_f32_16x16x32_bf16 v[114:117], v[176:179], v[184:187], v[114:117]
	v_mfma_f32_16x16x32_bf16 v[102:105], v[158:161], v[188:191], v[102:105]
	v_mfma_f32_16x16x32_bf16 v[102:105], v[168:171], v[192:195], v[102:105]
	v_mfma_f32_16x16x32_bf16 v[98:101], v[172:175], v[188:191], v[98:101]
	v_mfma_f32_16x16x32_bf16 v[98:101], v[176:179], v[192:195], v[98:101]
	v_mfma_f32_16x16x32_bf16 v[86:89], v[158:161], v[196:199], v[86:89]
	v_mfma_f32_16x16x32_bf16 v[86:89], v[168:171], v[200:203], v[86:89]
	v_mfma_f32_16x16x32_bf16 v[82:85], v[172:175], v[196:199], v[82:85]
	v_mfma_f32_16x16x32_bf16 v[82:85], v[176:179], v[200:203], v[82:85]
	v_mfma_f32_16x16x32_bf16 v[70:73], v[158:161], v[224:227], v[70:73]
	v_mfma_f32_16x16x32_bf16 v[70:73], v[168:171], v[228:231], v[70:73]
	v_mfma_f32_16x16x32_bf16 v[66:69], v[172:175], v[224:227], v[66:69]
	v_mfma_f32_16x16x32_bf16 v[66:69], v[176:179], v[228:231], v[66:69]
	s_barrier
; #define PG8_STAGE(bufoff, gbase, voff) do { _Pragma("unroll") for (int _i = 0; _i < 2; ++_i) \
;         __builtin_amdgcn_global_load_lds((const unsigned*)((const char*)(gbase) + (voff)[_i]), (PG8_LAS unsigned*)(lds + (bufoff) + ldsw + _i * 8192), 16, 0, 0); } while (0)
; #define PG8_LDA(dst, b, h) do { _Pragma("unroll") for (int m = 0; m < 4; ++m) _Pragma("unroll") for (int k = 0; k < 2; ++k) dst[m][k] = *(const PG8_LAS bf16x8*)(lds + PG8_SA(b, h) + aoff + m * 2048 + k * 1024); } while (0)
; #define PG8_MMA(ai, bj, At, Bt) do { __builtin_amdgcn_s_setprio(1); _Pragma("unroll") for (int m = 0; m < 4; ++m) _Pragma("unroll") for (int n = 0; n < 2; ++n) _Pragma("unroll") for (int k = 0; k < 2; ++k) \
;         acc[ai][bj][m][n] = __builtin_amdgcn_mfma_f32_16x16x32_bf16(Bt[n][k], At[m][k], acc[ai][bj][m][n], 0, 0, 0); __builtin_amdgcn_s_setprio(0); } while (0)
; #define PG8_WAIT_V(n) asm volatile("s_waitcnt vmcnt(" #n ")" ::: "memory")
; #define PG8_WAIT_L(n) asm volatile("s_waitcnt lgkmcnt(" #n ")" ::: "memory")
; #define PG8_BAR __builtin_amdgcn_s_barrier()
; #define PG8_SCHED __builtin_amdgcn_sched_barrier(0)
; template <class Epi, class Sched, bool ALIGN_EPI = false, bool SP2 = false>
; __device__ __forceinline__ void gemm_phase(PG8_LAS unsigned char* lds, const Gemm g, const Sched S, const Epi E) {
;     ...
;             PG8_LDA(At, 1, 1); PG8_STAGE(PG8_SB(1, 0), b3, voffB); PG8_STAGE(PG8_SB(1, 1), b3 + hstep, voffB); PG8_STAGE(PG8_SA(1, 0), a3, voffA);
;             PG8_WAIT_V(8); PG8_WAIT_L(0); PG8_BAR; PG8_MMA(1, 0, At, B0); PG8_MMA(1, 1, At, B1); PG8_BAR; PG8_SCHED;
;     ...
;         if constexpr (ALIGN_EPI) { if (wr == 0) PG8_BAR; }
	s_add_i32 s25, s25, s16
	v_lshl_add_u64 v[140:141], v[140:141], 0, s[28:29]
	s_mov_b32 m0, s25
	ds_read_b128 v[180:183], v145 offset:49152
	ds_read_b128 v[184:187], v145 offset:50176
	ds_read_b128 v[188:191], v145 offset:51200
	ds_read_b128 v[192:195], v145 offset:52224
	ds_read_b128 v[196:199], v145 offset:53248
	ds_read_b128 v[200:203], v145 offset:54272
	ds_read_b128 v[224:227], v145 offset:55296
	ds_read_b128 v[228:231], v145 offset:56320
	global_load_lds_dwordx4 v[140:141], off
	s_add_i32 m0, s25, 0x2000
	s_add_u32 s26, s66, 0x40080
	v_lshl_add_u64 v[140:141], v[214:215], 0, s[28:29]
	s_addc_u32 s27, s67, 0
	s_add_i32 s25, s30, s16
	global_load_lds_dwordx4 v[140:141], off
	v_lshl_add_u64 v[140:141], s[26:27], 0, v[0:1]
	s_mov_b32 m0, s25
	s_nop 0
	global_load_lds_dwordx4 v[140:141], off
	v_lshl_add_u64 v[140:141], s[26:27], 0, v[130:131]
	s_add_i32 m0, s25, 0x2000
	s_nop 0
	global_load_lds_dwordx4 v[140:141], off
	v_lshl_add_u64 v[140:141], v[232:233], 0, s[28:29]
	s_mov_b32 m0, s63
	s_nop 0
	global_load_lds_dwordx4 v[140:141], off
	v_lshl_add_u64 v[140:141], v[234:235], 0, s[28:29]
	s_mov_b32 m0, s74
	s_nop 0
	global_load_lds_dwordx4 v[140:141], off
	s_waitcnt vmcnt(8)
	s_waitcnt lgkmcnt(0)
	s_barrier
	v_mfma_f32_16x16x32_bf16 v[62:65], v[136:139], v[180:183], v[62:65]
	v_mfma_f32_16x16x32_bf16 v[62:65], v[146:149], v[184:187], v[62:65]
	v_mfma_f32_16x16x32_bf16 v[58:61], v[150:153], v[180:183], v[58:61]
	v_mfma_f32_16x16x32_bf16 v[58:61], v[154:157], v[184:187], v[58:61]
	v_mfma_f32_16x16x32_bf16 v[46:49], v[136:139], v[188:191], v[46:49]
	v_mfma_f32_16x16x32_bf16 v[46:49], v[146:149], v[192:195], v[46:49]
	v_mfma_f32_16x16x32_bf16 v[42:45], v[150:153], v[188:191], v[42:45]
	v_mfma_f32_16x16x32_bf16 v[42:45], v[154:157], v[192:195], v[42:45]
	v_mfma_f32_16x16x32_bf16 v[30:33], v[136:139], v[196:199], v[30:33]
	v_mfma_f32_16x16x32_bf16 v[30:33], v[146:149], v[200:203], v[30:33]
	v_mfma_f32_16x16x32_bf16 v[26:29], v[150:153], v[196:199], v[26:29]
	v_mfma_f32_16x16x32_bf16 v[26:29], v[154:157], v[200:203], v[26:29]
	v_mfma_f32_16x16x32_bf16 v[14:17], v[136:139], v[224:227], v[14:17]
	v_mfma_f32_16x16x32_bf16 v[14:17], v[146:149], v[228:231], v[14:17]
	v_mfma_f32_16x16x32_bf16 v[10:13], v[150:153], v[224:227], v[10:13]
	v_mfma_f32_16x16x32_bf16 v[10:13], v[154:157], v[228:231], v[10:13]
	v_mfma_f32_16x16x32_bf16 v[54:57], v[158:161], v[180:183], v[54:57]
	v_mfma_f32_16x16x32_bf16 v[54:57], v[168:171], v[184:187], v[54:57]
	v_mfma_f32_16x16x32_bf16 v[50:53], v[172:175], v[180:183], v[50:53]
	v_mfma_f32_16x16x32_bf16 v[50:53], v[176:179], v[184:187], v[50:53]
	v_mfma_f32_16x16x32_bf16 v[38:41], v[158:161], v[188:191], v[38:41]
	v_mfma_f32_16x16x32_bf16 v[38:41], v[168:171], v[192:195], v[38:41]
	v_mfma_f32_16x16x32_bf16 v[34:37], v[172:175], v[188:191], v[34:37]
	v_mfma_f32_16x16x32_bf16 v[34:37], v[176:179], v[192:195], v[34:37]
	v_mfma_f32_16x16x32_bf16 v[22:25], v[158:161], v[196:199], v[22:25]
	v_mfma_f32_16x16x32_bf16 v[22:25], v[168:171], v[200:203], v[22:25]
	v_mfma_f32_16x16x32_bf16 v[18:21], v[172:175], v[196:199], v[18:21]
	v_mfma_f32_16x16x32_bf16 v[18:21], v[176:179], v[200:203], v[18:21]
	v_mfma_f32_16x16x32_bf16 v[6:9], v[158:161], v[224:227], v[6:9]
	v_mfma_f32_16x16x32_bf16 v[6:9], v[168:171], v[228:231], v[6:9]
	v_mfma_f32_16x16x32_bf16 v[2:5], v[172:175], v[224:227], v[2:5]
	v_mfma_f32_16x16x32_bf16 v[2:5], v[176:179], v[228:231], v[2:5]
	s_barrier
	s_add_i32 s24, s24, 2
	s_add_u32 s14, s14, 0x100
	s_addc_u32 s15, s15, 0
	s_cmp_gt_u32 s24, 13
	s_mov_b64 s[58:59], s[64:65]
	s_cbranch_scc0 .LBB0_654
	s_and_b64 vcc, exec, s[8:9]
	s_cbranch_vccz .LBB0_657
	s_barrier

; #define PG8_STAGE(bufoff, gbase, voff) do { _Pragma("unroll") for (int _i = 0; _i < 2; ++_i) \
;         __builtin_amdgcn_global_load_lds((const unsigned*)((const char*)(gbase) + (voff)[_i]), (PG8_LAS unsigned*)(lds + (bufoff) + ldsw + _i * 8192), 16, 0, 0); } while (0)
; #define PG8_LDA(dst, b, h) do { _Pragma("unroll") for (int m = 0; m < 4; ++m) _Pragma("unroll") for (int k = 0; k < 2; ++k) dst[m][k] = *(const PG8_LAS bf16x8*)(lds + PG8_SA(b, h) + aoff + m * 2048 + k * 1024); } while (0)
; #define PG8_LDB(dst, b, h) do { _Pragma("unroll") for (int n = 0; n < 2; ++n) _Pragma("unroll") for (int k = 0; k < 2; ++k) dst[n][k] = *(const PG8_LAS bf16x8*)(lds + PG8_SB(b, h) + boff + n * 2048 + k * 1024); } while (0)
; #define PG8_MMA(ai, bj, At, Bt) do { __builtin_amdgcn_s_setprio(1); _Pragma("unroll") for (int m = 0; m < 4; ++m) _Pragma("unroll") for (int n = 0; n < 2; ++n) _Pragma("unroll") for (int k = 0; k < 2; ++k) \
;         acc[ai][bj][m][n] = __builtin_amdgcn_mfma_f32_16x16x32_bf16(Bt[n][k], At[m][k], acc[ai][bj][m][n], 0, 0, 0); __builtin_amdgcn_s_setprio(0); } while (0)
; #define PG8_WAIT_V(n) asm volatile("s_waitcnt vmcnt(" #n ")" ::: "memory")
; #define PG8_BAR __builtin_amdgcn_s_barrier()
; template <class Epi, class Sched, bool ALIGN_EPI = false, bool SP2 = false>
; __device__ __forceinline__ void gemm_phase(PG8_LAS unsigned char* lds, const Gemm g, const Sched S, const Epi E) {
;     ...
;         for (int t = 0; t < nt; t += 2) {
;             const bool last = (t == nt - 2);
;             const char* a1 = cA + (size_t)(t + 1) * kstep;
;             const char* a2 = last ? nA : cA + (size_t)(t + 2) * kstep; const char* b2 = last ? nB : cB + (size_t)(t + 2) * kstep;
;             const char* a3 = a2 + kstep; const char* b3 = b2 + kstep;
;             if (last && has_next) S.a_ready(nxt);
;             if constexpr (SP2) {
;             PG8_LDB(B0, 0, 0); PG8_LDB(B1, 0, 1); PG8_SCHED; PG8_LDA(At, 0, 0); PG8_STAGE(PG8_SA(1, 1), a1 + hstep, voffA);
;             PG8_WAIT_V(8); PG8_WAIT_L(0); PG8_BAR; PG8_MMA(0, 0, At, B0); PG8_MMA(0, 1, At, B1); PG8_BAR; PG8_SCHED;
;             PG8_LDA(At, 0, 1); PG8_STAGE(PG8_SB(0, 0), b2, voffB); PG8_STAGE(PG8_SB(0, 1), b2 + hstep, voffB); PG8_STAGE(PG8_SA(0, 0), a2, voffA);
;             PG8_WAIT_V(8); PG8_WAIT_L(0); PG8_BAR; PG8_MMA(1, 0, At, B0); PG8_MMA(1, 1, At, B1); PG8_BAR; PG8_SCHED;
.LBB0_726:
	s_add_u32 s25, s40, 0xfff80080
	s_addc_u32 s26, s41, -1
	s_add_i32 s27, 0, 0x10000
	s_cmp_eq_u32 s24, 28
	s_cselect_b32 s45, s57, s26
	s_cselect_b32 s44, s66, s25
	s_cselect_b32 s43, s53, s15
	s_cselect_b32 s42, s67, s14
	s_add_i32 s25, 0, 0x14000
	v_add_u32_e32 v152, s27, v141
	v_add_u32_e32 v160, s25, v141
	ds_read_b128 v[136:139], v152
	ds_read_b128 v[144:147], v152 offset:1024
	ds_read_b128 v[148:151], v152 offset:2048
	ds_read_b128 v[152:155], v152 offset:3072
	ds_read_b128 v[156:159], v160
	ds_read_b128 v[168:171], v160 offset:1024
	ds_read_b128 v[172:175], v160 offset:2048
	ds_read_b128 v[176:179], v160 offset:3072
	v_lshl_add_u64 v[160:161], s[40:41], 0, v[132:133]
	s_add_i32 m0, s21, 0xc000
	ds_read_b128 v[180:183], v143
	ds_read_b128 v[184:187], v143 offset:1024
	ds_read_b128 v[188:191], v143 offset:2048
	ds_read_b128 v[192:195], v143 offset:3072
	ds_read_b128 v[196:199], v143 offset:4096
	ds_read_b128 v[200:203], v143 offset:5120
	ds_read_b128 v[224:227], v143 offset:6144
	ds_read_b128 v[228:231], v143 offset:7168
	global_load_lds_dwordx4 v[160:161], off
	v_lshl_add_u64 v[160:161], s[40:41], 0, v[134:135]
	s_add_i32 m0, s21, 0xe000
	s_nop 0
	global_load_lds_dwordx4 v[160:161], off
	s_waitcnt vmcnt(8)
	s_waitcnt lgkmcnt(0)
	s_barrier
	v_mfma_f32_16x16x32_bf16 v[126:129], v[136:139], v[180:183], v[126:129]
	v_mfma_f32_16x16x32_bf16 v[126:129], v[144:147], v[184:187], v[126:129]
	v_mfma_f32_16x16x32_bf16 v[122:125], v[148:151], v[180:183], v[122:125]
	v_mfma_f32_16x16x32_bf16 v[122:125], v[152:155], v[184:187], v[122:125]
	v_mfma_f32_16x16x32_bf16 v[114:117], v[136:139], v[188:191], v[114:117]
	v_mfma_f32_16x16x32_bf16 v[114:117], v[144:147], v[192:195], v[114:117]
	v_mfma_f32_16x16x32_bf16 v[106:109], v[148:151], v[188:191], v[106:109]
	v_mfma_f32_16x16x32_bf16 v[106:109], v[152:155], v[192:195], v[106:109]
	v_mfma_f32_16x16x32_bf16 v[98:101], v[136:139], v[196:199], v[98:101]
	v_mfma_f32_16x16x32_bf16 v[98:101], v[144:147], v[200:203], v[98:101]
	v_mfma_f32_16x16x32_bf16 v[90:93], v[148:151], v[196:199], v[90:93]
	v_mfma_f32_16x16x32_bf16 v[90:93], v[152:155], v[200:203], v[90:93]
	v_mfma_f32_16x16x32_bf16 v[82:85], v[136:139], v[224:227], v[82:85]
	v_mfma_f32_16x16x32_bf16 v[82:85], v[144:147], v[228:231], v[82:85]
	v_mfma_f32_16x16x32_bf16 v[74:77], v[148:151], v[224:227], v[74:77]
	v_mfma_f32_16x16x32_bf16 v[74:77], v[152:155], v[228:231], v[74:77]
	v_mfma_f32_16x16x32_bf16 v[118:121], v[156:159], v[180:183], v[118:121]
	v_mfma_f32_16x16x32_bf16 v[118:121], v[168:171], v[184:187], v[118:121]
	v_mfma_f32_16x16x32_bf16 v[110:113], v[172:175], v[180:183], v[110:113]
	v_mfma_f32_16x16x32_bf16 v[110:113], v[176:179], v[184:187], v[110:113]
	v_mfma_f32_16x16x32_bf16 v[102:105], v[156:159], v[188:191], v[102:105]
	v_mfma_f32_16x16x32_bf16 v[102:105], v[168:171], v[192:195], v[102:105]
	v_mfma_f32_16x16x32_bf16 v[94:97], v[172:175], v[188:191], v[94:97]
	v_mfma_f32_16x16x32_bf16 v[94:97], v[176:179], v[192:195], v[94:97]
	v_mfma_f32_16x16x32_bf16 v[86:89], v[156:159], v[196:199], v[86:89]
	v_mfma_f32_16x16x32_bf16 v[86:89], v[168:171], v[200:203], v[86:89]
	v_mfma_f32_16x16x32_bf16 v[78:81], v[172:175], v[196:199], v[78:81]
	v_mfma_f32_16x16x32_bf16 v[78:81], v[176:179], v[200:203], v[78:81]
	v_mfma_f32_16x16x32_bf16 v[70:73], v[156:159], v[224:227], v[70:73]
	v_mfma_f32_16x16x32_bf16 v[70:73], v[168:171], v[228:231], v[70:73]
	v_mfma_f32_16x16x32_bf16 v[66:69], v[172:175], v[224:227], v[66:69]
	v_mfma_f32_16x16x32_bf16 v[66:69], v[176:179], v[228:231], v[66:69]
	s_barrier
	s_add_i32 s26, s27, s16
	v_lshl_add_u64 v[160:161], s[42:43], 0, v[0:1]
	s_mov_b32 m0, s26
	ds_read_b128 v[180:183], v143 offset:16384
	ds_read_b128 v[184:187], v143 offset:17408
	ds_read_b128 v[188:191], v143 offset:18432
	ds_read_b128 v[192:195], v143 offset:19456
	ds_read_b128 v[196:199], v143 offset:20480
	ds_read_b128 v[200:203], v143 offset:21504
	ds_read_b128 v[224:227], v143 offset:22528
	ds_read_b128 v[228:231], v143 offset:23552
	global_load_lds_dwordx4 v[160:161], off
	s_add_i32 m0, s26, 0x2000
	s_add_u32 s26, s42, 0x80000
	v_lshl_add_u64 v[232:233], s[42:43], 0, v[130:131]
	s_addc_u32 s27, s43, 0
	s_add_i32 s25, s25, s16
	global_load_lds_dwordx4 v[232:233], off
	v_lshl_add_u64 v[234:235], s[26:27], 0, v[0:1]
	s_mov_b32 m0, s25
	v_lshl_add_u64 v[236:237], s[44:45], 0, v[130:131]
	global_load_lds_dwordx4 v[234:235], off
	v_lshl_add_u64 v[234:235], s[26:27], 0, v[130:131]
	s_add_i32 m0, s25, 0x2000
	s_nop 0
	global_load_lds_dwordx4 v[234:235], off
	v_lshl_add_u64 v[234:235], s[44:45], 0, v[0:1]
	s_mov_b32 m0, s21
	s_nop 0
	global_load_lds_dwordx4 v[234:235], off
	s_mov_b32 m0, s22
	s_nop 0
	global_load_lds_dwordx4 v[236:237], off
	s_waitcnt vmcnt(8)
	s_waitcnt lgkmcnt(0)
	s_barrier
; #define PG8_STAGE(bufoff, gbase, voff) do { _Pragma("unroll") for (int _i = 0; _i < 2; ++_i) \
;         __builtin_amdgcn_global_load_lds((const unsigned*)((const char*)(gbase) + (voff)[_i]), (PG8_LAS unsigned*)(lds + (bufoff) + ldsw + _i * 8192), 16, 0, 0); } while (0)
; #define PG8_LDA(dst, b, h) do { _Pragma("unroll") for (int m = 0; m < 4; ++m) _Pragma("unroll") for (int k = 0; k < 2; ++k) dst[m][k] = *(const PG8_LAS bf16x8*)(lds + PG8_SA(b, h) + aoff + m * 2048 + k * 1024); } while (0)
; #define PG8_LDB(dst, b, h) do { _Pragma("unroll") for (int n = 0; n < 2; ++n) _Pragma("unroll") for (int k = 0; k < 2; ++k) dst[n][k] = *(const PG8_LAS bf16x8*)(lds + PG8_SB(b, h) + boff + n * 2048 + k * 1024); } while (0)
; #define PG8_MMA(ai, bj, At, Bt) do { __builtin_amdgcn_s_setprio(1); _Pragma("unroll") for (int m = 0; m < 4; ++m) _Pragma("unroll") for (int n = 0; n < 2; ++n) _Pragma("unroll") for (int k = 0; k < 2; ++k) \
;         acc[ai][bj][m][n] = __builtin_amdgcn_mfma_f32_16x16x32_bf16(Bt[n][k], At[m][k], acc[ai][bj][m][n], 0, 0, 0); __builtin_amdgcn_s_setprio(0); } while (0)
; #define PG8_WAIT_V(n) asm volatile("s_waitcnt vmcnt(" #n ")" ::: "memory")
; #define PG8_WAIT_L(n) asm volatile("s_waitcnt lgkmcnt(" #n ")" ::: "memory")
; #define PG8_BAR __builtin_amdgcn_s_barrier()
; #define PG8_SCHED __builtin_amdgcn_sched_barrier(0)
; template <class Epi, class Sched, bool ALIGN_EPI = false, bool SP2 = false>
; __device__ __forceinline__ void gemm_phase(PG8_LAS unsigned char* lds, const Gemm g, const Sched S, const Epi E) {
;     ...
;             PG8_WAIT_V(8); PG8_WAIT_L(0); PG8_BAR; PG8_MMA(1, 0, At, B0); PG8_MMA(1, 1, At, B1); PG8_BAR; PG8_SCHED;
;             PG8_LDB(B0, 1, 0); PG8_LDB(B1, 1, 1); PG8_SCHED; PG8_LDA(At, 1, 0); PG8_STAGE(PG8_SA(0, 1), a2 + hstep, voffA);
;             PG8_WAIT_V(8); PG8_WAIT_L(0); PG8_BAR; PG8_MMA(0, 0, At, B0); PG8_MMA(0, 1, At, B1); PG8_BAR; PG8_SCHED;
	v_mfma_f32_16x16x32_bf16 v[62:65], v[136:139], v[180:183], v[62:65]
	v_mfma_f32_16x16x32_bf16 v[62:65], v[144:147], v[184:187], v[62:65]
	v_mfma_f32_16x16x32_bf16 v[58:61], v[148:151], v[180:183], v[58:61]
	v_mfma_f32_16x16x32_bf16 v[58:61], v[152:155], v[184:187], v[58:61]
	v_mfma_f32_16x16x32_bf16 v[50:53], v[136:139], v[188:191], v[50:53]
	v_mfma_f32_16x16x32_bf16 v[50:53], v[144:147], v[192:195], v[50:53]
	v_mfma_f32_16x16x32_bf16 v[42:45], v[148:151], v[188:191], v[42:45]
	v_mfma_f32_16x16x32_bf16 v[42:45], v[152:155], v[192:195], v[42:45]
	v_mfma_f32_16x16x32_bf16 v[34:37], v[136:139], v[196:199], v[34:37]
	v_mfma_f32_16x16x32_bf16 v[34:37], v[144:147], v[200:203], v[34:37]
	v_mfma_f32_16x16x32_bf16 v[26:29], v[148:151], v[196:199], v[26:29]
	v_mfma_f32_16x16x32_bf16 v[26:29], v[152:155], v[200:203], v[26:29]
	v_mfma_f32_16x16x32_bf16 v[18:21], v[136:139], v[224:227], v[18:21]
	v_mfma_f32_16x16x32_bf16 v[18:21], v[144:147], v[228:231], v[18:21]
	v_mfma_f32_16x16x32_bf16 v[10:13], v[148:151], v[224:227], v[10:13]
	v_mfma_f32_16x16x32_bf16 v[10:13], v[152:155], v[228:231], v[10:13]
	v_mfma_f32_16x16x32_bf16 v[54:57], v[156:159], v[180:183], v[54:57]
	v_mfma_f32_16x16x32_bf16 v[54:57], v[168:171], v[184:187], v[54:57]
	v_mfma_f32_16x16x32_bf16 v[46:49], v[172:175], v[180:183], v[46:49]
	v_mfma_f32_16x16x32_bf16 v[46:49], v[176:179], v[184:187], v[46:49]
	v_mfma_f32_16x16x32_bf16 v[38:41], v[156:159], v[188:191], v[38:41]
	v_mfma_f32_16x16x32_bf16 v[38:41], v[168:171], v[192:195], v[38:41]
	v_mfma_f32_16x16x32_bf16 v[30:33], v[172:175], v[188:191], v[30:33]
	v_mfma_f32_16x16x32_bf16 v[30:33], v[176:179], v[192:195], v[30:33]
	v_mfma_f32_16x16x32_bf16 v[22:25], v[156:159], v[196:199], v[22:25]
	v_mfma_f32_16x16x32_bf16 v[22:25], v[168:171], v[200:203], v[22:25]
	v_mfma_f32_16x16x32_bf16 v[14:17], v[172:175], v[196:199], v[14:17]
	v_mfma_f32_16x16x32_bf16 v[14:17], v[176:179], v[200:203], v[14:17]
	v_mfma_f32_16x16x32_bf16 v[6:9], v[156:159], v[224:227], v[6:9]
	v_mfma_f32_16x16x32_bf16 v[6:9], v[168:171], v[228:231], v[6:9]
	v_mfma_f32_16x16x32_bf16 v[2:5], v[172:175], v[224:227], v[2:5]
	v_mfma_f32_16x16x32_bf16 v[2:5], v[176:179], v[228:231], v[2:5]
	s_barrier
	s_add_i32 s25, 0, 0x18000
	s_add_i32 s30, 0, 0x1c000
	v_add_u32_e32 v152, s25, v141
	v_add_u32_e32 v167, s30, v141
	ds_read_b128 v[136:139], v152
	ds_read_b128 v[144:147], v152 offset:1024
	ds_read_b128 v[148:151], v152 offset:2048
	ds_read_b128 v[152:155], v152 offset:3072
	ds_read_b128 v[156:159], v167
	ds_read_b128 v[168:171], v167 offset:1024
	ds_read_b128 v[172:175], v167 offset:2048
	ds_read_b128 v[176:179], v167 offset:3072
	s_add_u32 s26, s44, 0x80000
	s_addc_u32 s27, s45, 0
	s_mov_b32 m0, s47
	v_lshl_add_u64 v[238:239], s[26:27], 0, v[0:1]
	ds_read_b128 v[180:183], v143 offset:32768
	ds_read_b128 v[184:187], v143 offset:33792
	ds_read_b128 v[188:191], v143 offset:34816
	ds_read_b128 v[192:195], v143 offset:35840
	ds_read_b128 v[196:199], v143 offset:36864
	ds_read_b128 v[200:203], v143 offset:37888
	ds_read_b128 v[224:227], v143 offset:38912
	ds_read_b128 v[228:231], v143 offset:39936
	global_load_lds_dwordx4 v[238:239], off
	v_lshl_add_u64 v[238:239], s[26:27], 0, v[130:131]
	s_mov_b32 m0, s62
	s_nop 0
	global_load_lds_dwordx4 v[238:239], off
	s_waitcnt vmcnt(8)
	s_waitcnt lgkmcnt(0)
	s_barrier
	v_mfma_f32_16x16x32_bf16 v[126:129], v[136:139], v[180:183], v[126:129]
	v_mfma_f32_16x16x32_bf16 v[126:129], v[144:147], v[184:187], v[126:129]
	v_mfma_f32_16x16x32_bf16 v[122:125], v[148:151], v[180:183], v[122:125]
	v_mfma_f32_16x16x32_bf16 v[122:125], v[152:155], v[184:187], v[122:125]
	v_mfma_f32_16x16x32_bf16 v[114:117], v[136:139], v[188:191], v[114:117]
	v_mfma_f32_16x16x32_bf16 v[114:117], v[144:147], v[192:195], v[114:117]
	v_mfma_f32_16x16x32_bf16 v[106:109], v[148:151], v[188:191], v[106:109]
	v_mfma_f32_16x16x32_bf16 v[106:109], v[152:155], v[192:195], v[106:109]
	v_mfma_f32_16x16x32_bf16 v[98:101], v[136:139], v[196:199], v[98:101]
	v_mfma_f32_16x16x32_bf16 v[98:101], v[144:147], v[200:203], v[98:101]
	v_mfma_f32_16x16x32_bf16 v[90:93], v[148:151], v[196:199], v[90:93]
	v_mfma_f32_16x16x32_bf16 v[90:93], v[152:155], v[200:203], v[90:93]
	v_mfma_f32_16x16x32_bf16 v[82:85], v[136:139], v[224:227], v[82:85]
	v_mfma_f32_16x16x32_bf16 v[82:85], v[144:147], v[228:231], v[82:85]
	v_mfma_f32_16x16x32_bf16 v[74:77], v[148:151], v[224:227], v[74:77]
	v_mfma_f32_16x16x32_bf16 v[74:77], v[152:155], v[228:231], v[74:77]
	v_mfma_f32_16x16x32_bf16 v[118:121], v[156:159], v[180:183], v[118:121]
	v_mfma_f32_16x16x32_bf16 v[118:121], v[168:171], v[184:187], v[118:121]
	v_mfma_f32_16x16x32_bf16 v[110:113], v[172:175], v[180:183], v[110:113]
	v_mfma_f32_16x16x32_bf16 v[110:113], v[176:179], v[184:187], v[110:113]
	v_mfma_f32_16x16x32_bf16 v[102:105], v[156:159], v[188:191], v[102:105]
	v_mfma_f32_16x16x32_bf16 v[102:105], v[168:171], v[192:195], v[102:105]
	v_mfma_f32_16x16x32_bf16 v[94:97], v[172:175], v[188:191], v[94:97]
	v_mfma_f32_16x16x32_bf16 v[94:97], v[176:179], v[192:195], v[94:97]
	v_mfma_f32_16x16x32_bf16 v[86:89], v[156:159], v[196:199], v[86:89]
	v_mfma_f32_16x16x32_bf16 v[86:89], v[168:171], v[200:203], v[86:89]
	v_mfma_f32_16x16x32_bf16 v[78:81], v[172:175], v[196:199], v[78:81]
	v_mfma_f32_16x16x32_bf16 v[78:81], v[176:179], v[200:203], v[78:81]
	v_mfma_f32_16x16x32_bf16 v[70:73], v[156:159], v[224:227], v[70:73]
	v_mfma_f32_16x16x32_bf16 v[70:73], v[168:171], v[228:231], v[70:73]
	v_mfma_f32_16x16x32_bf16 v[66:69], v[172:175], v[224:227], v[66:69]
	v_mfma_f32_16x16x32_bf16 v[66:69], v[176:179], v[228:231], v[66:69]
	s_barrier
; #define PG8_STAGE(bufoff, gbase, voff) do { _Pragma("unroll") for (int _i = 0; _i < 2; ++_i) \
;         __builtin_amdgcn_global_load_lds((const unsigned*)((const char*)(gbase) + (voff)[_i]), (PG8_LAS unsigned*)(lds + (bufoff) + ldsw + _i * 8192), 16, 0, 0); } while (0)
; #define PG8_LDA(dst, b, h) do { _Pragma("unroll") for (int m = 0; m < 4; ++m) _Pragma("unroll") for (int k = 0; k < 2; ++k) dst[m][k] = *(const PG8_LAS bf16x8*)(lds + PG8_SA(b, h) + aoff + m * 2048 + k * 1024); } while (0)
; #define PG8_MMA(ai, bj, At, Bt) do { __builtin_amdgcn_s_setprio(1); _Pragma("unroll") for (int m = 0; m < 4; ++m) _Pragma("unroll") for (int n = 0; n < 2; ++n) _Pragma("unroll") for (int k = 0; k < 2; ++k) \
;         acc[ai][bj][m][n] = __builtin_amdgcn_mfma_f32_16x16x32_bf16(Bt[n][k], At[m][k], acc[ai][bj][m][n], 0, 0, 0); __builtin_amdgcn_s_setprio(0); } while (0)
; #define PG8_WAIT_V(n) asm volatile("s_waitcnt vmcnt(" #n ")" ::: "memory")
; #define PG8_WAIT_L(n) asm volatile("s_waitcnt lgkmcnt(" #n ")" ::: "memory")
; #define PG8_BAR __builtin_amdgcn_s_barrier()
; #define PG8_SCHED __builtin_amdgcn_sched_barrier(0)
; template <class Epi, class Sched, bool ALIGN_EPI = false, bool SP2 = false>
; __device__ __forceinline__ void gemm_phase(PG8_LAS unsigned char* lds, const Gemm g, const Sched S, const Epi E) {
;     ...
;             PG8_LDA(At, 1, 1); PG8_STAGE(PG8_SB(1, 0), b3, voffB); PG8_STAGE(PG8_SB(1, 1), b3 + hstep, voffB); PG8_STAGE(PG8_SA(1, 0), a3, voffA);
;             PG8_WAIT_V(8); PG8_WAIT_L(0); PG8_BAR; PG8_MMA(1, 0, At, B0); PG8_MMA(1, 1, At, B1); PG8_BAR; PG8_SCHED;
;     ...
;         if constexpr (ALIGN_EPI) { if (wr == 0) PG8_BAR; }
	s_add_i32 s25, s25, s16
	v_lshl_add_u64 v[160:161], v[160:161], 0, s[28:29]
	s_mov_b32 m0, s25
	ds_read_b128 v[180:183], v143 offset:49152
	ds_read_b128 v[184:187], v143 offset:50176
	ds_read_b128 v[188:191], v143 offset:51200
	ds_read_b128 v[192:195], v143 offset:52224
	ds_read_b128 v[196:199], v143 offset:53248
	ds_read_b128 v[200:203], v143 offset:54272
	ds_read_b128 v[224:227], v143 offset:55296
	ds_read_b128 v[228:231], v143 offset:56320
	global_load_lds_dwordx4 v[160:161], off
	s_add_i32 m0, s25, 0x2000
	s_add_u32 s26, s42, 0x80080
	v_lshl_add_u64 v[160:161], v[232:233], 0, s[28:29]
	s_addc_u32 s27, s43, 0
	s_add_i32 s25, s30, s16
	global_load_lds_dwordx4 v[160:161], off
	v_lshl_add_u64 v[160:161], s[26:27], 0, v[0:1]
	s_mov_b32 m0, s25
	s_nop 0
	global_load_lds_dwordx4 v[160:161], off
	v_lshl_add_u64 v[160:161], s[26:27], 0, v[130:131]
	s_add_i32 m0, s25, 0x2000
	s_nop 0
	global_load_lds_dwordx4 v[160:161], off
	v_lshl_add_u64 v[160:161], v[234:235], 0, s[28:29]
	s_mov_b32 m0, s63
	s_nop 0
	global_load_lds_dwordx4 v[160:161], off
	v_lshl_add_u64 v[160:161], v[236:237], 0, s[28:29]
	s_mov_b32 m0, s74
	s_nop 0
	global_load_lds_dwordx4 v[160:161], off
	s_waitcnt vmcnt(8)
	s_waitcnt lgkmcnt(0)
	s_barrier
	v_mfma_f32_16x16x32_bf16 v[62:65], v[136:139], v[180:183], v[62:65]
	v_mfma_f32_16x16x32_bf16 v[62:65], v[144:147], v[184:187], v[62:65]
	v_mfma_f32_16x16x32_bf16 v[58:61], v[148:151], v[180:183], v[58:61]
	v_mfma_f32_16x16x32_bf16 v[58:61], v[152:155], v[184:187], v[58:61]
	v_mfma_f32_16x16x32_bf16 v[50:53], v[136:139], v[188:191], v[50:53]
	v_mfma_f32_16x16x32_bf16 v[50:53], v[144:147], v[192:195], v[50:53]
	v_mfma_f32_16x16x32_bf16 v[42:45], v[148:151], v[188:191], v[42:45]
	v_mfma_f32_16x16x32_bf16 v[42:45], v[152:155], v[192:195], v[42:45]
	v_mfma_f32_16x16x32_bf16 v[34:37], v[136:139], v[196:199], v[34:37]
	v_mfma_f32_16x16x32_bf16 v[34:37], v[144:147], v[200:203], v[34:37]
	v_mfma_f32_16x16x32_bf16 v[26:29], v[148:151], v[196:199], v[26:29]
	v_mfma_f32_16x16x32_bf16 v[26:29], v[152:155], v[200:203], v[26:29]
	v_mfma_f32_16x16x32_bf16 v[18:21], v[136:139], v[224:227], v[18:21]
	v_mfma_f32_16x16x32_bf16 v[18:21], v[144:147], v[228:231], v[18:21]
	v_mfma_f32_16x16x32_bf16 v[10:13], v[148:151], v[224:227], v[10:13]
	v_mfma_f32_16x16x32_bf16 v[10:13], v[152:155], v[228:231], v[10:13]
	v_mfma_f32_16x16x32_bf16 v[54:57], v[156:159], v[180:183], v[54:57]
	v_mfma_f32_16x16x32_bf16 v[54:57], v[168:171], v[184:187], v[54:57]
	v_mfma_f32_16x16x32_bf16 v[46:49], v[172:175], v[180:183], v[46:49]
	v_mfma_f32_16x16x32_bf16 v[46:49], v[176:179], v[184:187], v[46:49]
	v_mfma_f32_16x16x32_bf16 v[38:41], v[156:159], v[188:191], v[38:41]
	v_mfma_f32_16x16x32_bf16 v[38:41], v[168:171], v[192:195], v[38:41]
	v_mfma_f32_16x16x32_bf16 v[30:33], v[172:175], v[188:191], v[30:33]
	v_mfma_f32_16x16x32_bf16 v[30:33], v[176:179], v[192:195], v[30:33]
	v_mfma_f32_16x16x32_bf16 v[22:25], v[156:159], v[196:199], v[22:25]
	v_mfma_f32_16x16x32_bf16 v[22:25], v[168:171], v[200:203], v[22:25]
	v_mfma_f32_16x16x32_bf16 v[14:17], v[172:175], v[196:199], v[14:17]
	v_mfma_f32_16x16x32_bf16 v[14:17], v[176:179], v[200:203], v[14:17]
	v_mfma_f32_16x16x32_bf16 v[6:9], v[156:159], v[224:227], v[6:9]
	v_mfma_f32_16x16x32_bf16 v[6:9], v[168:171], v[228:231], v[6:9]
	v_mfma_f32_16x16x32_bf16 v[2:5], v[172:175], v[224:227], v[2:5]
	v_mfma_f32_16x16x32_bf16 v[2:5], v[176:179], v[228:231], v[2:5]
	s_barrier
	s_add_i32 s24, s24, 2
	s_add_u32 s40, s40, 0x100
	s_addc_u32 s41, s41, 0
	s_add_u32 s14, s14, 0x100
	s_addc_u32 s15, s15, 0
	s_cmp_gt_u32 s24, 29
	s_cbranch_scc0 .LBB0_726
	s_and_b64 vcc, exec, s[8:9]
	s_cbranch_vccz .LBB0_729
	s_barrier

; #define PG8_STAGE(bufoff, gbase, voff) do { _Pragma("unroll") for (int _i = 0; _i < 2; ++_i) \
;         __builtin_amdgcn_global_load_lds((const unsigned*)((const char*)(gbase) + (voff)[_i]), (PG8_LAS unsigned*)(lds + (bufoff) + ldsw + _i * 8192), 16, 0, 0); } while (0)
; #define PG8_LDA(dst, b, h) do { _Pragma("unroll") for (int m = 0; m < 4; ++m) _Pragma("unroll") for (int k = 0; k < 2; ++k) dst[m][k] = *(const PG8_LAS bf16x8*)(lds + PG8_SA(b, h) + aoff + m * 2048 + k * 1024); } while (0)
; #define PG8_LDB(dst, b, h) do { _Pragma("unroll") for (int n = 0; n < 2; ++n) _Pragma("unroll") for (int k = 0; k < 2; ++k) dst[n][k] = *(const PG8_LAS bf16x8*)(lds + PG8_SB(b, h) + boff + n * 2048 + k * 1024); } while (0)
; #define PG8_MMA(ai, bj, At, Bt) do { __builtin_amdgcn_s_setprio(1); _Pragma("unroll") for (int m = 0; m < 4; ++m) _Pragma("unroll") for (int n = 0; n < 2; ++n) _Pragma("unroll") for (int k = 0; k < 2; ++k) \
;         acc[ai][bj][m][n] = __builtin_amdgcn_mfma_f32_16x16x32_bf16(Bt[n][k], At[m][k], acc[ai][bj][m][n], 0, 0, 0); __builtin_amdgcn_s_setprio(0); } while (0)
; #define PG8_WAIT_V(n) asm volatile("s_waitcnt vmcnt(" #n ")" ::: "memory")
; #define PG8_BAR __builtin_amdgcn_s_barrier()
; template <class Epi, class Sched, bool ALIGN_EPI = false, bool SP2 = false>
; __device__ __forceinline__ void gemm_phase(PG8_LAS unsigned char* lds, const Gemm g, const Sched S, const Epi E) {
;     ...
;         for (int t = 0; t < nt; t += 2) {
;             const bool last = (t == nt - 2);
;             const char* a1 = cA + (size_t)(t + 1) * kstep;
;             const char* a2 = last ? nA : cA + (size_t)(t + 2) * kstep; const char* b2 = last ? nB : cB + (size_t)(t + 2) * kstep;
;             const char* a3 = a2 + kstep; const char* b3 = b2 + kstep;
;             if (last && has_next) S.a_ready(nxt);
;             if constexpr (SP2) {
;             PG8_LDB(B0, 0, 0); PG8_LDB(B1, 0, 1); PG8_SCHED; PG8_LDA(At, 0, 0); PG8_STAGE(PG8_SA(1, 1), a1 + hstep, voffA);
;             PG8_WAIT_V(8); PG8_WAIT_L(0); PG8_BAR; PG8_MMA(0, 0, At, B0); PG8_MMA(0, 1, At, B1); PG8_BAR; PG8_SCHED;
;             PG8_LDA(At, 0, 1); PG8_STAGE(PG8_SB(0, 0), b2, voffB); PG8_STAGE(PG8_SB(0, 1), b2 + hstep, voffB); PG8_STAGE(PG8_SA(0, 0), a2, voffA);
;             PG8_WAIT_V(8); PG8_WAIT_L(0); PG8_BAR; PG8_MMA(1, 0, At, B0); PG8_MMA(1, 1, At, B1); PG8_BAR; PG8_SCHED;
.LBB0_922:
	s_add_u32 s25, s56, 0xfffe0080
	s_addc_u32 s26, s57, -1
	s_add_i32 s27, 0, 0x10000
	s_cmp_eq_u32 s24, 4
	s_cselect_b32 s65, s5, s26
	s_cselect_b32 s64, s41, s25
	v_add_u32_e32 v140, s27, v143
	s_cselect_b32 s59, s43, s15
	s_cselect_b32 s58, s75, s14
	s_add_i32 s25, 0, 0x14000
	ds_read_b128 v[146:149], v140
	ds_read_b128 v[150:153], v140 offset:1024
	ds_read_b128 v[154:157], v140 offset:2048
	ds_read_b128 v[158:161], v140 offset:3072
	v_add_u32_e32 v140, s25, v143
	ds_read_b128 v[168:171], v140
	ds_read_b128 v[172:175], v140 offset:1024
	ds_read_b128 v[176:179], v140 offset:2048
	ds_read_b128 v[180:183], v140 offset:3072
	v_lshl_add_u64 v[140:141], s[56:57], 0, v[136:137]
	s_add_i32 m0, s21, 0xc000
	ds_read_b128 v[184:187], v145
	ds_read_b128 v[188:191], v145 offset:1024
	ds_read_b128 v[192:195], v145 offset:2048
	ds_read_b128 v[196:199], v145 offset:3072
	ds_read_b128 v[200:203], v145 offset:4096
	ds_read_b128 v[224:227], v145 offset:5120
	ds_read_b128 v[228:231], v145 offset:6144
	ds_read_b128 v[232:235], v145 offset:7168
	global_load_lds_dwordx4 v[140:141], off
	v_lshl_add_u64 v[140:141], s[56:57], 0, v[138:139]
	s_add_i32 m0, s21, 0xe000
	s_nop 0
	global_load_lds_dwordx4 v[140:141], off
	s_waitcnt vmcnt(8)
	s_waitcnt lgkmcnt(0)
	s_barrier
	v_mfma_f32_16x16x32_bf16 v[126:129], v[146:149], v[184:187], v[126:129]
	v_mfma_f32_16x16x32_bf16 v[126:129], v[150:153], v[188:191], v[126:129]
	v_mfma_f32_16x16x32_bf16 v[122:125], v[154:157], v[184:187], v[122:125]
	v_mfma_f32_16x16x32_bf16 v[122:125], v[158:161], v[188:191], v[122:125]
	v_mfma_f32_16x16x32_bf16 v[118:121], v[146:149], v[192:195], v[118:121]
	v_mfma_f32_16x16x32_bf16 v[118:121], v[150:153], v[196:199], v[118:121]
	v_mfma_f32_16x16x32_bf16 v[110:113], v[154:157], v[192:195], v[110:113]
	v_mfma_f32_16x16x32_bf16 v[110:113], v[158:161], v[196:199], v[110:113]
	v_mfma_f32_16x16x32_bf16 v[102:105], v[146:149], v[200:203], v[102:105]
	v_mfma_f32_16x16x32_bf16 v[102:105], v[150:153], v[224:227], v[102:105]
	v_mfma_f32_16x16x32_bf16 v[94:97], v[154:157], v[200:203], v[94:97]
	v_mfma_f32_16x16x32_bf16 v[94:97], v[158:161], v[224:227], v[94:97]
	v_mfma_f32_16x16x32_bf16 v[86:89], v[146:149], v[228:231], v[86:89]
	v_mfma_f32_16x16x32_bf16 v[86:89], v[150:153], v[232:235], v[86:89]
	v_mfma_f32_16x16x32_bf16 v[78:81], v[154:157], v[228:231], v[78:81]
	v_mfma_f32_16x16x32_bf16 v[78:81], v[158:161], v[232:235], v[78:81]
	v_mfma_f32_16x16x32_bf16 v[114:117], v[168:171], v[184:187], v[114:117]
	v_mfma_f32_16x16x32_bf16 v[114:117], v[172:175], v[188:191], v[114:117]
	v_mfma_f32_16x16x32_bf16 v[106:109], v[176:179], v[184:187], v[106:109]
	v_mfma_f32_16x16x32_bf16 v[106:109], v[180:183], v[188:191], v[106:109]
	v_mfma_f32_16x16x32_bf16 v[98:101], v[168:171], v[192:195], v[98:101]
	v_mfma_f32_16x16x32_bf16 v[98:101], v[172:175], v[196:199], v[98:101]
	v_mfma_f32_16x16x32_bf16 v[90:93], v[176:179], v[192:195], v[90:93]
	v_mfma_f32_16x16x32_bf16 v[90:93], v[180:183], v[196:199], v[90:93]
	v_mfma_f32_16x16x32_bf16 v[82:85], v[168:171], v[200:203], v[82:85]
	v_mfma_f32_16x16x32_bf16 v[82:85], v[172:175], v[224:227], v[82:85]
	v_mfma_f32_16x16x32_bf16 v[74:77], v[176:179], v[200:203], v[74:77]
	v_mfma_f32_16x16x32_bf16 v[74:77], v[180:183], v[224:227], v[74:77]
	v_mfma_f32_16x16x32_bf16 v[70:73], v[168:171], v[228:231], v[70:73]
	v_mfma_f32_16x16x32_bf16 v[70:73], v[172:175], v[232:235], v[70:73]
	v_mfma_f32_16x16x32_bf16 v[66:69], v[176:179], v[228:231], v[66:69]
	v_mfma_f32_16x16x32_bf16 v[66:69], v[180:183], v[232:235], v[66:69]
	s_barrier
	s_add_i32 s26, s27, s16
	v_lshl_add_u64 v[140:141], s[58:59], 0, v[0:1]
	s_mov_b32 m0, s26
	ds_read_b128 v[184:187], v145 offset:16384
	ds_read_b128 v[188:191], v145 offset:17408
	ds_read_b128 v[192:195], v145 offset:18432
	ds_read_b128 v[196:199], v145 offset:19456
	ds_read_b128 v[200:203], v145 offset:20480
	ds_read_b128 v[224:227], v145 offset:21504
	ds_read_b128 v[228:231], v145 offset:22528
	ds_read_b128 v[232:235], v145 offset:23552
	global_load_lds_dwordx4 v[140:141], off
	s_add_i32 m0, s26, 0x2000
	s_add_u32 s26, s58, 0x20000
	v_lshl_add_u64 v[236:237], s[58:59], 0, v[130:131]
	s_addc_u32 s27, s59, 0
	s_add_i32 s25, s25, s16
	global_load_lds_dwordx4 v[236:237], off
	v_lshl_add_u64 v[238:239], s[26:27], 0, v[0:1]
	s_mov_b32 m0, s25
	v_lshl_add_u64 v[240:241], s[64:65], 0, v[132:133]
	global_load_lds_dwordx4 v[238:239], off
	v_lshl_add_u64 v[238:239], s[26:27], 0, v[130:131]
	s_add_i32 m0, s25, 0x2000
	s_nop 0
	global_load_lds_dwordx4 v[238:239], off
	v_lshl_add_u64 v[238:239], s[64:65], 0, v[134:135]
	s_mov_b32 m0, s21
	s_nop 0
	global_load_lds_dwordx4 v[238:239], off
	s_mov_b32 m0, s22
	s_nop 0
	global_load_lds_dwordx4 v[240:241], off
	s_waitcnt vmcnt(8)
	s_waitcnt lgkmcnt(0)
	s_barrier
; #define PG8_STAGE(bufoff, gbase, voff) do { _Pragma("unroll") for (int _i = 0; _i < 2; ++_i) \
;         __builtin_amdgcn_global_load_lds((const unsigned*)((const char*)(gbase) + (voff)[_i]), (PG8_LAS unsigned*)(lds + (bufoff) + ldsw + _i * 8192), 16, 0, 0); } while (0)
; #define PG8_LDA(dst, b, h) do { _Pragma("unroll") for (int m = 0; m < 4; ++m) _Pragma("unroll") for (int k = 0; k < 2; ++k) dst[m][k] = *(const PG8_LAS bf16x8*)(lds + PG8_SA(b, h) + aoff + m * 2048 + k * 1024); } while (0)
; #define PG8_LDB(dst, b, h) do { _Pragma("unroll") for (int n = 0; n < 2; ++n) _Pragma("unroll") for (int k = 0; k < 2; ++k) dst[n][k] = *(const PG8_LAS bf16x8*)(lds + PG8_SB(b, h) + boff + n * 2048 + k * 1024); } while (0)
; #define PG8_MMA(ai, bj, At, Bt) do { __builtin_amdgcn_s_setprio(1); _Pragma("unroll") for (int m = 0; m < 4; ++m) _Pragma("unroll") for (int n = 0; n < 2; ++n) _Pragma("unroll") for (int k = 0; k < 2; ++k) \
;         acc[ai][bj][m][n] = __builtin_amdgcn_mfma_f32_16x16x32_bf16(Bt[n][k], At[m][k], acc[ai][bj][m][n], 0, 0, 0); __builtin_amdgcn_s_setprio(0); } while (0)
; #define PG8_WAIT_V(n) asm volatile("s_waitcnt vmcnt(" #n ")" ::: "memory")
; #define PG8_WAIT_L(n) asm volatile("s_waitcnt lgkmcnt(" #n ")" ::: "memory")
; #define PG8_BAR __builtin_amdgcn_s_barrier()
; #define PG8_SCHED __builtin_amdgcn_sched_barrier(0)
; template <class Epi, class Sched, bool ALIGN_EPI = false, bool SP2 = false>
; __device__ __forceinline__ void gemm_phase(PG8_LAS unsigned char* lds, const Gemm g, const Sched S, const Epi E) {
;     ...
;             PG8_WAIT_V(8); PG8_WAIT_L(0); PG8_BAR; PG8_MMA(1, 0, At, B0); PG8_MMA(1, 1, At, B1); PG8_BAR; PG8_SCHED;
;             PG8_LDB(B0, 1, 0); PG8_LDB(B1, 1, 1); PG8_SCHED; PG8_LDA(At, 1, 0); PG8_STAGE(PG8_SA(0, 1), a2 + hstep, voffA);
;             PG8_WAIT_V(8); PG8_WAIT_L(0); PG8_BAR; PG8_MMA(0, 0, At, B0); PG8_MMA(0, 1, At, B1); PG8_BAR; PG8_SCHED;
	v_mfma_f32_16x16x32_bf16 v[62:65], v[146:149], v[184:187], v[62:65]
	v_mfma_f32_16x16x32_bf16 v[62:65], v[150:153], v[188:191], v[62:65]
	v_mfma_f32_16x16x32_bf16 v[58:61], v[154:157], v[184:187], v[58:61]
	v_mfma_f32_16x16x32_bf16 v[58:61], v[158:161], v[188:191], v[58:61]
	v_mfma_f32_16x16x32_bf16 v[54:57], v[146:149], v[192:195], v[54:57]
	v_mfma_f32_16x16x32_bf16 v[54:57], v[150:153], v[196:199], v[54:57]
	v_mfma_f32_16x16x32_bf16 v[46:49], v[154:157], v[192:195], v[46:49]
	v_mfma_f32_16x16x32_bf16 v[46:49], v[158:161], v[196:199], v[46:49]
	v_mfma_f32_16x16x32_bf16 v[38:41], v[146:149], v[200:203], v[38:41]
	v_mfma_f32_16x16x32_bf16 v[38:41], v[150:153], v[224:227], v[38:41]
	v_mfma_f32_16x16x32_bf16 v[30:33], v[154:157], v[200:203], v[30:33]
	v_mfma_f32_16x16x32_bf16 v[30:33], v[158:161], v[224:227], v[30:33]
	v_mfma_f32_16x16x32_bf16 v[22:25], v[146:149], v[228:231], v[22:25]
	v_mfma_f32_16x16x32_bf16 v[22:25], v[150:153], v[232:235], v[22:25]
	v_mfma_f32_16x16x32_bf16 v[14:17], v[154:157], v[228:231], v[14:17]
	v_mfma_f32_16x16x32_bf16 v[14:17], v[158:161], v[232:235], v[14:17]
	v_mfma_f32_16x16x32_bf16 v[50:53], v[168:171], v[184:187], v[50:53]
	v_mfma_f32_16x16x32_bf16 v[50:53], v[172:175], v[188:191], v[50:53]
	v_mfma_f32_16x16x32_bf16 v[42:45], v[176:179], v[184:187], v[42:45]
	v_mfma_f32_16x16x32_bf16 v[42:45], v[180:183], v[188:191], v[42:45]
	v_mfma_f32_16x16x32_bf16 v[34:37], v[168:171], v[192:195], v[34:37]
	v_mfma_f32_16x16x32_bf16 v[34:37], v[172:175], v[196:199], v[34:37]
	v_mfma_f32_16x16x32_bf16 v[26:29], v[176:179], v[192:195], v[26:29]
	v_mfma_f32_16x16x32_bf16 v[26:29], v[180:183], v[196:199], v[26:29]
	v_mfma_f32_16x16x32_bf16 v[18:21], v[168:171], v[200:203], v[18:21]
	v_mfma_f32_16x16x32_bf16 v[18:21], v[172:175], v[224:227], v[18:21]
	v_mfma_f32_16x16x32_bf16 v[10:13], v[176:179], v[200:203], v[10:13]
	v_mfma_f32_16x16x32_bf16 v[10:13], v[180:183], v[224:227], v[10:13]
	v_mfma_f32_16x16x32_bf16 v[6:9], v[168:171], v[228:231], v[6:9]
	v_mfma_f32_16x16x32_bf16 v[6:9], v[172:175], v[232:235], v[6:9]
	v_mfma_f32_16x16x32_bf16 v[2:5], v[176:179], v[228:231], v[2:5]
	v_mfma_f32_16x16x32_bf16 v[2:5], v[180:183], v[232:235], v[2:5]
	s_barrier
	s_add_i32 s25, 0, 0x18000
	s_add_i32 s30, 0, 0x1c000
	v_add_u32_e32 v158, s25, v143
	v_add_u32_e32 v167, s30, v143
	ds_read_b128 v[146:149], v158
	ds_read_b128 v[150:153], v158 offset:1024
	ds_read_b128 v[154:157], v158 offset:2048
	ds_read_b128 v[158:161], v158 offset:3072
	ds_read_b128 v[168:171], v167
	ds_read_b128 v[172:175], v167 offset:1024
	ds_read_b128 v[176:179], v167 offset:2048
	ds_read_b128 v[180:183], v167 offset:3072
	s_add_u32 s26, s64, 0x20000
	s_addc_u32 s27, s65, 0
	s_mov_b32 m0, s47
	v_lshl_add_u64 v[242:243], s[26:27], 0, v[134:135]
	ds_read_b128 v[184:187], v145 offset:32768
	ds_read_b128 v[188:191], v145 offset:33792
	ds_read_b128 v[192:195], v145 offset:34816
	ds_read_b128 v[196:199], v145 offset:35840
	ds_read_b128 v[200:203], v145 offset:36864
	ds_read_b128 v[224:227], v145 offset:37888
	ds_read_b128 v[228:231], v145 offset:38912
	ds_read_b128 v[232:235], v145 offset:39936
	global_load_lds_dwordx4 v[242:243], off
	v_lshl_add_u64 v[242:243], s[26:27], 0, v[132:133]
	s_mov_b32 m0, s62
	s_nop 0
	global_load_lds_dwordx4 v[242:243], off
	s_waitcnt vmcnt(8)
	s_waitcnt lgkmcnt(0)
	s_barrier
	v_mfma_f32_16x16x32_bf16 v[126:129], v[146:149], v[184:187], v[126:129]
	v_mfma_f32_16x16x32_bf16 v[126:129], v[150:153], v[188:191], v[126:129]
	v_mfma_f32_16x16x32_bf16 v[122:125], v[154:157], v[184:187], v[122:125]
	v_mfma_f32_16x16x32_bf16 v[122:125], v[158:161], v[188:191], v[122:125]
	v_mfma_f32_16x16x32_bf16 v[118:121], v[146:149], v[192:195], v[118:121]
	v_mfma_f32_16x16x32_bf16 v[118:121], v[150:153], v[196:199], v[118:121]
	v_mfma_f32_16x16x32_bf16 v[110:113], v[154:157], v[192:195], v[110:113]
	v_mfma_f32_16x16x32_bf16 v[110:113], v[158:161], v[196:199], v[110:113]
	v_mfma_f32_16x16x32_bf16 v[102:105], v[146:149], v[200:203], v[102:105]
	v_mfma_f32_16x16x32_bf16 v[102:105], v[150:153], v[224:227], v[102:105]
	v_mfma_f32_16x16x32_bf16 v[94:97], v[154:157], v[200:203], v[94:97]
	v_mfma_f32_16x16x32_bf16 v[94:97], v[158:161], v[224:227], v[94:97]
	v_mfma_f32_16x16x32_bf16 v[86:89], v[146:149], v[228:231], v[86:89]
	v_mfma_f32_16x16x32_bf16 v[86:89], v[150:153], v[232:235], v[86:89]
	v_mfma_f32_16x16x32_bf16 v[78:81], v[154:157], v[228:231], v[78:81]
	v_mfma_f32_16x16x32_bf16 v[78:81], v[158:161], v[232:235], v[78:81]
	v_mfma_f32_16x16x32_bf16 v[114:117], v[168:171], v[184:187], v[114:117]
	v_mfma_f32_16x16x32_bf16 v[114:117], v[172:175], v[188:191], v[114:117]
	v_mfma_f32_16x16x32_bf16 v[106:109], v[176:179], v[184:187], v[106:109]
	v_mfma_f32_16x16x32_bf16 v[106:109], v[180:183], v[188:191], v[106:109]
	v_mfma_f32_16x16x32_bf16 v[98:101], v[168:171], v[192:195], v[98:101]
	v_mfma_f32_16x16x32_bf16 v[98:101], v[172:175], v[196:199], v[98:101]
	v_mfma_f32_16x16x32_bf16 v[90:93], v[176:179], v[192:195], v[90:93]
	v_mfma_f32_16x16x32_bf16 v[90:93], v[180:183], v[196:199], v[90:93]
	v_mfma_f32_16x16x32_bf16 v[82:85], v[168:171], v[200:203], v[82:85]
	v_mfma_f32_16x16x32_bf16 v[82:85], v[172:175], v[224:227], v[82:85]
	v_mfma_f32_16x16x32_bf16 v[74:77], v[176:179], v[200:203], v[74:77]
	v_mfma_f32_16x16x32_bf16 v[74:77], v[180:183], v[224:227], v[74:77]
	v_mfma_f32_16x16x32_bf16 v[70:73], v[168:171], v[228:231], v[70:73]
	v_mfma_f32_16x16x32_bf16 v[70:73], v[172:175], v[232:235], v[70:73]
	v_mfma_f32_16x16x32_bf16 v[66:69], v[176:179], v[228:231], v[66:69]
	v_mfma_f32_16x16x32_bf16 v[66:69], v[180:183], v[232:235], v[66:69]
	s_barrier
; #define PG8_STAGE(bufoff, gbase, voff) do { _Pragma("unroll") for (int _i = 0; _i < 2; ++_i) \
;         __builtin_amdgcn_global_load_lds((const unsigned*)((const char*)(gbase) + (voff)[_i]), (PG8_LAS unsigned*)(lds + (bufoff) + ldsw + _i * 8192), 16, 0, 0); } while (0)
; #define PG8_LDA(dst, b, h) do { _Pragma("unroll") for (int m = 0; m < 4; ++m) _Pragma("unroll") for (int k = 0; k < 2; ++k) dst[m][k] = *(const PG8_LAS bf16x8*)(lds + PG8_SA(b, h) + aoff + m * 2048 + k * 1024); } while (0)
; #define PG8_MMA(ai, bj, At, Bt) do { __builtin_amdgcn_s_setprio(1); _Pragma("unroll") for (int m = 0; m < 4; ++m) _Pragma("unroll") for (int n = 0; n < 2; ++n) _Pragma("unroll") for (int k = 0; k < 2; ++k) \
;         acc[ai][bj][m][n] = __builtin_amdgcn_mfma_f32_16x16x32_bf16(Bt[n][k], At[m][k], acc[ai][bj][m][n], 0, 0, 0); __builtin_amdgcn_s_setprio(0); } while (0)
; #define PG8_WAIT_V(n) asm volatile("s_waitcnt vmcnt(" #n ")" ::: "memory")
; #define PG8_WAIT_L(n) asm volatile("s_waitcnt lgkmcnt(" #n ")" ::: "memory")
; #define PG8_BAR __builtin_amdgcn_s_barrier()
; #define PG8_SCHED __builtin_amdgcn_sched_barrier(0)
; template <class Epi, class Sched, bool ALIGN_EPI = false, bool SP2 = false>
; __device__ __forceinline__ void gemm_phase(PG8_LAS unsigned char* lds, const Gemm g, const Sched S, const Epi E) {
;     ...
;             PG8_LDA(At, 1, 1); PG8_STAGE(PG8_SB(1, 0), b3, voffB); PG8_STAGE(PG8_SB(1, 1), b3 + hstep, voffB); PG8_STAGE(PG8_SA(1, 0), a3, voffA);
;             PG8_WAIT_V(8); PG8_WAIT_L(0); PG8_BAR; PG8_MMA(1, 0, At, B0); PG8_MMA(1, 1, At, B1); PG8_BAR; PG8_SCHED;
;     ...
;         if constexpr (ALIGN_EPI) { if (wr == 0) PG8_BAR; }
	s_add_i32 s25, s25, s16
	v_lshl_add_u64 v[140:141], v[140:141], 0, s[28:29]
	s_mov_b32 m0, s25
	ds_read_b128 v[184:187], v145 offset:49152
	ds_read_b128 v[188:191], v145 offset:50176
	ds_read_b128 v[192:195], v145 offset:51200
	ds_read_b128 v[196:199], v145 offset:52224
	ds_read_b128 v[200:203], v145 offset:53248
	ds_read_b128 v[224:227], v145 offset:54272
	ds_read_b128 v[228:231], v145 offset:55296
	ds_read_b128 v[232:235], v145 offset:56320
	global_load_lds_dwordx4 v[140:141], off
	s_add_i32 m0, s25, 0x2000
	s_add_u32 s26, s58, 0x20080
	v_lshl_add_u64 v[140:141], v[236:237], 0, s[28:29]
	s_addc_u32 s27, s59, 0
	s_add_i32 s25, s30, s16
	global_load_lds_dwordx4 v[140:141], off
	v_lshl_add_u64 v[140:141], s[26:27], 0, v[0:1]
	s_mov_b32 m0, s25
	s_nop 0
	global_load_lds_dwordx4 v[140:141], off
	v_lshl_add_u64 v[140:141], s[26:27], 0, v[130:131]
	s_add_i32 m0, s25, 0x2000
	s_nop 0
	global_load_lds_dwordx4 v[140:141], off
	v_lshl_add_u64 v[140:141], v[238:239], 0, s[28:29]
	s_mov_b32 m0, s63
	s_nop 0
	global_load_lds_dwordx4 v[140:141], off
	v_lshl_add_u64 v[140:141], v[240:241], 0, s[28:29]
	s_mov_b32 m0, s66
	s_nop 0
	global_load_lds_dwordx4 v[140:141], off
	s_waitcnt vmcnt(8)
	s_waitcnt lgkmcnt(0)
	s_barrier
	v_mfma_f32_16x16x32_bf16 v[62:65], v[146:149], v[184:187], v[62:65]
	v_mfma_f32_16x16x32_bf16 v[62:65], v[150:153], v[188:191], v[62:65]
	v_mfma_f32_16x16x32_bf16 v[58:61], v[154:157], v[184:187], v[58:61]
	v_mfma_f32_16x16x32_bf16 v[58:61], v[158:161], v[188:191], v[58:61]
	v_mfma_f32_16x16x32_bf16 v[54:57], v[146:149], v[192:195], v[54:57]
	v_mfma_f32_16x16x32_bf16 v[54:57], v[150:153], v[196:199], v[54:57]
	v_mfma_f32_16x16x32_bf16 v[46:49], v[154:157], v[192:195], v[46:49]
	v_mfma_f32_16x16x32_bf16 v[46:49], v[158:161], v[196:199], v[46:49]
	v_mfma_f32_16x16x32_bf16 v[38:41], v[146:149], v[200:203], v[38:41]
	v_mfma_f32_16x16x32_bf16 v[38:41], v[150:153], v[224:227], v[38:41]
	v_mfma_f32_16x16x32_bf16 v[30:33], v[154:157], v[200:203], v[30:33]
	v_mfma_f32_16x16x32_bf16 v[30:33], v[158:161], v[224:227], v[30:33]
	v_mfma_f32_16x16x32_bf16 v[22:25], v[146:149], v[228:231], v[22:25]
	v_mfma_f32_16x16x32_bf16 v[22:25], v[150:153], v[232:235], v[22:25]
	v_mfma_f32_16x16x32_bf16 v[14:17], v[154:157], v[228:231], v[14:17]
	v_mfma_f32_16x16x32_bf16 v[14:17], v[158:161], v[232:235], v[14:17]
	v_mfma_f32_16x16x32_bf16 v[50:53], v[168:171], v[184:187], v[50:53]
	v_mfma_f32_16x16x32_bf16 v[50:53], v[172:175], v[188:191], v[50:53]
	v_mfma_f32_16x16x32_bf16 v[42:45], v[176:179], v[184:187], v[42:45]
	v_mfma_f32_16x16x32_bf16 v[42:45], v[180:183], v[188:191], v[42:45]
	v_mfma_f32_16x16x32_bf16 v[34:37], v[168:171], v[192:195], v[34:37]
	v_mfma_f32_16x16x32_bf16 v[34:37], v[172:175], v[196:199], v[34:37]
	v_mfma_f32_16x16x32_bf16 v[26:29], v[176:179], v[192:195], v[26:29]
	v_mfma_f32_16x16x32_bf16 v[26:29], v[180:183], v[196:199], v[26:29]
	v_mfma_f32_16x16x32_bf16 v[18:21], v[168:171], v[200:203], v[18:21]
	v_mfma_f32_16x16x32_bf16 v[18:21], v[172:175], v[224:227], v[18:21]
	v_mfma_f32_16x16x32_bf16 v[10:13], v[176:179], v[200:203], v[10:13]
	v_mfma_f32_16x16x32_bf16 v[10:13], v[180:183], v[224:227], v[10:13]
	v_mfma_f32_16x16x32_bf16 v[6:9], v[168:171], v[228:231], v[6:9]
	v_mfma_f32_16x16x32_bf16 v[6:9], v[172:175], v[232:235], v[6:9]
	v_mfma_f32_16x16x32_bf16 v[2:5], v[176:179], v[228:231], v[2:5]
	v_mfma_f32_16x16x32_bf16 v[2:5], v[180:183], v[232:235], v[2:5]
	s_barrier
	s_add_i32 s24, s24, 2
	s_add_u32 s56, s56, 0x100
	s_addc_u32 s57, s57, 0
	s_add_u32 s14, s14, 0x100
	s_addc_u32 s15, s15, 0
	s_cmp_gt_u32 s24, 5
	s_cbranch_scc0 .LBB0_922
	s_and_b64 vcc, exec, s[38:39]
	s_cbranch_vccz .LBB0_925
	s_barrier

; #define PG8_STAGE(bufoff, gbase, voff) do { _Pragma("unroll") for (int _i = 0; _i < 2; ++_i) \
;         __builtin_amdgcn_global_load_lds((const unsigned*)((const char*)(gbase) + (voff)[_i]), (PG8_LAS unsigned*)(lds + (bufoff) + ldsw + _i * 8192), 16, 0, 0); } while (0)
; #define PG8_LDA(dst, b, h) do { _Pragma("unroll") for (int m = 0; m < 4; ++m) _Pragma("unroll") for (int k = 0; k < 2; ++k) dst[m][k] = *(const PG8_LAS bf16x8*)(lds + PG8_SA(b, h) + aoff + m * 2048 + k * 1024); } while (0)
; #define PG8_LDB(dst, b, h) do { _Pragma("unroll") for (int n = 0; n < 2; ++n) _Pragma("unroll") for (int k = 0; k < 2; ++k) dst[n][k] = *(const PG8_LAS bf16x8*)(lds + PG8_SB(b, h) + boff + n * 2048 + k * 1024); } while (0)
; #define PG8_MMA(ai, bj, At, Bt) do { __builtin_amdgcn_s_setprio(1); _Pragma("unroll") for (int m = 0; m < 4; ++m) _Pragma("unroll") for (int n = 0; n < 2; ++n) _Pragma("unroll") for (int k = 0; k < 2; ++k) \
;         acc[ai][bj][m][n] = __builtin_amdgcn_mfma_f32_16x16x32_bf16(Bt[n][k], At[m][k], acc[ai][bj][m][n], 0, 0, 0); __builtin_amdgcn_s_setprio(0); } while (0)
; #define PG8_WAIT_V(n) asm volatile("s_waitcnt vmcnt(" #n ")" ::: "memory")
; #define PG8_BAR __builtin_amdgcn_s_barrier()
; template <class Epi, class Sched, bool ALIGN_EPI = false, bool SP2 = false>
; __device__ __forceinline__ void gemm_phase(PG8_LAS unsigned char* lds, const Gemm g, const Sched S, const Epi E) {
;     ...
;         for (int t = 0; t < nt; t += 2) {
;             const bool last = (t == nt - 2);
;             const char* a1 = cA + (size_t)(t + 1) * kstep;
;             const char* a2 = last ? nA : cA + (size_t)(t + 2) * kstep; const char* b2 = last ? nB : cB + (size_t)(t + 2) * kstep;
;             const char* a3 = a2 + kstep; const char* b3 = b2 + kstep;
;             if (last && has_next) S.a_ready(nxt);
;             if constexpr (SP2) {
;             PG8_LDB(B0, 0, 0); PG8_LDB(B1, 0, 1); PG8_SCHED; PG8_LDA(At, 0, 0); PG8_STAGE(PG8_SA(1, 1), a1 + hstep, voffA);
;             PG8_WAIT_V(8); PG8_WAIT_L(0); PG8_BAR; PG8_MMA(0, 0, At, B0); PG8_MMA(0, 1, At, B1); PG8_BAR; PG8_SCHED;
;             PG8_LDA(At, 0, 1); PG8_STAGE(PG8_SB(0, 0), b2, voffB); PG8_STAGE(PG8_SB(0, 1), b2 + hstep, voffB); PG8_STAGE(PG8_SA(0, 0), a2, voffA);
;             PG8_WAIT_V(8); PG8_WAIT_L(0); PG8_BAR; PG8_MMA(1, 0, At, B0); PG8_MMA(1, 1, At, B1); PG8_BAR; PG8_SCHED;
.LBB0_2074:
	s_add_u32 s56, s52, 0x100
	s_addc_u32 s57, s53, 0
	s_add_i32 s25, 0, 0x10000
	s_cmp_eq_u32 s24, 28
	s_cselect_b32 s65, s43, s57
	s_cselect_b32 s64, s74, s56
	v_add_u32_e32 v140, s25, v143
	s_cselect_b32 s59, s41, s15
	s_cselect_b32 s58, s75, s14
	s_add_i32 s30, 0, 0x14000
	ds_read_b128 v[136:139], v140
	ds_read_b128 v[146:149], v140 offset:1024
	ds_read_b128 v[150:153], v140 offset:2048
	ds_read_b128 v[154:157], v140 offset:3072
	v_add_u32_e32 v140, s30, v143
	ds_read_b128 v[158:161], v140
	ds_read_b128 v[168:171], v140 offset:1024
	ds_read_b128 v[172:175], v140 offset:2048
	ds_read_b128 v[176:179], v140 offset:3072
	v_lshl_add_u64 v[140:141], s[52:53], 0, v[132:133]
	s_add_i32 m0, s21, 0xc000
	ds_read_b128 v[180:183], v145
	ds_read_b128 v[184:187], v145 offset:1024
	ds_read_b128 v[188:191], v145 offset:2048
	ds_read_b128 v[192:195], v145 offset:3072
	ds_read_b128 v[196:199], v145 offset:4096
	ds_read_b128 v[200:203], v145 offset:5120
	ds_read_b128 v[224:227], v145 offset:6144
	ds_read_b128 v[228:231], v145 offset:7168
	global_load_lds_dwordx4 v[140:141], off
	v_lshl_add_u64 v[140:141], s[52:53], 0, v[134:135]
	s_add_i32 m0, s21, 0xe000
	s_nop 0
	global_load_lds_dwordx4 v[140:141], off
	s_waitcnt vmcnt(8)
	s_waitcnt lgkmcnt(0)
	s_barrier
	v_mfma_f32_16x16x32_bf16 v[126:129], v[136:139], v[180:183], v[126:129]
	v_mfma_f32_16x16x32_bf16 v[126:129], v[146:149], v[184:187], v[126:129]
	v_mfma_f32_16x16x32_bf16 v[122:125], v[150:153], v[180:183], v[122:125]
	v_mfma_f32_16x16x32_bf16 v[122:125], v[154:157], v[184:187], v[122:125]
	v_mfma_f32_16x16x32_bf16 v[110:113], v[136:139], v[188:191], v[110:113]
	v_mfma_f32_16x16x32_bf16 v[110:113], v[146:149], v[192:195], v[110:113]
	v_mfma_f32_16x16x32_bf16 v[106:109], v[150:153], v[188:191], v[106:109]
	v_mfma_f32_16x16x32_bf16 v[106:109], v[154:157], v[192:195], v[106:109]
	v_mfma_f32_16x16x32_bf16 v[94:97], v[136:139], v[196:199], v[94:97]
	v_mfma_f32_16x16x32_bf16 v[94:97], v[146:149], v[200:203], v[94:97]
	v_mfma_f32_16x16x32_bf16 v[90:93], v[150:153], v[196:199], v[90:93]
	v_mfma_f32_16x16x32_bf16 v[90:93], v[154:157], v[200:203], v[90:93]
	v_mfma_f32_16x16x32_bf16 v[78:81], v[136:139], v[224:227], v[78:81]
	v_mfma_f32_16x16x32_bf16 v[78:81], v[146:149], v[228:231], v[78:81]
	v_mfma_f32_16x16x32_bf16 v[74:77], v[150:153], v[224:227], v[74:77]
	v_mfma_f32_16x16x32_bf16 v[74:77], v[154:157], v[228:231], v[74:77]
	v_mfma_f32_16x16x32_bf16 v[118:121], v[158:161], v[180:183], v[118:121]
	v_mfma_f32_16x16x32_bf16 v[118:121], v[168:171], v[184:187], v[118:121]
	v_mfma_f32_16x16x32_bf16 v[114:117], v[172:175], v[180:183], v[114:117]
	v_mfma_f32_16x16x32_bf16 v[114:117], v[176:179], v[184:187], v[114:117]
	v_mfma_f32_16x16x32_bf16 v[102:105], v[158:161], v[188:191], v[102:105]
	v_mfma_f32_16x16x32_bf16 v[102:105], v[168:171], v[192:195], v[102:105]
	v_mfma_f32_16x16x32_bf16 v[98:101], v[172:175], v[188:191], v[98:101]
	v_mfma_f32_16x16x32_bf16 v[98:101], v[176:179], v[192:195], v[98:101]
	v_mfma_f32_16x16x32_bf16 v[86:89], v[158:161], v[196:199], v[86:89]
	v_mfma_f32_16x16x32_bf16 v[86:89], v[168:171], v[200:203], v[86:89]
	v_mfma_f32_16x16x32_bf16 v[82:85], v[172:175], v[196:199], v[82:85]
	v_mfma_f32_16x16x32_bf16 v[82:85], v[176:179], v[200:203], v[82:85]
	v_mfma_f32_16x16x32_bf16 v[70:73], v[158:161], v[224:227], v[70:73]
	v_mfma_f32_16x16x32_bf16 v[70:73], v[168:171], v[228:231], v[70:73]
	v_mfma_f32_16x16x32_bf16 v[66:69], v[172:175], v[224:227], v[66:69]
	v_mfma_f32_16x16x32_bf16 v[66:69], v[176:179], v[228:231], v[66:69]
	s_barrier
	s_add_i32 s25, s25, s16
	v_lshl_add_u64 v[140:141], s[58:59], 0, v[0:1]
	s_mov_b32 m0, s25
	ds_read_b128 v[180:183], v145 offset:16384
	ds_read_b128 v[184:187], v145 offset:17408
	ds_read_b128 v[188:191], v145 offset:18432
	ds_read_b128 v[192:195], v145 offset:19456
	ds_read_b128 v[196:199], v145 offset:20480
	ds_read_b128 v[200:203], v145 offset:21504
	ds_read_b128 v[224:227], v145 offset:22528
	ds_read_b128 v[228:231], v145 offset:23552
	global_load_lds_dwordx4 v[140:141], off
	s_add_i32 m0, s25, 0x2000
	s_add_u32 s26, s58, 0x80000
	v_lshl_add_u64 v[232:233], s[58:59], 0, v[130:131]
	s_addc_u32 s27, s59, 0
	s_add_i32 s25, s30, s16
	global_load_lds_dwordx4 v[232:233], off
	v_lshl_add_u64 v[234:235], s[26:27], 0, v[0:1]
	s_mov_b32 m0, s25
	v_lshl_add_u64 v[236:237], s[64:65], 0, v[130:131]
	global_load_lds_dwordx4 v[234:235], off
	v_lshl_add_u64 v[234:235], s[26:27], 0, v[130:131]
	s_add_i32 m0, s25, 0x2000
	s_nop 0
	global_load_lds_dwordx4 v[234:235], off
	v_lshl_add_u64 v[234:235], s[64:65], 0, v[0:1]
	s_mov_b32 m0, s21
	s_nop 0
	global_load_lds_dwordx4 v[234:235], off
	s_mov_b32 m0, s22
	s_nop 0
	global_load_lds_dwordx4 v[236:237], off
	s_waitcnt vmcnt(8)
	s_waitcnt lgkmcnt(0)
	s_barrier
; #define PG8_STAGE(bufoff, gbase, voff) do { _Pragma("unroll") for (int _i = 0; _i < 2; ++_i) \
;         __builtin_amdgcn_global_load_lds((const unsigned*)((const char*)(gbase) + (voff)[_i]), (PG8_LAS unsigned*)(lds + (bufoff) + ldsw + _i * 8192), 16, 0, 0); } while (0)
; #define PG8_LDA(dst, b, h) do { _Pragma("unroll") for (int m = 0; m < 4; ++m) _Pragma("unroll") for (int k = 0; k < 2; ++k) dst[m][k] = *(const PG8_LAS bf16x8*)(lds + PG8_SA(b, h) + aoff + m * 2048 + k * 1024); } while (0)
; #define PG8_LDB(dst, b, h) do { _Pragma("unroll") for (int n = 0; n < 2; ++n) _Pragma("unroll") for (int k = 0; k < 2; ++k) dst[n][k] = *(const PG8_LAS bf16x8*)(lds + PG8_SB(b, h) + boff + n * 2048 + k * 1024); } while (0)
; #define PG8_MMA(ai, bj, At, Bt) do { __builtin_amdgcn_s_setprio(1); _Pragma("unroll") for (int m = 0; m < 4; ++m) _Pragma("unroll") for (int n = 0; n < 2; ++n) _Pragma("unroll") for (int k = 0; k < 2; ++k) \
;         acc[ai][bj][m][n] = __builtin_amdgcn_mfma_f32_16x16x32_bf16(Bt[n][k], At[m][k], acc[ai][bj][m][n], 0, 0, 0); __builtin_amdgcn_s_setprio(0); } while (0)
; #define PG8_WAIT_V(n) asm volatile("s_waitcnt vmcnt(" #n ")" ::: "memory")
; #define PG8_WAIT_L(n) asm volatile("s_waitcnt lgkmcnt(" #n ")" ::: "memory")
; #define PG8_BAR __builtin_amdgcn_s_barrier()
; #define PG8_SCHED __builtin_amdgcn_sched_barrier(0)
; template <class Epi, class Sched, bool ALIGN_EPI = false, bool SP2 = false>
; __device__ __forceinline__ void gemm_phase(PG8_LAS unsigned char* lds, const Gemm g, const Sched S, const Epi E) {
;     ...
;             PG8_WAIT_V(8); PG8_WAIT_L(0); PG8_BAR; PG8_MMA(1, 0, At, B0); PG8_MMA(1, 1, At, B1); PG8_BAR; PG8_SCHED;
;             PG8_LDB(B0, 1, 0); PG8_LDB(B1, 1, 1); PG8_SCHED; PG8_LDA(At, 1, 0); PG8_STAGE(PG8_SA(0, 1), a2 + hstep, voffA);
;             PG8_WAIT_V(8); PG8_WAIT_L(0); PG8_BAR; PG8_MMA(0, 0, At, B0); PG8_MMA(0, 1, At, B1); PG8_BAR; PG8_SCHED;
	v_mfma_f32_16x16x32_bf16 v[62:65], v[136:139], v[180:183], v[62:65]
	v_mfma_f32_16x16x32_bf16 v[62:65], v[146:149], v[184:187], v[62:65]
	v_mfma_f32_16x16x32_bf16 v[58:61], v[150:153], v[180:183], v[58:61]
	v_mfma_f32_16x16x32_bf16 v[58:61], v[154:157], v[184:187], v[58:61]
	v_mfma_f32_16x16x32_bf16 v[46:49], v[136:139], v[188:191], v[46:49]
	v_mfma_f32_16x16x32_bf16 v[46:49], v[146:149], v[192:195], v[46:49]
	v_mfma_f32_16x16x32_bf16 v[42:45], v[150:153], v[188:191], v[42:45]
	v_mfma_f32_16x16x32_bf16 v[42:45], v[154:157], v[192:195], v[42:45]
	v_mfma_f32_16x16x32_bf16 v[30:33], v[136:139], v[196:199], v[30:33]
	v_mfma_f32_16x16x32_bf16 v[30:33], v[146:149], v[200:203], v[30:33]
	v_mfma_f32_16x16x32_bf16 v[26:29], v[150:153], v[196:199], v[26:29]
	v_mfma_f32_16x16x32_bf16 v[26:29], v[154:157], v[200:203], v[26:29]
	v_mfma_f32_16x16x32_bf16 v[14:17], v[136:139], v[224:227], v[14:17]
	v_mfma_f32_16x16x32_bf16 v[14:17], v[146:149], v[228:231], v[14:17]
	v_mfma_f32_16x16x32_bf16 v[10:13], v[150:153], v[224:227], v[10:13]
	v_mfma_f32_16x16x32_bf16 v[10:13], v[154:157], v[228:231], v[10:13]
	v_mfma_f32_16x16x32_bf16 v[54:57], v[158:161], v[180:183], v[54:57]
	v_mfma_f32_16x16x32_bf16 v[54:57], v[168:171], v[184:187], v[54:57]
	v_mfma_f32_16x16x32_bf16 v[50:53], v[172:175], v[180:183], v[50:53]
	v_mfma_f32_16x16x32_bf16 v[50:53], v[176:179], v[184:187], v[50:53]
	v_mfma_f32_16x16x32_bf16 v[38:41], v[158:161], v[188:191], v[38:41]
	v_mfma_f32_16x16x32_bf16 v[38:41], v[168:171], v[192:195], v[38:41]
	v_mfma_f32_16x16x32_bf16 v[34:37], v[172:175], v[188:191], v[34:37]
	v_mfma_f32_16x16x32_bf16 v[34:37], v[176:179], v[192:195], v[34:37]
	v_mfma_f32_16x16x32_bf16 v[22:25], v[158:161], v[196:199], v[22:25]
	v_mfma_f32_16x16x32_bf16 v[22:25], v[168:171], v[200:203], v[22:25]
	v_mfma_f32_16x16x32_bf16 v[18:21], v[172:175], v[196:199], v[18:21]
	v_mfma_f32_16x16x32_bf16 v[18:21], v[176:179], v[200:203], v[18:21]
	v_mfma_f32_16x16x32_bf16 v[6:9], v[158:161], v[224:227], v[6:9]
	v_mfma_f32_16x16x32_bf16 v[6:9], v[168:171], v[228:231], v[6:9]
	v_mfma_f32_16x16x32_bf16 v[2:5], v[172:175], v[224:227], v[2:5]
	v_mfma_f32_16x16x32_bf16 v[2:5], v[176:179], v[228:231], v[2:5]
	s_barrier
	s_add_i32 s25, 0, 0x18000
	s_add_i32 s30, 0, 0x1c000
	v_add_u32_e32 v154, s25, v143
	v_add_u32_e32 v167, s30, v143
	ds_read_b128 v[136:139], v154
	ds_read_b128 v[146:149], v154 offset:1024
	ds_read_b128 v[150:153], v154 offset:2048
	ds_read_b128 v[154:157], v154 offset:3072
	ds_read_b128 v[158:161], v167
	ds_read_b128 v[168:171], v167 offset:1024
	ds_read_b128 v[172:175], v167 offset:2048
	ds_read_b128 v[176:179], v167 offset:3072
	s_add_u32 s26, s64, 0x80000
	s_addc_u32 s27, s65, 0
	s_mov_b32 m0, s47
	v_lshl_add_u64 v[238:239], s[26:27], 0, v[0:1]
	ds_read_b128 v[180:183], v145 offset:32768
	ds_read_b128 v[184:187], v145 offset:33792
	ds_read_b128 v[188:191], v145 offset:34816
	ds_read_b128 v[192:195], v145 offset:35840
	ds_read_b128 v[196:199], v145 offset:36864
	ds_read_b128 v[200:203], v145 offset:37888
	ds_read_b128 v[224:227], v145 offset:38912
	ds_read_b128 v[228:231], v145 offset:39936
	global_load_lds_dwordx4 v[238:239], off
	v_lshl_add_u64 v[238:239], s[26:27], 0, v[130:131]
	s_mov_b32 m0, s62
	s_nop 0
	global_load_lds_dwordx4 v[238:239], off
	s_waitcnt vmcnt(8)
	s_waitcnt lgkmcnt(0)
	s_barrier
	v_mfma_f32_16x16x32_bf16 v[126:129], v[136:139], v[180:183], v[126:129]
	v_mfma_f32_16x16x32_bf16 v[126:129], v[146:149], v[184:187], v[126:129]
	v_mfma_f32_16x16x32_bf16 v[122:125], v[150:153], v[180:183], v[122:125]
	v_mfma_f32_16x16x32_bf16 v[122:125], v[154:157], v[184:187], v[122:125]
	v_mfma_f32_16x16x32_bf16 v[110:113], v[136:139], v[188:191], v[110:113]
	v_mfma_f32_16x16x32_bf16 v[110:113], v[146:149], v[192:195], v[110:113]
	v_mfma_f32_16x16x32_bf16 v[106:109], v[150:153], v[188:191], v[106:109]
	v_mfma_f32_16x16x32_bf16 v[106:109], v[154:157], v[192:195], v[106:109]
	v_mfma_f32_16x16x32_bf16 v[94:97], v[136:139], v[196:199], v[94:97]
	v_mfma_f32_16x16x32_bf16 v[94:97], v[146:149], v[200:203], v[94:97]
	v_mfma_f32_16x16x32_bf16 v[90:93], v[150:153], v[196:199], v[90:93]
	v_mfma_f32_16x16x32_bf16 v[90:93], v[154:157], v[200:203], v[90:93]
	v_mfma_f32_16x16x32_bf16 v[78:81], v[136:139], v[224:227], v[78:81]
	v_mfma_f32_16x16x32_bf16 v[78:81], v[146:149], v[228:231], v[78:81]
	v_mfma_f32_16x16x32_bf16 v[74:77], v[150:153], v[224:227], v[74:77]
	v_mfma_f32_16x16x32_bf16 v[74:77], v[154:157], v[228:231], v[74:77]
	v_mfma_f32_16x16x32_bf16 v[118:121], v[158:161], v[180:183], v[118:121]
	v_mfma_f32_16x16x32_bf16 v[118:121], v[168:171], v[184:187], v[118:121]
	v_mfma_f32_16x16x32_bf16 v[114:117], v[172:175], v[180:183], v[114:117]
	v_mfma_f32_16x16x32_bf16 v[114:117], v[176:179], v[184:187], v[114:117]
	v_mfma_f32_16x16x32_bf16 v[102:105], v[158:161], v[188:191], v[102:105]
	v_mfma_f32_16x16x32_bf16 v[102:105], v[168:171], v[192:195], v[102:105]
	v_mfma_f32_16x16x32_bf16 v[98:101], v[172:175], v[188:191], v[98:101]
	v_mfma_f32_16x16x32_bf16 v[98:101], v[176:179], v[192:195], v[98:101]
	v_mfma_f32_16x16x32_bf16 v[86:89], v[158:161], v[196:199], v[86:89]
	v_mfma_f32_16x16x32_bf16 v[86:89], v[168:171], v[200:203], v[86:89]
	v_mfma_f32_16x16x32_bf16 v[82:85], v[172:175], v[196:199], v[82:85]
	v_mfma_f32_16x16x32_bf16 v[82:85], v[176:179], v[200:203], v[82:85]
	v_mfma_f32_16x16x32_bf16 v[70:73], v[158:161], v[224:227], v[70:73]
	v_mfma_f32_16x16x32_bf16 v[70:73], v[168:171], v[228:231], v[70:73]
	v_mfma_f32_16x16x32_bf16 v[66:69], v[172:175], v[224:227], v[66:69]
	v_mfma_f32_16x16x32_bf16 v[66:69], v[176:179], v[228:231], v[66:69]
	s_barrier
; #define PG8_STAGE(bufoff, gbase, voff) do { _Pragma("unroll") for (int _i = 0; _i < 2; ++_i) \
;         __builtin_amdgcn_global_load_lds((const unsigned*)((const char*)(gbase) + (voff)[_i]), (PG8_LAS unsigned*)(lds + (bufoff) + ldsw + _i * 8192), 16, 0, 0); } while (0)
; #define PG8_LDA(dst, b, h) do { _Pragma("unroll") for (int m = 0; m < 4; ++m) _Pragma("unroll") for (int k = 0; k < 2; ++k) dst[m][k] = *(const PG8_LAS bf16x8*)(lds + PG8_SA(b, h) + aoff + m * 2048 + k * 1024); } while (0)
; #define PG8_MMA(ai, bj, At, Bt) do { __builtin_amdgcn_s_setprio(1); _Pragma("unroll") for (int m = 0; m < 4; ++m) _Pragma("unroll") for (int n = 0; n < 2; ++n) _Pragma("unroll") for (int k = 0; k < 2; ++k) \
;         acc[ai][bj][m][n] = __builtin_amdgcn_mfma_f32_16x16x32_bf16(Bt[n][k], At[m][k], acc[ai][bj][m][n], 0, 0, 0); __builtin_amdgcn_s_setprio(0); } while (0)
; #define PG8_WAIT_V(n) asm volatile("s_waitcnt vmcnt(" #n ")" ::: "memory")
; #define PG8_WAIT_L(n) asm volatile("s_waitcnt lgkmcnt(" #n ")" ::: "memory")
; #define PG8_BAR __builtin_amdgcn_s_barrier()
; #define PG8_SCHED __builtin_amdgcn_sched_barrier(0)
; template <class Epi, class Sched, bool ALIGN_EPI = false, bool SP2 = false>
; __device__ __forceinline__ void gemm_phase(PG8_LAS unsigned char* lds, const Gemm g, const Sched S, const Epi E) {
;     ...
;             PG8_LDA(At, 1, 1); PG8_STAGE(PG8_SB(1, 0), b3, voffB); PG8_STAGE(PG8_SB(1, 1), b3 + hstep, voffB); PG8_STAGE(PG8_SA(1, 0), a3, voffA);
;             PG8_WAIT_V(8); PG8_WAIT_L(0); PG8_BAR; PG8_MMA(1, 0, At, B0); PG8_MMA(1, 1, At, B1); PG8_BAR; PG8_SCHED;
;     ...
;         if constexpr (ALIGN_EPI) { if (wr == 0) PG8_BAR; }
	s_add_i32 s25, s25, s16
	v_lshl_add_u64 v[140:141], v[140:141], 0, s[28:29]
	s_mov_b32 m0, s25
	ds_read_b128 v[180:183], v145 offset:49152
	ds_read_b128 v[184:187], v145 offset:50176
	ds_read_b128 v[188:191], v145 offset:51200
	ds_read_b128 v[192:195], v145 offset:52224
	ds_read_b128 v[196:199], v145 offset:53248
	ds_read_b128 v[200:203], v145 offset:54272
	ds_read_b128 v[224:227], v145 offset:55296
	ds_read_b128 v[228:231], v145 offset:56320
	global_load_lds_dwordx4 v[140:141], off
	s_add_i32 m0, s25, 0x2000
	s_add_u32 s26, s58, 0x80080
	v_lshl_add_u64 v[140:141], v[232:233], 0, s[28:29]
	s_addc_u32 s27, s59, 0
	s_add_i32 s25, s30, s16
	global_load_lds_dwordx4 v[140:141], off
	v_lshl_add_u64 v[140:141], s[26:27], 0, v[0:1]
	s_mov_b32 m0, s25
	s_nop 0
	global_load_lds_dwordx4 v[140:141], off
	v_lshl_add_u64 v[140:141], s[26:27], 0, v[130:131]
	s_add_i32 m0, s25, 0x2000
	s_nop 0
	global_load_lds_dwordx4 v[140:141], off
	v_lshl_add_u64 v[140:141], v[234:235], 0, s[28:29]
	s_mov_b32 m0, s63
	s_nop 0
	global_load_lds_dwordx4 v[140:141], off
	v_lshl_add_u64 v[140:141], v[236:237], 0, s[28:29]
	s_mov_b32 m0, s66
	s_nop 0
	global_load_lds_dwordx4 v[140:141], off
	s_waitcnt vmcnt(8)
	s_waitcnt lgkmcnt(0)
	s_barrier
	v_mfma_f32_16x16x32_bf16 v[62:65], v[136:139], v[180:183], v[62:65]
	v_mfma_f32_16x16x32_bf16 v[62:65], v[146:149], v[184:187], v[62:65]
	v_mfma_f32_16x16x32_bf16 v[58:61], v[150:153], v[180:183], v[58:61]
	v_mfma_f32_16x16x32_bf16 v[58:61], v[154:157], v[184:187], v[58:61]
	v_mfma_f32_16x16x32_bf16 v[46:49], v[136:139], v[188:191], v[46:49]
	v_mfma_f32_16x16x32_bf16 v[46:49], v[146:149], v[192:195], v[46:49]
	v_mfma_f32_16x16x32_bf16 v[42:45], v[150:153], v[188:191], v[42:45]
	v_mfma_f32_16x16x32_bf16 v[42:45], v[154:157], v[192:195], v[42:45]
	v_mfma_f32_16x16x32_bf16 v[30:33], v[136:139], v[196:199], v[30:33]
	v_mfma_f32_16x16x32_bf16 v[30:33], v[146:149], v[200:203], v[30:33]
	v_mfma_f32_16x16x32_bf16 v[26:29], v[150:153], v[196:199], v[26:29]
	v_mfma_f32_16x16x32_bf16 v[26:29], v[154:157], v[200:203], v[26:29]
	v_mfma_f32_16x16x32_bf16 v[14:17], v[136:139], v[224:227], v[14:17]
	v_mfma_f32_16x16x32_bf16 v[14:17], v[146:149], v[228:231], v[14:17]
	v_mfma_f32_16x16x32_bf16 v[10:13], v[150:153], v[224:227], v[10:13]
	v_mfma_f32_16x16x32_bf16 v[10:13], v[154:157], v[228:231], v[10:13]
	v_mfma_f32_16x16x32_bf16 v[54:57], v[158:161], v[180:183], v[54:57]
	v_mfma_f32_16x16x32_bf16 v[54:57], v[168:171], v[184:187], v[54:57]
	v_mfma_f32_16x16x32_bf16 v[50:53], v[172:175], v[180:183], v[50:53]
	v_mfma_f32_16x16x32_bf16 v[50:53], v[176:179], v[184:187], v[50:53]
	v_mfma_f32_16x16x32_bf16 v[38:41], v[158:161], v[188:191], v[38:41]
	v_mfma_f32_16x16x32_bf16 v[38:41], v[168:171], v[192:195], v[38:41]
	v_mfma_f32_16x16x32_bf16 v[34:37], v[172:175], v[188:191], v[34:37]
	v_mfma_f32_16x16x32_bf16 v[34:37], v[176:179], v[192:195], v[34:37]
	v_mfma_f32_16x16x32_bf16 v[22:25], v[158:161], v[196:199], v[22:25]
	v_mfma_f32_16x16x32_bf16 v[22:25], v[168:171], v[200:203], v[22:25]
	v_mfma_f32_16x16x32_bf16 v[18:21], v[172:175], v[196:199], v[18:21]
	v_mfma_f32_16x16x32_bf16 v[18:21], v[176:179], v[200:203], v[18:21]
	v_mfma_f32_16x16x32_bf16 v[6:9], v[158:161], v[224:227], v[6:9]
	v_mfma_f32_16x16x32_bf16 v[6:9], v[168:171], v[228:231], v[6:9]
	v_mfma_f32_16x16x32_bf16 v[2:5], v[172:175], v[224:227], v[2:5]
	v_mfma_f32_16x16x32_bf16 v[2:5], v[176:179], v[228:231], v[2:5]
	s_barrier
	s_add_i32 s24, s24, 2
	s_add_u32 s14, s14, 0x100
	s_addc_u32 s15, s15, 0
	s_cmp_gt_u32 s24, 29
	s_mov_b64 s[52:53], s[56:57]
	s_cbranch_scc0 .LBB0_2074
	s_and_b64 vcc, exec, s[38:39]
	s_cbranch_vccz .LBB0_2077
	s_barrier
